# GEMM k-loops (19 of 25): the six LDS-DMA issues of each k-tile are spread among the MFMA groups instead of bunched at the loop top
# speedup vs baseline: 1.0089x; 1.0047x over previous
; DEV int stage_next(int s) { return (s == 2 * GS_STAGE) ? 0 : s + GS_STAGE; }
; template <int WAIT0>
; DEV void gk_main(f32x16 (&acc)[2][2], const GTile& t, int s0) {
;     ...
;   vm_wait_bar<WAIT0>();
;   int stc = s0, std_ = stage_next(stage_next(s0));
; #pragma nounroll
;   for (int kt = 0; kt < nk - 2; ++kt) {
;     GK_DMA(std_, kt + 2);
;     GK_COMPUTE(stc);
;     vm_wait_bar<6>();
;     stc = stage_next(stc); std_ = stage_next(std_);
;   }
.LBB0_75:
	s_add_i32 s21, s19, s20
	s_mov_b32 s98, s21
	s_mov_b64 s[100:101], s[6:7]
	s_add_i32 s27, s18, 0
	v_add_u32_e32 v100, s27, v82
	v_add_u32_e32 v101, s27, v83
	ds_read_b128 v[84:87], v101 offset:16384
	ds_read_b128 v[88:91], v100
	ds_read_b128 v[92:95], v100 offset:4096
	s_waitcnt lgkmcnt(0)
	v_add_u32_e32 v100, s27, v80
	s_add_i32 s21, s18, 0xc000
	s_cmp_lg_u32 s18, 0x18000
	s_cselect_b32 s18, s21, 0
	s_add_i32 s21, s20, 0xc000
	s_cmp_lg_u32 s20, 0x18000
	s_cselect_b32 s20, s21, 0
	ds_read_b128 v[236:239], v101 offset:20480
	v_mfma_f32_32x32x16_bf16 v[48:63], v[84:87], v[88:91], v[48:63]
	v_mfma_f32_32x32x16_bf16 v[16:31], v[84:87], v[92:95], v[16:31]
	s_mov_b32 m0, s98
	v_lshl_add_u64 v[254:255], v[64:65], 0, s[100:101]
	global_load_lds_dwordx4 v[254:255], off
	v_add_u32_e32 v101, s27, v81
	s_add_u32 s6, s6, 0x80
	s_addc_u32 s7, s7, 0
	s_waitcnt lgkmcnt(0)
	ds_read_b128 v[84:87], v101 offset:16384
	ds_read_b128 v[240:243], v100
	ds_read_b128 v[244:247], v100 offset:4096
	v_mfma_f32_32x32x16_bf16 v[32:47], v[236:239], v[88:91], v[32:47]
	v_mfma_f32_32x32x16_bf16 v[0:15], v[236:239], v[92:95], v[0:15]
	s_add_i32 m0, s98, 0x2000
	v_lshl_add_u64 v[254:255], v[66:67], 0, s[100:101]
	global_load_lds_dwordx4 v[254:255], off
	v_add_u32_e32 v100, s27, v78
	s_waitcnt lgkmcnt(0)
	ds_read_b128 v[236:239], v101 offset:20480
	v_mfma_f32_32x32x16_bf16 v[48:63], v[84:87], v[240:243], v[48:63]
	v_mfma_f32_32x32x16_bf16 v[16:31], v[84:87], v[244:247], v[16:31]
	s_add_i32 m0, s98, 0x4000
	v_lshl_add_u64 v[254:255], v[68:69], 0, s[100:101]
	global_load_lds_dwordx4 v[254:255], off
	v_add_u32_e32 v101, s27, v79
	s_waitcnt lgkmcnt(0)
	ds_read_b128 v[84:87], v101 offset:16384
	ds_read_b128 v[88:91], v100
	ds_read_b128 v[92:95], v100 offset:4096
	v_mfma_f32_32x32x16_bf16 v[32:47], v[236:239], v[240:243], v[32:47]
	v_mfma_f32_32x32x16_bf16 v[0:15], v[236:239], v[244:247], v[0:15]
	s_add_i32 m0, s98, 0x6000
	v_lshl_add_u64 v[254:255], v[70:71], 0, s[100:101]
	global_load_lds_dwordx4 v[254:255], off
	v_add_u32_e32 v100, s27, v76
	s_waitcnt lgkmcnt(0)
	ds_read_b128 v[236:239], v101 offset:20480
	v_mfma_f32_32x32x16_bf16 v[48:63], v[84:87], v[88:91], v[48:63]
	v_mfma_f32_32x32x16_bf16 v[16:31], v[84:87], v[92:95], v[16:31]
	s_add_i32 m0, s98, 0x8000
	v_lshl_add_u64 v[254:255], v[72:73], 0, s[100:101]
	global_load_lds_dwordx4 v[254:255], off
	v_add_u32_e32 v101, s27, v77
	s_waitcnt lgkmcnt(0)
	ds_read_b128 v[84:87], v101 offset:16384
	ds_read_b128 v[240:243], v100
	ds_read_b128 v[244:247], v100 offset:4096
	v_mfma_f32_32x32x16_bf16 v[32:47], v[236:239], v[88:91], v[32:47]
	v_mfma_f32_32x32x16_bf16 v[0:15], v[236:239], v[92:95], v[0:15]
	s_add_i32 m0, s98, 0xa000
	v_lshl_add_u64 v[254:255], v[74:75], 0, s[100:101]
	global_load_lds_dwordx4 v[254:255], off
	s_waitcnt lgkmcnt(0)
	ds_read_b128 v[236:239], v101 offset:20480
	v_mfma_f32_32x32x16_bf16 v[48:63], v[84:87], v[240:243], v[48:63]
	v_mfma_f32_32x32x16_bf16 v[16:31], v[84:87], v[244:247], v[16:31]
	s_waitcnt vmcnt(6) lgkmcnt(0)
	s_barrier
	s_waitcnt lgkmcnt(0)
	v_mfma_f32_32x32x16_bf16 v[32:47], v[236:239], v[240:243], v[32:47]
	v_mfma_f32_32x32x16_bf16 v[0:15], v[236:239], v[244:247], v[0:15]
	s_cmpk_lg_i32 s6, 0x700
	s_cbranch_scc1 .LBB0_75
; DEV int stage_next(int s) { return (s == 2 * GS_STAGE) ? 0 : s + GS_STAGE; }
; template <int WAIT0>
; DEV void gk_main(f32x16 (&acc)[2][2], const GTile& t, int s0) {
;     ...
;   GK_COMPUTE(stc);
;   vm_wait_bar<0>();
;   stc = stage_next(stc);
;   GK_COMPUTE(stc);
;   vm_wait_bar<0>();
	s_add_i32 s6, s18, 0
	v_add_u32_e32 v84, s6, v83
	ds_read_b128 v[64:67], v84 offset:16384
	v_add_u32_e32 v72, s6, v82
	ds_read_b128 v[68:71], v72
	ds_read_b128 v[72:75], v72 offset:4096
	s_waitcnt lgkmcnt(0)
	v_mfma_f32_32x32x16_bf16 v[48:63], v[64:67], v[68:71], v[48:63]
	v_mfma_f32_32x32x16_bf16 v[16:31], v[64:67], v[72:75], v[16:31]
	ds_read_b128 v[64:67], v84 offset:20480
	v_add_u32_e32 v84, s6, v81
	s_waitcnt lgkmcnt(0)
	v_mfma_f32_32x32x16_bf16 v[32:47], v[64:67], v[68:71], v[32:47]
	v_mfma_f32_32x32x16_bf16 v[0:15], v[64:67], v[72:75], v[0:15]
	ds_read_b128 v[64:67], v84 offset:16384
	v_add_u32_e32 v72, s6, v80
	ds_read_b128 v[68:71], v72
	ds_read_b128 v[72:75], v72 offset:4096
	s_waitcnt lgkmcnt(0)
	v_mfma_f32_32x32x16_bf16 v[48:63], v[64:67], v[68:71], v[48:63]
	v_mfma_f32_32x32x16_bf16 v[16:31], v[64:67], v[72:75], v[16:31]
	ds_read_b128 v[64:67], v84 offset:20480
	v_add_u32_e32 v84, s6, v79
	s_waitcnt lgkmcnt(0)
	v_mfma_f32_32x32x16_bf16 v[32:47], v[64:67], v[68:71], v[32:47]
	v_mfma_f32_32x32x16_bf16 v[0:15], v[64:67], v[72:75], v[0:15]
	ds_read_b128 v[64:67], v84 offset:16384
	v_add_u32_e32 v72, s6, v78
	ds_read_b128 v[68:71], v72
	ds_read_b128 v[72:75], v72 offset:4096
	s_waitcnt lgkmcnt(0)
	v_mfma_f32_32x32x16_bf16 v[48:63], v[64:67], v[68:71], v[48:63]
	v_mfma_f32_32x32x16_bf16 v[16:31], v[64:67], v[72:75], v[16:31]
	ds_read_b128 v[64:67], v84 offset:20480
	v_add_u32_e32 v84, s6, v77
	s_waitcnt lgkmcnt(0)
	v_mfma_f32_32x32x16_bf16 v[32:47], v[64:67], v[68:71], v[32:47]
	v_mfma_f32_32x32x16_bf16 v[0:15], v[64:67], v[72:75], v[0:15]
	ds_read_b128 v[64:67], v84 offset:16384
	v_add_u32_e32 v72, s6, v76
	ds_read_b128 v[68:71], v72
	ds_read_b128 v[72:75], v72 offset:4096
	s_add_i32 s6, s18, 0xc000
	s_cmp_lg_u32 s18, 0x18000
	s_cselect_b32 s6, s6, 0
	s_waitcnt lgkmcnt(0)
	v_mfma_f32_32x32x16_bf16 v[48:63], v[64:67], v[68:71], v[48:63]
	s_add_i32 s6, s6, 0
	v_add_u32_e32 v83, s6, v83
	v_add_u32_e32 v81, s6, v81
	v_add_u32_e32 v79, s6, v79
	v_add_u32_e32 v77, s6, v77
	v_mfma_f32_32x32x16_bf16 v[16:31], v[64:67], v[72:75], v[16:31]
	ds_read_b128 v[64:67], v84 offset:20480
	s_waitcnt vmcnt(0) lgkmcnt(0)
	s_barrier
	s_waitcnt lgkmcnt(0)
	v_mfma_f32_32x32x16_bf16 v[32:47], v[64:67], v[68:71], v[32:47]
	v_mfma_f32_32x32x16_bf16 v[0:15], v[64:67], v[72:75], v[0:15]
	ds_read_b128 v[64:67], v83 offset:16384
	v_add_u32_e32 v72, s6, v82
	ds_read_b128 v[68:71], v72
	ds_read_b128 v[72:75], v72 offset:4096
	s_waitcnt lgkmcnt(0)
	v_mfma_f32_32x32x16_bf16 v[48:63], v[64:67], v[68:71], v[48:63]
	v_mfma_f32_32x32x16_bf16 v[16:31], v[64:67], v[72:75], v[16:31]
	ds_read_b128 v[64:67], v83 offset:20480
	s_waitcnt lgkmcnt(0)
	v_mfma_f32_32x32x16_bf16 v[32:47], v[64:67], v[68:71], v[32:47]
	v_mfma_f32_32x32x16_bf16 v[0:15], v[64:67], v[72:75], v[0:15]
	ds_read_b128 v[64:67], v81 offset:16384
	v_add_u32_e32 v72, s6, v80
	ds_read_b128 v[68:71], v72
	ds_read_b128 v[72:75], v72 offset:4096
	s_waitcnt lgkmcnt(0)
	v_mfma_f32_32x32x16_bf16 v[48:63], v[64:67], v[68:71], v[48:63]
	v_mfma_f32_32x32x16_bf16 v[16:31], v[64:67], v[72:75], v[16:31]
	ds_read_b128 v[64:67], v81 offset:20480
	s_waitcnt lgkmcnt(0)
	v_mfma_f32_32x32x16_bf16 v[32:47], v[64:67], v[68:71], v[32:47]
	v_mfma_f32_32x32x16_bf16 v[0:15], v[64:67], v[72:75], v[0:15]
	ds_read_b128 v[64:67], v79 offset:16384
	v_add_u32_e32 v72, s6, v78
	ds_read_b128 v[68:71], v72
	ds_read_b128 v[72:75], v72 offset:4096
	s_waitcnt lgkmcnt(0)
	v_mfma_f32_32x32x16_bf16 v[48:63], v[64:67], v[68:71], v[48:63]
	v_mfma_f32_32x32x16_bf16 v[16:31], v[64:67], v[72:75], v[16:31]
	ds_read_b128 v[64:67], v79 offset:20480
	s_waitcnt lgkmcnt(0)
	v_mfma_f32_32x32x16_bf16 v[32:47], v[64:67], v[68:71], v[32:47]
	v_mfma_f32_32x32x16_bf16 v[0:15], v[64:67], v[72:75], v[0:15]
	ds_read_b128 v[64:67], v77 offset:16384
	v_add_u32_e32 v72, s6, v76
	ds_read_b128 v[68:71], v72
	ds_read_b128 v[72:75], v72 offset:4096
	s_mov_b64 s[6:7], 0
	s_waitcnt lgkmcnt(0)
	v_mfma_f32_32x32x16_bf16 v[48:63], v[64:67], v[68:71], v[48:63]
	v_mfma_f32_32x32x16_bf16 v[16:31], v[64:67], v[72:75], v[16:31]
	ds_read_b128 v[64:67], v77 offset:20480
	s_waitcnt vmcnt(0) lgkmcnt(0)
	s_barrier
	s_waitcnt lgkmcnt(0)
	v_mfma_f32_32x32x16_bf16 v[32:47], v[64:67], v[68:71], v[32:47]
	v_mfma_f32_32x32x16_bf16 v[0:15], v[64:67], v[72:75], v[0:15]

; DEV int stage_next(int s) { return (s == 2 * GS_STAGE) ? 0 : s + GS_STAGE; }
; template <int WAIT0>
; DEV void gk_main(f32x16 (&acc)[2][2], const GTile& t, int s0) {
;     ...
;   vm_wait_bar<WAIT0>();
;   int stc = s0, std_ = stage_next(stage_next(s0));
; #pragma nounroll
;   for (int kt = 0; kt < nk - 2; ++kt) {
;     GK_DMA(std_, kt + 2);
;     GK_COMPUTE(stc);
;     vm_wait_bar<6>();
;     stc = stage_next(stc); std_ = stage_next(std_);
;   }
.LBB0_79:
	s_add_i32 s21, s19, s20
	s_mov_b32 s98, s21
	s_mov_b64 s[100:101], s[6:7]
	s_add_i32 s27, s18, 0
	v_add_u32_e32 v100, s27, v82
	v_add_u32_e32 v101, s27, v83
	ds_read_b128 v[84:87], v101 offset:16384
	ds_read_b128 v[88:91], v100
	ds_read_b128 v[92:95], v100 offset:4096
	s_waitcnt lgkmcnt(0)
	v_add_u32_e32 v100, s27, v80
	s_add_i32 s21, s18, 0xc000
	s_cmp_lg_u32 s18, 0x18000
	s_cselect_b32 s18, s21, 0
	s_add_i32 s21, s20, 0xc000
	s_cmp_lg_u32 s20, 0x18000
	s_cselect_b32 s20, s21, 0
	ds_read_b128 v[236:239], v101 offset:20480
	v_mfma_f32_32x32x16_bf16 v[48:63], v[84:87], v[88:91], v[48:63]
	v_mfma_f32_32x32x16_bf16 v[16:31], v[84:87], v[92:95], v[16:31]
	s_mov_b32 m0, s98
	v_lshl_add_u64 v[254:255], v[64:65], 0, s[100:101]
	global_load_lds_dwordx4 v[254:255], off
	v_add_u32_e32 v101, s27, v81
	s_add_u32 s6, s6, 0x80
	s_addc_u32 s7, s7, 0
	s_waitcnt lgkmcnt(0)
	ds_read_b128 v[84:87], v101 offset:16384
	ds_read_b128 v[240:243], v100
	ds_read_b128 v[244:247], v100 offset:4096
	v_mfma_f32_32x32x16_bf16 v[32:47], v[236:239], v[88:91], v[32:47]
	v_mfma_f32_32x32x16_bf16 v[0:15], v[236:239], v[92:95], v[0:15]
	s_add_i32 m0, s98, 0x2000
	v_lshl_add_u64 v[254:255], v[66:67], 0, s[100:101]
	global_load_lds_dwordx4 v[254:255], off
	v_add_u32_e32 v100, s27, v78
	s_waitcnt lgkmcnt(0)
	ds_read_b128 v[236:239], v101 offset:20480
	v_mfma_f32_32x32x16_bf16 v[48:63], v[84:87], v[240:243], v[48:63]
	v_mfma_f32_32x32x16_bf16 v[16:31], v[84:87], v[244:247], v[16:31]
	s_add_i32 m0, s98, 0x4000
	v_lshl_add_u64 v[254:255], v[68:69], 0, s[100:101]
	global_load_lds_dwordx4 v[254:255], off
	v_add_u32_e32 v101, s27, v79
	s_waitcnt lgkmcnt(0)
	ds_read_b128 v[84:87], v101 offset:16384
	ds_read_b128 v[88:91], v100
	ds_read_b128 v[92:95], v100 offset:4096
	v_mfma_f32_32x32x16_bf16 v[32:47], v[236:239], v[240:243], v[32:47]
	v_mfma_f32_32x32x16_bf16 v[0:15], v[236:239], v[244:247], v[0:15]
	s_add_i32 m0, s98, 0x6000
	v_lshl_add_u64 v[254:255], v[70:71], 0, s[100:101]
	global_load_lds_dwordx4 v[254:255], off
	v_add_u32_e32 v100, s27, v76
	s_waitcnt lgkmcnt(0)
	ds_read_b128 v[236:239], v101 offset:20480
	v_mfma_f32_32x32x16_bf16 v[48:63], v[84:87], v[88:91], v[48:63]
	v_mfma_f32_32x32x16_bf16 v[16:31], v[84:87], v[92:95], v[16:31]
	s_add_i32 m0, s98, 0x8000
	v_lshl_add_u64 v[254:255], v[72:73], 0, s[100:101]
	global_load_lds_dwordx4 v[254:255], off
	v_add_u32_e32 v101, s27, v77
	s_waitcnt lgkmcnt(0)
	ds_read_b128 v[84:87], v101 offset:16384
	ds_read_b128 v[240:243], v100
	ds_read_b128 v[244:247], v100 offset:4096
	v_mfma_f32_32x32x16_bf16 v[32:47], v[236:239], v[88:91], v[32:47]
	v_mfma_f32_32x32x16_bf16 v[0:15], v[236:239], v[92:95], v[0:15]
	s_add_i32 m0, s98, 0xa000
	v_lshl_add_u64 v[254:255], v[74:75], 0, s[100:101]
	global_load_lds_dwordx4 v[254:255], off
	s_waitcnt lgkmcnt(0)
	ds_read_b128 v[236:239], v101 offset:20480
	v_mfma_f32_32x32x16_bf16 v[48:63], v[84:87], v[240:243], v[48:63]
	v_mfma_f32_32x32x16_bf16 v[16:31], v[84:87], v[244:247], v[16:31]
	s_waitcnt vmcnt(6) lgkmcnt(0)
	s_barrier
	s_waitcnt lgkmcnt(0)
	v_mfma_f32_32x32x16_bf16 v[32:47], v[236:239], v[240:243], v[32:47]
	v_mfma_f32_32x32x16_bf16 v[0:15], v[236:239], v[244:247], v[0:15]
	s_cmpk_lg_i32 s6, 0x700
	s_cbranch_scc1 .LBB0_79
; DEV int stage_next(int s) { return (s == 2 * GS_STAGE) ? 0 : s + GS_STAGE; }
; template <int WAIT0>
; DEV void gk_main(f32x16 (&acc)[2][2], const GTile& t, int s0) {
;     ...
;   GK_COMPUTE(stc);
;   vm_wait_bar<0>();
;   stc = stage_next(stc);
;   GK_COMPUTE(stc);
;   vm_wait_bar<0>();
	s_add_i32 s6, s18, 0
	v_add_u32_e32 v84, s6, v83
	ds_read_b128 v[64:67], v84 offset:16384
	v_add_u32_e32 v72, s6, v82
	ds_read_b128 v[68:71], v72
	ds_read_b128 v[72:75], v72 offset:4096
	s_waitcnt lgkmcnt(0)
	v_mfma_f32_32x32x16_bf16 v[48:63], v[64:67], v[68:71], v[48:63]
	v_mfma_f32_32x32x16_bf16 v[16:31], v[64:67], v[72:75], v[16:31]
	ds_read_b128 v[64:67], v84 offset:20480
	v_add_u32_e32 v84, s6, v81
	s_waitcnt lgkmcnt(0)
	v_mfma_f32_32x32x16_bf16 v[32:47], v[64:67], v[68:71], v[32:47]
	v_mfma_f32_32x32x16_bf16 v[0:15], v[64:67], v[72:75], v[0:15]
	ds_read_b128 v[64:67], v84 offset:16384
	v_add_u32_e32 v72, s6, v80
	ds_read_b128 v[68:71], v72
	ds_read_b128 v[72:75], v72 offset:4096
	s_waitcnt lgkmcnt(0)
	v_mfma_f32_32x32x16_bf16 v[48:63], v[64:67], v[68:71], v[48:63]
	v_mfma_f32_32x32x16_bf16 v[16:31], v[64:67], v[72:75], v[16:31]
	ds_read_b128 v[64:67], v84 offset:20480
	v_add_u32_e32 v84, s6, v79
	s_waitcnt lgkmcnt(0)
	v_mfma_f32_32x32x16_bf16 v[32:47], v[64:67], v[68:71], v[32:47]
	v_mfma_f32_32x32x16_bf16 v[0:15], v[64:67], v[72:75], v[0:15]
	ds_read_b128 v[64:67], v84 offset:16384
	v_add_u32_e32 v72, s6, v78
	ds_read_b128 v[68:71], v72
	ds_read_b128 v[72:75], v72 offset:4096
	s_waitcnt lgkmcnt(0)
	v_mfma_f32_32x32x16_bf16 v[48:63], v[64:67], v[68:71], v[48:63]
	v_mfma_f32_32x32x16_bf16 v[16:31], v[64:67], v[72:75], v[16:31]
	ds_read_b128 v[64:67], v84 offset:20480
	v_add_u32_e32 v84, s6, v77
	s_waitcnt lgkmcnt(0)
	v_mfma_f32_32x32x16_bf16 v[32:47], v[64:67], v[68:71], v[32:47]
	v_mfma_f32_32x32x16_bf16 v[0:15], v[64:67], v[72:75], v[0:15]
	ds_read_b128 v[64:67], v84 offset:16384
	v_add_u32_e32 v72, s6, v76
	ds_read_b128 v[68:71], v72
	ds_read_b128 v[72:75], v72 offset:4096
	s_add_i32 s6, s18, 0xc000
	s_cmp_lg_u32 s18, 0x18000
	s_cselect_b32 s6, s6, 0
	s_waitcnt lgkmcnt(0)
	v_mfma_f32_32x32x16_bf16 v[48:63], v[64:67], v[68:71], v[48:63]
	s_add_i32 s6, s6, 0
	v_add_u32_e32 v83, s6, v83
	v_add_u32_e32 v81, s6, v81
	v_add_u32_e32 v79, s6, v79
	v_add_u32_e32 v77, s6, v77
	v_mfma_f32_32x32x16_bf16 v[16:31], v[64:67], v[72:75], v[16:31]
	ds_read_b128 v[64:67], v84 offset:20480
	s_waitcnt vmcnt(0) lgkmcnt(0)
	s_barrier
	s_waitcnt lgkmcnt(0)
	v_mfma_f32_32x32x16_bf16 v[32:47], v[64:67], v[68:71], v[32:47]
	v_mfma_f32_32x32x16_bf16 v[0:15], v[64:67], v[72:75], v[0:15]
	ds_read_b128 v[64:67], v83 offset:16384
	v_add_u32_e32 v72, s6, v82
	ds_read_b128 v[68:71], v72
	ds_read_b128 v[72:75], v72 offset:4096
	s_waitcnt lgkmcnt(0)
	v_mfma_f32_32x32x16_bf16 v[48:63], v[64:67], v[68:71], v[48:63]
	v_mfma_f32_32x32x16_bf16 v[16:31], v[64:67], v[72:75], v[16:31]
	ds_read_b128 v[64:67], v83 offset:20480
	s_waitcnt lgkmcnt(0)
	v_mfma_f32_32x32x16_bf16 v[32:47], v[64:67], v[68:71], v[32:47]
	v_mfma_f32_32x32x16_bf16 v[0:15], v[64:67], v[72:75], v[0:15]
	ds_read_b128 v[64:67], v81 offset:16384
	v_add_u32_e32 v72, s6, v80
	ds_read_b128 v[68:71], v72
	ds_read_b128 v[72:75], v72 offset:4096
	s_waitcnt lgkmcnt(0)
	v_mfma_f32_32x32x16_bf16 v[48:63], v[64:67], v[68:71], v[48:63]
	v_mfma_f32_32x32x16_bf16 v[16:31], v[64:67], v[72:75], v[16:31]
	ds_read_b128 v[64:67], v81 offset:20480
	s_waitcnt lgkmcnt(0)
	v_mfma_f32_32x32x16_bf16 v[32:47], v[64:67], v[68:71], v[32:47]
	v_mfma_f32_32x32x16_bf16 v[0:15], v[64:67], v[72:75], v[0:15]
	ds_read_b128 v[64:67], v79 offset:16384
	v_add_u32_e32 v72, s6, v78
	ds_read_b128 v[68:71], v72
	ds_read_b128 v[72:75], v72 offset:4096
	s_waitcnt lgkmcnt(0)
	v_mfma_f32_32x32x16_bf16 v[48:63], v[64:67], v[68:71], v[48:63]
	v_mfma_f32_32x32x16_bf16 v[16:31], v[64:67], v[72:75], v[16:31]
	ds_read_b128 v[64:67], v79 offset:20480
	s_waitcnt lgkmcnt(0)
	v_mfma_f32_32x32x16_bf16 v[32:47], v[64:67], v[68:71], v[32:47]
	v_mfma_f32_32x32x16_bf16 v[0:15], v[64:67], v[72:75], v[0:15]
	ds_read_b128 v[64:67], v77 offset:16384
	v_add_u32_e32 v72, s6, v76
	ds_read_b128 v[68:71], v72
	ds_read_b128 v[72:75], v72 offset:4096
	s_waitcnt lgkmcnt(0)
	v_mfma_f32_32x32x16_bf16 v[48:63], v[64:67], v[68:71], v[48:63]
	v_mfma_f32_32x32x16_bf16 v[16:31], v[64:67], v[72:75], v[16:31]
	ds_read_b128 v[64:67], v77 offset:20480
	s_waitcnt vmcnt(0) lgkmcnt(0)
	s_barrier
	s_waitcnt lgkmcnt(0)
	v_mfma_f32_32x32x16_bf16 v[32:47], v[64:67], v[68:71], v[32:47]
	v_mfma_f32_32x32x16_bf16 v[0:15], v[64:67], v[72:75], v[0:15]

; DEV int stage_next(int s) { return (s == 2 * GS_STAGE) ? 0 : s + GS_STAGE; }
; template <int WAIT0>
; DEV void gk_main(f32x16 (&acc)[2][2], const GTile& t, int s0) {
;     ...
;   vm_wait_bar<WAIT0>();
;   int stc = s0, std_ = stage_next(stage_next(s0));
; #pragma nounroll
;   for (int kt = 0; kt < nk - 2; ++kt) {
;     GK_DMA(std_, kt + 2);
;     GK_COMPUTE(stc);
;     vm_wait_bar<6>();
;     stc = stage_next(stc); std_ = stage_next(std_);
;   }
.LBB0_87:
	s_add_i32 s21, s19, s20
	s_mov_b32 s98, s21
	s_mov_b64 s[100:101], s[6:7]
	s_add_i32 s27, s18, 0
	v_add_u32_e32 v100, s27, v82
	v_add_u32_e32 v101, s27, v83
	ds_read_b128 v[84:87], v101 offset:16384
	ds_read_b128 v[88:91], v100
	ds_read_b128 v[92:95], v100 offset:4096
	s_waitcnt lgkmcnt(0)
	v_add_u32_e32 v100, s27, v80
	s_add_i32 s21, s18, 0xc000
	s_cmp_lg_u32 s18, 0x18000
	s_cselect_b32 s18, s21, 0
	s_add_i32 s21, s20, 0xc000
	s_cmp_lg_u32 s20, 0x18000
	s_cselect_b32 s20, s21, 0
	ds_read_b128 v[236:239], v101 offset:20480
	v_mfma_f32_32x32x16_bf16 v[48:63], v[84:87], v[88:91], v[48:63]
	v_mfma_f32_32x32x16_bf16 v[16:31], v[84:87], v[92:95], v[16:31]
	s_mov_b32 m0, s98
	v_lshl_add_u64 v[254:255], v[64:65], 0, s[100:101]
	global_load_lds_dwordx4 v[254:255], off
	v_add_u32_e32 v101, s27, v81
	s_add_u32 s6, s6, 0x80
	s_addc_u32 s7, s7, 0
	s_waitcnt lgkmcnt(0)
	ds_read_b128 v[84:87], v101 offset:16384
	ds_read_b128 v[240:243], v100
	ds_read_b128 v[244:247], v100 offset:4096
	v_mfma_f32_32x32x16_bf16 v[32:47], v[236:239], v[88:91], v[32:47]
	v_mfma_f32_32x32x16_bf16 v[0:15], v[236:239], v[92:95], v[0:15]
	s_add_i32 m0, s98, 0x2000
	v_lshl_add_u64 v[254:255], v[66:67], 0, s[100:101]
	global_load_lds_dwordx4 v[254:255], off
	v_add_u32_e32 v100, s27, v78
	s_waitcnt lgkmcnt(0)
	ds_read_b128 v[236:239], v101 offset:20480
	v_mfma_f32_32x32x16_bf16 v[48:63], v[84:87], v[240:243], v[48:63]
	v_mfma_f32_32x32x16_bf16 v[16:31], v[84:87], v[244:247], v[16:31]
	s_add_i32 m0, s98, 0x4000
	v_lshl_add_u64 v[254:255], v[68:69], 0, s[100:101]
	global_load_lds_dwordx4 v[254:255], off
	v_add_u32_e32 v101, s27, v79
	s_waitcnt lgkmcnt(0)
	ds_read_b128 v[84:87], v101 offset:16384
	ds_read_b128 v[88:91], v100
	ds_read_b128 v[92:95], v100 offset:4096
	v_mfma_f32_32x32x16_bf16 v[32:47], v[236:239], v[240:243], v[32:47]
	v_mfma_f32_32x32x16_bf16 v[0:15], v[236:239], v[244:247], v[0:15]
	s_add_i32 m0, s98, 0x6000
	v_lshl_add_u64 v[254:255], v[70:71], 0, s[100:101]
	global_load_lds_dwordx4 v[254:255], off
	v_add_u32_e32 v100, s27, v76
	s_waitcnt lgkmcnt(0)
	ds_read_b128 v[236:239], v101 offset:20480
	v_mfma_f32_32x32x16_bf16 v[48:63], v[84:87], v[88:91], v[48:63]
	v_mfma_f32_32x32x16_bf16 v[16:31], v[84:87], v[92:95], v[16:31]
	s_add_i32 m0, s98, 0x8000
	v_lshl_add_u64 v[254:255], v[72:73], 0, s[100:101]
	global_load_lds_dwordx4 v[254:255], off
	v_add_u32_e32 v101, s27, v77
	s_waitcnt lgkmcnt(0)
	ds_read_b128 v[84:87], v101 offset:16384
	ds_read_b128 v[240:243], v100
	ds_read_b128 v[244:247], v100 offset:4096
	v_mfma_f32_32x32x16_bf16 v[32:47], v[236:239], v[88:91], v[32:47]
	v_mfma_f32_32x32x16_bf16 v[0:15], v[236:239], v[92:95], v[0:15]
	s_add_i32 m0, s98, 0xa000
	v_lshl_add_u64 v[254:255], v[74:75], 0, s[100:101]
	global_load_lds_dwordx4 v[254:255], off
	s_waitcnt lgkmcnt(0)
	ds_read_b128 v[236:239], v101 offset:20480
	v_mfma_f32_32x32x16_bf16 v[48:63], v[84:87], v[240:243], v[48:63]
	v_mfma_f32_32x32x16_bf16 v[16:31], v[84:87], v[244:247], v[16:31]
	s_waitcnt vmcnt(6) lgkmcnt(0)
	s_barrier
	s_waitcnt lgkmcnt(0)
	v_mfma_f32_32x32x16_bf16 v[32:47], v[236:239], v[240:243], v[32:47]
	v_mfma_f32_32x32x16_bf16 v[0:15], v[236:239], v[244:247], v[0:15]
	s_cmpk_lg_i32 s6, 0x700
	s_cbranch_scc1 .LBB0_87
; DEV int stage_next(int s) { return (s == 2 * GS_STAGE) ? 0 : s + GS_STAGE; }
; template <int WAIT0>
; DEV void gk_main(f32x16 (&acc)[2][2], const GTile& t, int s0) {
;     ...
;   GK_COMPUTE(stc);
;   vm_wait_bar<0>();
;   stc = stage_next(stc);
;   GK_COMPUTE(stc);
;   vm_wait_bar<0>();
; template <int WAIT_E, int WAIT_O, class TileFn, class EpiFn>
; DEV void gemm_seq(int ntiles, TileFn tf, EpiFn epi) {
;     ...
;   for (int i = 0; i < ntiles; ++i) {
;     f32x16 acc[2][2]; acc_zero(acc);
;     if (i == 0) gk_main<6>(acc, cur, s0);
;     else if (i & 1) gk_main<WAIT_O>(acc, cur, s0);
;     else gk_main<WAIT_E>(acc, cur, s0);
;     const int sn = stage_next(s0);
;     if (i + 1 < ntiles) { cur = tf(i + 1); gk_issue2(cur, sn); }
;     epi(i, acc, s0);
;     s0 = sn;
;   }
	s_add_i32 s6, s18, 0
	v_add_u32_e32 v84, s6, v83
	ds_read_b128 v[64:67], v84 offset:16384
	v_add_u32_e32 v72, s6, v82
	ds_read_b128 v[68:71], v72
	ds_read_b128 v[72:75], v72 offset:4096
	s_waitcnt lgkmcnt(0)
	v_mfma_f32_32x32x16_bf16 v[48:63], v[64:67], v[68:71], v[48:63]
	v_mfma_f32_32x32x16_bf16 v[16:31], v[64:67], v[72:75], v[16:31]
	ds_read_b128 v[64:67], v84 offset:20480
	v_add_u32_e32 v84, s6, v81
	s_waitcnt lgkmcnt(0)
	v_mfma_f32_32x32x16_bf16 v[32:47], v[64:67], v[68:71], v[32:47]
	v_mfma_f32_32x32x16_bf16 v[0:15], v[64:67], v[72:75], v[0:15]
	ds_read_b128 v[64:67], v84 offset:16384
	v_add_u32_e32 v72, s6, v80
	ds_read_b128 v[68:71], v72
	ds_read_b128 v[72:75], v72 offset:4096
	s_waitcnt lgkmcnt(0)
	v_mfma_f32_32x32x16_bf16 v[48:63], v[64:67], v[68:71], v[48:63]
	v_mfma_f32_32x32x16_bf16 v[16:31], v[64:67], v[72:75], v[16:31]
	ds_read_b128 v[64:67], v84 offset:20480
	v_add_u32_e32 v84, s6, v79
	s_waitcnt lgkmcnt(0)
	v_mfma_f32_32x32x16_bf16 v[32:47], v[64:67], v[68:71], v[32:47]
	v_mfma_f32_32x32x16_bf16 v[0:15], v[64:67], v[72:75], v[0:15]
	ds_read_b128 v[64:67], v84 offset:16384
	v_add_u32_e32 v72, s6, v78
	ds_read_b128 v[68:71], v72
	ds_read_b128 v[72:75], v72 offset:4096
	s_waitcnt lgkmcnt(0)
	v_mfma_f32_32x32x16_bf16 v[48:63], v[64:67], v[68:71], v[48:63]
	v_mfma_f32_32x32x16_bf16 v[16:31], v[64:67], v[72:75], v[16:31]
	ds_read_b128 v[64:67], v84 offset:20480
	v_add_u32_e32 v84, s6, v77
	s_waitcnt lgkmcnt(0)
	v_mfma_f32_32x32x16_bf16 v[32:47], v[64:67], v[68:71], v[32:47]
	v_mfma_f32_32x32x16_bf16 v[0:15], v[64:67], v[72:75], v[0:15]
	ds_read_b128 v[64:67], v84 offset:16384
	v_add_u32_e32 v72, s6, v76
	ds_read_b128 v[68:71], v72
	ds_read_b128 v[72:75], v72 offset:4096
	s_add_i32 s6, s18, 0xc000
	s_cmp_lg_u32 s18, 0x18000
	s_cselect_b32 s6, s6, 0
	s_waitcnt lgkmcnt(0)
	v_mfma_f32_32x32x16_bf16 v[48:63], v[64:67], v[68:71], v[48:63]
	s_add_i32 s6, s6, 0
	v_add_u32_e32 v83, s6, v83
	v_add_u32_e32 v81, s6, v81
	v_add_u32_e32 v79, s6, v79
	v_add_u32_e32 v77, s6, v77
	v_mfma_f32_32x32x16_bf16 v[16:31], v[64:67], v[72:75], v[16:31]
	ds_read_b128 v[64:67], v84 offset:20480
	s_waitcnt vmcnt(0) lgkmcnt(0)
	s_barrier
	s_waitcnt lgkmcnt(0)
	v_mfma_f32_32x32x16_bf16 v[32:47], v[64:67], v[68:71], v[32:47]
	v_mfma_f32_32x32x16_bf16 v[0:15], v[64:67], v[72:75], v[0:15]
	ds_read_b128 v[64:67], v83 offset:16384
	v_add_u32_e32 v72, s6, v82
	ds_read_b128 v[68:71], v72
	ds_read_b128 v[72:75], v72 offset:4096
	s_waitcnt lgkmcnt(0)
	v_mfma_f32_32x32x16_bf16 v[48:63], v[64:67], v[68:71], v[48:63]
	v_mfma_f32_32x32x16_bf16 v[16:31], v[64:67], v[72:75], v[16:31]
	ds_read_b128 v[64:67], v83 offset:20480
	s_waitcnt lgkmcnt(0)
	v_mfma_f32_32x32x16_bf16 v[32:47], v[64:67], v[68:71], v[32:47]
	v_mfma_f32_32x32x16_bf16 v[0:15], v[64:67], v[72:75], v[0:15]
	ds_read_b128 v[64:67], v81 offset:16384
	v_add_u32_e32 v72, s6, v80
	ds_read_b128 v[68:71], v72
	ds_read_b128 v[72:75], v72 offset:4096
	s_waitcnt lgkmcnt(0)
	v_mfma_f32_32x32x16_bf16 v[48:63], v[64:67], v[68:71], v[48:63]
	v_mfma_f32_32x32x16_bf16 v[16:31], v[64:67], v[72:75], v[16:31]
	ds_read_b128 v[64:67], v81 offset:20480
	s_waitcnt lgkmcnt(0)
	v_mfma_f32_32x32x16_bf16 v[32:47], v[64:67], v[68:71], v[32:47]
	v_mfma_f32_32x32x16_bf16 v[0:15], v[64:67], v[72:75], v[0:15]
	ds_read_b128 v[64:67], v79 offset:16384
	v_add_u32_e32 v72, s6, v78
	ds_read_b128 v[68:71], v72
	ds_read_b128 v[72:75], v72 offset:4096
	s_waitcnt lgkmcnt(0)
	v_mfma_f32_32x32x16_bf16 v[48:63], v[64:67], v[68:71], v[48:63]
	v_mfma_f32_32x32x16_bf16 v[16:31], v[64:67], v[72:75], v[16:31]
	ds_read_b128 v[64:67], v79 offset:20480
	s_waitcnt lgkmcnt(0)
	v_mfma_f32_32x32x16_bf16 v[32:47], v[64:67], v[68:71], v[32:47]
	v_mfma_f32_32x32x16_bf16 v[0:15], v[64:67], v[72:75], v[0:15]
	ds_read_b128 v[64:67], v77 offset:16384
	v_add_u32_e32 v72, s6, v76
	ds_read_b128 v[68:71], v72
	ds_read_b128 v[72:75], v72 offset:4096
	s_waitcnt lgkmcnt(0)
	v_mfma_f32_32x32x16_bf16 v[48:63], v[64:67], v[68:71], v[48:63]
	v_mfma_f32_32x32x16_bf16 v[16:31], v[64:67], v[72:75], v[16:31]
	ds_read_b128 v[64:67], v77 offset:20480
	s_waitcnt vmcnt(0) lgkmcnt(0)
	s_barrier
	s_waitcnt lgkmcnt(0)
	v_mfma_f32_32x32x16_bf16 v[32:47], v[64:67], v[68:71], v[32:47]
	v_mfma_f32_32x32x16_bf16 v[0:15], v[64:67], v[72:75], v[0:15]
	s_add_i32 s18, s17, 1
	s_cmp_eq_u32 s17, 11
	s_cbranch_scc1 .LBB0_83

; DEV bf16_t f2bf(float f) { return (bf16_t)(pk2(f, 0.f) & 0xffffu); }
; DEV int stage_next(int s) { return (s == 2 * GS_STAGE) ? 0 : s + GS_STAGE; }
; #define FOR_ACC _Pragma("unroll") for (int nb = 0; nb < 2; ++nb) _Pragma("unroll") for (int mb = 0; mb < 2; ++mb) _Pragma("unroll") for (int rq = 0; rq < 4; ++rq)
; template <int WAIT0>
; DEV void gk_main(f32x16 (&acc)[2][2], const GTile& t, int s0) {
;     ...
;   vm_wait_bar<WAIT0>();
;   int stc = s0, std_ = stage_next(stage_next(s0));
; #pragma nounroll
;   for (int kt = 0; kt < nk - 2; ++kt) {
;     GK_DMA(std_, kt + 2);
;     GK_COMPUTE(stc);
;     vm_wait_bar<6>();
;     stc = stage_next(stc); std_ = stage_next(std_);
;   }
;   GK_COMPUTE(stc);
;   vm_wait_bar<0>();
;   stc = stage_next(stc);
;   GK_COMPUTE(stc);
;   vm_wait_bar<0>();
; DEV void fold_unit(const Params& P, int u) {
;     ...
;     FOR_ACC {
;       const int j = jt * 128 + 64 * wm + 32 * mb + l32, n = 64 * wn + 32 * nb + 8 * rq + 4 * hi;
; #pragma unroll
;       for (int e = 0; e < 4; ++e) wpt[((size_t)l * 2048 + hh * 256 + n + e) * 1024 + j] = f2bf(acc[nb][mb][4 * rq + e]);
.LBB0_96:
	s_add_i32 s39, s38, s24
	s_mov_b32 s98, s39
	s_mov_b64 s[100:101], s[22:23]
	s_add_i32 s40, s25, 0
	v_add_u32_e32 v252, s40, v89
	v_add_u32_e32 v91, s40, v88
	ds_read_b128 v[92:95], v252 offset:16384
	ds_read_b128 v[96:99], v91
	ds_read_b128 v[100:103], v91 offset:4096
	ds_read_b128 v[104:107], v252 offset:20480
	s_waitcnt lgkmcnt(0)
	v_add_u32_e32 v108, s40, v87
	v_add_u32_e32 v91, s40, v86
	s_add_i32 s39, s25, 0xc000
	s_cmp_lg_u32 s25, 0x18000
	s_cselect_b32 s25, s39, 0
	s_add_i32 s39, s24, 0xc000
	s_cmp_lg_u32 s24, 0x18000
	s_cselect_b32 s24, s39, 0
	s_add_u32 s22, s22, 0x80
	s_addc_u32 s23, s23, 0
	ds_read_b128 v[236:239], v108 offset:16384
	ds_read_b128 v[240:243], v91
	ds_read_b128 v[244:247], v91 offset:4096
	ds_read_b128 v[248:251], v108 offset:20480
	v_mfma_f32_32x32x16_bf16 v[48:63], v[92:95], v[96:99], v[48:63]
	v_mfma_f32_32x32x16_bf16 v[32:47], v[92:95], v[100:103], v[32:47]
	s_mov_b32 m0, s98
	v_lshl_add_u64 v[254:255], v[64:65], 0, s[100:101]
	global_load_lds_dwordx4 v[254:255], off
	v_mfma_f32_32x32x16_bf16 v[16:31], v[104:107], v[96:99], v[16:31]
	v_mfma_f32_32x32x16_bf16 v[0:15], v[104:107], v[100:103], v[0:15]
	s_add_i32 m0, s98, 0x2000
	v_lshl_add_u64 v[254:255], v[66:67], 0, s[100:101]
	global_load_lds_dwordx4 v[254:255], off
	v_add_u32_e32 v108, s40, v85
	v_add_u32_e32 v91, s40, v84
	s_waitcnt lgkmcnt(0)
	ds_read_b128 v[92:95], v108 offset:16384
	ds_read_b128 v[96:99], v91
	ds_read_b128 v[100:103], v91 offset:4096
	ds_read_b128 v[104:107], v108 offset:20480
	v_mfma_f32_32x32x16_bf16 v[48:63], v[236:239], v[240:243], v[48:63]
	v_mfma_f32_32x32x16_bf16 v[32:47], v[236:239], v[244:247], v[32:47]
	s_add_i32 m0, s98, 0x4000
	v_lshl_add_u64 v[254:255], v[68:69], 0, s[100:101]
	global_load_lds_dwordx4 v[254:255], off
	v_mfma_f32_32x32x16_bf16 v[16:31], v[248:251], v[240:243], v[16:31]
	v_mfma_f32_32x32x16_bf16 v[0:15], v[248:251], v[244:247], v[0:15]
	s_add_i32 m0, s98, 0x6000
	v_lshl_add_u64 v[254:255], v[70:71], 0, s[100:101]
	global_load_lds_dwordx4 v[254:255], off
	v_add_u32_e32 v108, s40, v83
	v_add_u32_e32 v91, s40, v80
	s_waitcnt lgkmcnt(0)
	ds_read_b128 v[236:239], v108 offset:16384
	ds_read_b128 v[240:243], v91
	ds_read_b128 v[244:247], v91 offset:4096
	ds_read_b128 v[248:251], v108 offset:20480
	v_mfma_f32_32x32x16_bf16 v[48:63], v[92:95], v[96:99], v[48:63]
	v_mfma_f32_32x32x16_bf16 v[32:47], v[92:95], v[100:103], v[32:47]
	s_add_i32 m0, s98, 0x8000
	v_lshl_add_u64 v[254:255], v[72:73], 0, s[100:101]
	global_load_lds_dwordx4 v[254:255], off
	v_mfma_f32_32x32x16_bf16 v[16:31], v[104:107], v[96:99], v[16:31]
	v_mfma_f32_32x32x16_bf16 v[0:15], v[104:107], v[100:103], v[0:15]
	s_add_i32 m0, s98, 0xa000
	v_lshl_add_u64 v[254:255], v[74:75], 0, s[100:101]
	global_load_lds_dwordx4 v[254:255], off
	s_waitcnt vmcnt(6) lgkmcnt(0)
	s_barrier
	s_waitcnt lgkmcnt(0)
	v_mfma_f32_32x32x16_bf16 v[48:63], v[236:239], v[240:243], v[48:63]
	v_mfma_f32_32x32x16_bf16 v[32:47], v[236:239], v[244:247], v[32:47]
	v_mfma_f32_32x32x16_bf16 v[16:31], v[248:251], v[240:243], v[16:31]
	v_mfma_f32_32x32x16_bf16 v[0:15], v[248:251], v[244:247], v[0:15]
	s_cmpk_lg_i32 s22, 0x100
	s_cbranch_scc1 .LBB0_96
	v_add_u32_e32 v72, 0x4000, v79
	v_or_b32_e32 v64, v72, v90
	v_add_u32_e32 v73, s35, v64
	ds_read_b128 v[64:67], v73
	v_add_u32_e32 v74, s35, v88
	ds_read_b128 v[68:71], v74
	ds_read_b128 v[90:93], v74 offset:4096
	ds_read_b128 v[94:97], v73 offset:4096
	v_or_b32_e32 v73, v72, v76
	v_or_b32_e32 v74, v72, v77
	s_waitcnt lgkmcnt(0)
	v_mfma_f32_32x32x16_bf16 v[16:31], v[94:97], v[68:71], v[16:31]
	v_or_b32_e32 v76, v72, v78
	v_add_u32_e32 v72, s35, v80
	v_add_u32_e32 v76, s35, v76
	v_add_u32_e32 v88, 0, v88
	v_add_u32_e32 v154, 0, v87
	v_add_u32_e32 v80, 0, v80
	s_lshl_b64 s[20:21], s[20:21], 11
	v_mfma_f32_32x32x16_bf16 v[48:63], v[64:67], v[68:71], v[48:63]
	v_add_u32_e32 v68, s35, v74
	s_or_b64 s[20:21], s[20:21], s[8:9]
	s_add_i32 s36, s36, s86
	s_add_i32 s30, s30, s31
	s_add_i32 s33, s33, s34
	s_cmpk_gt_i32 s36, 0x7f
	v_mfma_f32_32x32x16_bf16 v[32:47], v[64:67], v[90:93], v[32:47]
	v_add_u32_e32 v64, s35, v86
	ds_read_b128 v[98:101], v64
	ds_read_b128 v[102:105], v64 offset:4096
	v_add_u32_e32 v64, s35, v73
	ds_read_b128 v[106:109], v64
	ds_read_b128 v[110:113], v64 offset:4096
	v_add_u32_e32 v64, s35, v84
	ds_read_b128 v[114:117], v64
	ds_read_b128 v[64:67], v64 offset:4096
	ds_read_b128 v[118:121], v68
	ds_read_b128 v[68:71], v68 offset:4096
	s_waitcnt lgkmcnt(0)
	v_mfma_f32_32x32x16_bf16 v[48:63], v[106:109], v[98:101], v[48:63]
	ds_read_b128 v[122:125], v72
	ds_read_b128 v[72:75], v72 offset:4096
	ds_read_b128 v[126:129], v76
	ds_read_b128 v[76:79], v76 offset:4096
	s_waitcnt vmcnt(0) lgkmcnt(0)
	s_barrier
	ds_read_b128 v[130:133], v88
	ds_read_b128 v[134:137], v88 offset:4096
	v_add_u32_e32 v88, 0, v89
	v_mfma_f32_32x32x16_bf16 v[48:63], v[118:121], v[114:117], v[48:63]
	ds_read_b128 v[138:141], v88 offset:16384
	ds_read_b128 v[142:145], v88 offset:20480
	v_add_u32_e32 v86, 0, v86
	ds_read_b128 v[146:149], v86
	ds_read_b128 v[150:153], v86 offset:4096
	ds_read_b128 v[86:89], v154 offset:16384
	ds_read_b128 v[154:157], v154 offset:20480
	v_add_u32_e32 v84, 0, v84
	ds_read_b128 v[158:161], v84
	ds_read_b128 v[162:165], v84 offset:4096
	v_add_u32_e32 v84, 0, v85
	s_waitcnt lgkmcnt(0)
	v_mfma_f32_32x32x16_bf16 v[48:63], v[126:129], v[122:125], v[48:63]
	ds_read_b128 v[166:169], v84 offset:16384
	ds_read_b128 v[170:173], v84 offset:20480
	ds_read_b128 v[182:185], v80
	ds_read_b128 v[186:189], v80 offset:4096
	v_add_u32_e32 v80, 0, v83
	ds_read_b128 v[190:193], v80 offset:16384
	ds_read_b128 v[194:197], v80 offset:20480
	v_ashrrev_i32_e32 v83, 1, v82
	v_and_b32_e32 v80, 0x5f, v82
	v_and_b32_e32 v83, 0xffffffc0, v83
	v_mfma_f32_32x32x16_bf16 v[48:63], v[138:141], v[130:133], v[48:63]
	v_lshrrev_b32_e32 v82, 3, v82
	v_and_or_b32 v84, v82, 4, v83
	v_or_b32_e32 v80, s37, v80
	v_ashrrev_i32_e32 v85, 31, v84
	v_lshlrev_b32_e32 v80, 1, v80
	v_lshl_add_u64 v[174:175], s[20:21], 0, v[84:85]
	v_lshl_add_u64 v[82:83], s[2:3], 0, v[80:81]
	v_mfma_f32_32x32x16_bf16 v[32:47], v[106:109], v[102:105], v[32:47]
	v_lshlrev_b64 v[174:175], 11, v[174:175]
	v_lshl_add_u64 v[198:199], v[82:83], 0, v[174:175]
	s_waitcnt vmcnt(0) lgkmcnt(0)
	s_barrier
; DEV bf16_t f2bf(float f) { return (bf16_t)(pk2(f, 0.f) & 0xffffu); }
; DEV int stage_next(int s) { return (s == 2 * GS_STAGE) ? 0 : s + GS_STAGE; }
; #define FOR_ACC _Pragma("unroll") for (int nb = 0; nb < 2; ++nb) _Pragma("unroll") for (int mb = 0; mb < 2; ++mb) _Pragma("unroll") for (int rq = 0; rq < 4; ++rq)
; template <int WAIT0>
; DEV void gk_main(f32x16 (&acc)[2][2], const GTile& t, int s0) {
;     ...
;   GK_COMPUTE(stc);
;   vm_wait_bar<0>();
;   stc = stage_next(stc);
;   GK_COMPUTE(stc);
;   vm_wait_bar<0>();
; DEV void fold_unit(const Params& P, int u) {
;     ...
;     FOR_ACC {
;       const int j = jt * 128 + 64 * wm + 32 * mb + l32, n = 64 * wn + 32 * nb + 8 * rq + 4 * hi;
; #pragma unroll
;       for (int e = 0; e < 4; ++e) wpt[((size_t)l * 2048 + hh * 256 + n + e) * 1024 + j] = f2bf(acc[nb][mb][4 * rq + e]);
	v_mfma_f32_32x32x16_bf16 v[48:63], v[86:89], v[146:149], v[48:63]
	v_mfma_f32_32x32x16_bf16 v[32:47], v[118:121], v[64:67], v[32:47]
	s_waitcnt lgkmcnt(0)
	v_mfma_f32_32x32x16_bf16 v[48:63], v[166:169], v[158:161], v[48:63]
	v_mfma_f32_32x32x16_bf16 v[32:47], v[126:129], v[72:75], v[32:47]
	v_mfma_f32_32x32x16_bf16 v[48:63], v[190:193], v[182:185], v[48:63]
	v_mfma_f32_32x32x16_bf16 v[16:31], v[110:113], v[98:101], v[16:31]
	s_nop 10
	v_cvt_pk_bf16_f32 v48, v48, s0
	global_store_short v[198:199], v48, off
	v_cvt_pk_bf16_f32 v48, v49, s0
	global_store_short v[198:199], v48, off offset:2048
	v_or_b32_e32 v48, 0x1000, v174
	v_mov_b32_e32 v49, v175
	v_cvt_pk_bf16_f32 v50, v50, s0
	v_mfma_f32_32x32x16_bf16 v[32:47], v[138:141], v[134:137], v[32:47]
	v_or_b32_e32 v174, 0x1800, v174
	v_cvt_pk_bf16_f32 v80, v51, s0
	v_cvt_pk_bf16_f32 v52, v52, s0
	v_cvt_pk_bf16_f32 v54, v54, s0
	v_cvt_pk_bf16_f32 v56, v56, s0
	v_cvt_pk_bf16_f32 v58, v58, s0
	v_cvt_pk_bf16_f32 v60, v60, s0
	v_mfma_f32_32x32x16_bf16 v[16:31], v[68:71], v[114:117], v[16:31]
	v_cvt_pk_bf16_f32 v62, v62, s0
	v_mfma_f32_32x32x16_bf16 v[0:15], v[94:97], v[90:93], v[0:15]
	v_lshl_add_u64 v[90:91], v[82:83], 0, v[48:49]
	global_store_short v[90:91], v50, off
	v_lshl_add_u64 v[50:51], v[82:83], 0, v[174:175]
	global_store_short v[50:51], v80, off
	v_or_b32_e32 v50, 8, v84
	v_ashrrev_i32_e32 v51, 31, v50
	v_lshl_add_u64 v[50:51], s[20:21], 0, v[50:51]
	v_mfma_f32_32x32x16_bf16 v[32:47], v[86:89], v[150:153], v[32:47]
	v_lshlrev_b64 v[50:51], 11, v[50:51]
	v_lshl_add_u64 v[90:91], v[82:83], 0, v[50:51]
	global_store_short v[90:91], v52, off
	v_cvt_pk_bf16_f32 v80, v53, s0
	v_or_b32_e32 v52, 0x800, v50
	v_mov_b32_e32 v53, v51
	v_or_b32_e32 v92, 0x1000, v50
	v_mfma_f32_32x32x16_bf16 v[16:31], v[76:79], v[122:125], v[16:31]
	v_mov_b32_e32 v93, v51
	v_lshl_add_u64 v[52:53], v[82:83], 0, v[52:53]
	v_lshl_add_u64 v[92:93], v[82:83], 0, v[92:93]
	v_or_b32_e32 v50, 0x1800, v50
	global_store_short v[52:53], v80, off
	global_store_short v[92:93], v54, off
	v_cvt_pk_bf16_f32 v54, v55, s0
	v_lshl_add_u64 v[50:51], v[82:83], 0, v[50:51]
	v_mfma_f32_32x32x16_bf16 v[32:47], v[166:169], v[162:165], v[32:47]
	global_store_short v[50:51], v54, off
	v_or_b32_e32 v54, 16, v84
	v_ashrrev_i32_e32 v55, 31, v54
	v_lshl_add_u64 v[54:55], s[20:21], 0, v[54:55]
	v_lshlrev_b64 v[54:55], 11, v[54:55]
	v_lshl_add_u64 v[94:95], v[82:83], 0, v[54:55]
	global_store_short v[94:95], v56, off
	v_mfma_f32_32x32x16_bf16 v[16:31], v[142:145], v[130:133], v[16:31]
	v_cvt_pk_bf16_f32 v80, v57, s0
	v_or_b32_e32 v56, 0x800, v54
	v_mov_b32_e32 v57, v55
	v_or_b32_e32 v96, 0x1000, v54
	v_mov_b32_e32 v97, v55
	v_lshl_add_u64 v[56:57], v[82:83], 0, v[56:57]
	v_lshl_add_u64 v[96:97], v[82:83], 0, v[96:97]
	v_or_b32_e32 v54, 0x1800, v54
	global_store_short v[56:57], v80, off
	global_store_short v[96:97], v58, off
	v_cvt_pk_bf16_f32 v58, v59, s0
	v_lshl_add_u64 v[54:55], v[82:83], 0, v[54:55]
	v_mfma_f32_32x32x16_bf16 v[32:47], v[190:193], v[186:189], v[32:47]
	global_store_short v[54:55], v58, off
	v_or_b32_e32 v58, 24, v84
	v_ashrrev_i32_e32 v59, 31, v58
	v_lshl_add_u64 v[58:59], s[20:21], 0, v[58:59]
	v_lshlrev_b64 v[58:59], 11, v[58:59]
	v_lshl_add_u64 v[86:87], v[82:83], 0, v[58:59]
	global_store_short v[86:87], v60, off
	v_mfma_f32_32x32x16_bf16 v[0:15], v[110:113], v[102:105], v[0:15]
	v_cvt_pk_bf16_f32 v80, v61, s0
	v_or_b32_e32 v60, 0x800, v58
	v_mov_b32_e32 v61, v59
	v_or_b32_e32 v88, 0x1000, v58
	v_mov_b32_e32 v89, v59
	v_lshl_add_u64 v[60:61], v[82:83], 0, v[60:61]
	v_lshl_add_u64 v[88:89], v[82:83], 0, v[88:89]
	v_mfma_f32_32x32x16_bf16 v[16:31], v[154:157], v[146:149], v[16:31]
	v_or_b32_e32 v58, 0x1800, v58
	global_store_short v[60:61], v80, off
	global_store_short v[88:89], v62, off
	v_cvt_pk_bf16_f32 v62, v63, s0
	v_lshl_add_u64 v[58:59], v[82:83], 0, v[58:59]
	v_cvt_pk_bf16_f32 v32, v32, s0
	global_store_short v[58:59], v62, off
	v_lshl_add_u64 v[62:63], v[82:83], 0, 64
	global_store_short v[198:199], v32, off offset:64
	v_cvt_pk_bf16_f32 v32, v33, s0
	global_store_short v[198:199], v32, off offset:2112
	v_cvt_pk_bf16_f32 v34, v34, s0
	v_lshl_add_u64 v[32:33], v[62:63], 0, v[48:49]
	global_store_short v[32:33], v34, off
	v_cvt_pk_bf16_f32 v34, v35, s0
	v_lshl_add_u64 v[32:33], v[62:63], 0, v[174:175]
	global_store_short v[32:33], v34, off
	v_cvt_pk_bf16_f32 v32, v36, s0
	v_mfma_f32_32x32x16_bf16 v[16:31], v[170:173], v[158:161], v[16:31]
	global_store_short v[90:91], v32, off offset:64
	v_cvt_pk_bf16_f32 v32, v37, s0
	global_store_short v[52:53], v32, off offset:64
	v_cvt_pk_bf16_f32 v32, v38, s0
	global_store_short v[92:93], v32, off offset:64
	v_cvt_pk_bf16_f32 v32, v39, s0
	global_store_short v[50:51], v32, off offset:64
	v_mfma_f32_32x32x16_bf16 v[0:15], v[68:71], v[64:67], v[0:15]
	v_cvt_pk_bf16_f32 v32, v40, s0
	global_store_short v[94:95], v32, off offset:64
	v_cvt_pk_bf16_f32 v32, v41, s0
	global_store_short v[56:57], v32, off offset:64
	v_cvt_pk_bf16_f32 v32, v42, s0
	global_store_short v[96:97], v32, off offset:64
	v_cvt_pk_bf16_f32 v32, v43, s0
	global_store_short v[54:55], v32, off offset:64
; DEV bf16_t f2bf(float f) { return (bf16_t)(pk2(f, 0.f) & 0xffffu); }
; #define FOR_ACC _Pragma("unroll") for (int nb = 0; nb < 2; ++nb) _Pragma("unroll") for (int mb = 0; mb < 2; ++mb) _Pragma("unroll") for (int rq = 0; rq < 4; ++rq)
; DEV void fold_unit(const Params& P, int u) {
;     ...
;     FOR_ACC {
;       const int j = jt * 128 + 64 * wm + 32 * mb + l32, n = 64 * wn + 32 * nb + 8 * rq + 4 * hi;
; #pragma unroll
;       for (int e = 0; e < 4; ++e) wpt[((size_t)l * 2048 + hh * 256 + n + e) * 1024 + j] = f2bf(acc[nb][mb][4 * rq + e]);
	v_cvt_pk_bf16_f32 v32, v44, s0
	v_mfma_f32_32x32x16_bf16 v[16:31], v[194:197], v[182:185], v[16:31]
	global_store_short v[86:87], v32, off offset:64
	v_cvt_pk_bf16_f32 v32, v45, s0
	global_store_short v[60:61], v32, off offset:64
	v_cvt_pk_bf16_f32 v32, v46, s0
	global_store_short v[88:89], v32, off offset:64
	v_cvt_pk_bf16_f32 v32, v47, s0
	global_store_short v[58:59], v32, off offset:64
	v_mfma_f32_32x32x16_bf16 v[0:15], v[76:79], v[72:75], v[0:15]
	v_or_b32_e32 v32, 32, v84
	v_ashrrev_i32_e32 v33, 31, v32
	v_lshl_add_u64 v[32:33], s[20:21], 0, v[32:33]
	v_lshlrev_b64 v[32:33], 11, v[32:33]
	v_cvt_pk_bf16_f32 v16, v16, s0
	v_lshl_add_u64 v[34:35], v[82:83], 0, v[32:33]
	global_store_short v[34:35], v16, off
	v_mfma_f32_32x32x16_bf16 v[0:15], v[142:145], v[134:137], v[0:15]
	v_cvt_pk_bf16_f32 v36, v17, s0
	v_or_b32_e32 v16, 0x800, v32
	v_mov_b32_e32 v17, v33
	v_lshl_add_u64 v[16:17], v[82:83], 0, v[16:17]
	global_store_short v[16:17], v36, off
	v_or_b32_e32 v36, 0x1000, v32
	v_mov_b32_e32 v37, v33
	v_cvt_pk_bf16_f32 v18, v18, s0
	v_lshl_add_u64 v[36:37], v[82:83], 0, v[36:37]
	v_or_b32_e32 v32, 0x1800, v32
	global_store_short v[36:37], v18, off
	v_cvt_pk_bf16_f32 v38, v19, s0
	v_lshl_add_u64 v[18:19], v[82:83], 0, v[32:33]
	v_or_b32_e32 v32, 40, v84
	v_ashrrev_i32_e32 v33, 31, v32
	v_lshl_add_u64 v[32:33], s[20:21], 0, v[32:33]
	v_mfma_f32_32x32x16_bf16 v[0:15], v[154:157], v[150:153], v[0:15]
	v_lshlrev_b64 v[32:33], 11, v[32:33]
	global_store_short v[18:19], v38, off
	v_cvt_pk_bf16_f32 v20, v20, s0
	v_lshl_add_u64 v[38:39], v[82:83], 0, v[32:33]
	global_store_short v[38:39], v20, off
	v_cvt_pk_bf16_f32 v40, v21, s0
	v_or_b32_e32 v20, 0x800, v32
	v_mov_b32_e32 v21, v33
	v_lshl_add_u64 v[20:21], v[82:83], 0, v[20:21]
	global_store_short v[20:21], v40, off
	v_or_b32_e32 v40, 0x1000, v32
	v_mov_b32_e32 v41, v33
	v_cvt_pk_bf16_f32 v22, v22, s0
	v_lshl_add_u64 v[40:41], v[82:83], 0, v[40:41]
	v_or_b32_e32 v32, 0x1800, v32
	global_store_short v[40:41], v22, off
	v_cvt_pk_bf16_f32 v42, v23, s0
	v_lshl_add_u64 v[22:23], v[82:83], 0, v[32:33]
	v_or_b32_e32 v32, 48, v84
	v_ashrrev_i32_e32 v33, 31, v32
	v_mfma_f32_32x32x16_bf16 v[0:15], v[170:173], v[162:165], v[0:15]
	v_lshl_add_u64 v[32:33], s[20:21], 0, v[32:33]
	v_lshlrev_b64 v[32:33], 11, v[32:33]
	global_store_short v[22:23], v42, off
	v_cvt_pk_bf16_f32 v24, v24, s0
	v_lshl_add_u64 v[42:43], v[82:83], 0, v[32:33]
	global_store_short v[42:43], v24, off
	v_cvt_pk_bf16_f32 v44, v25, s0
	v_or_b32_e32 v24, 0x800, v32
	v_mov_b32_e32 v25, v33
	v_lshl_add_u64 v[24:25], v[82:83], 0, v[24:25]
	global_store_short v[24:25], v44, off
	v_or_b32_e32 v44, 0x1000, v32
	v_mov_b32_e32 v45, v33
	v_cvt_pk_bf16_f32 v26, v26, s0
	v_lshl_add_u64 v[44:45], v[82:83], 0, v[44:45]
	v_or_b32_e32 v32, 0x1800, v32
	global_store_short v[44:45], v26, off
	v_cvt_pk_bf16_f32 v46, v27, s0
	v_lshl_add_u64 v[26:27], v[82:83], 0, v[32:33]
	v_or_b32_e32 v32, 56, v84
	v_mfma_f32_32x32x16_bf16 v[0:15], v[194:197], v[186:189], v[0:15]
	v_ashrrev_i32_e32 v33, 31, v32
	v_lshl_add_u64 v[32:33], s[20:21], 0, v[32:33]
	v_lshlrev_b64 v[32:33], 11, v[32:33]
	global_store_short v[26:27], v46, off
	v_cvt_pk_bf16_f32 v28, v28, s0
	v_lshl_add_u64 v[46:47], v[82:83], 0, v[32:33]
	global_store_short v[46:47], v28, off
	v_cvt_pk_bf16_f32 v48, v29, s0
	v_or_b32_e32 v28, 0x800, v32
	v_mov_b32_e32 v29, v33
	v_lshl_add_u64 v[28:29], v[82:83], 0, v[28:29]
	global_store_short v[28:29], v48, off
	v_or_b32_e32 v48, 0x1000, v32
	v_mov_b32_e32 v49, v33
	v_cvt_pk_bf16_f32 v30, v30, s0
	v_lshl_add_u64 v[48:49], v[82:83], 0, v[48:49]
	v_or_b32_e32 v32, 0x1800, v32
	global_store_short v[48:49], v30, off
	v_cvt_pk_bf16_f32 v50, v31, s0
	v_lshl_add_u64 v[30:31], v[82:83], 0, v[32:33]
	v_cvt_pk_bf16_f32 v0, v0, s0
	global_store_short v[30:31], v50, off
	global_store_short v[34:35], v0, off offset:64
	v_cvt_pk_bf16_f32 v0, v1, s0
	global_store_short v[16:17], v0, off offset:64
	v_cvt_pk_bf16_f32 v0, v2, s0
	global_store_short v[36:37], v0, off offset:64
	v_cvt_pk_bf16_f32 v0, v3, s0
	global_store_short v[18:19], v0, off offset:64
	v_cvt_pk_bf16_f32 v0, v4, s0
	global_store_short v[38:39], v0, off offset:64
	v_cvt_pk_bf16_f32 v0, v5, s0
	global_store_short v[20:21], v0, off offset:64
	v_cvt_pk_bf16_f32 v0, v6, s0
	global_store_short v[40:41], v0, off offset:64
	v_cvt_pk_bf16_f32 v0, v7, s0
	global_store_short v[22:23], v0, off offset:64
	v_cvt_pk_bf16_f32 v0, v8, s0
	global_store_short v[42:43], v0, off offset:64
	v_cvt_pk_bf16_f32 v0, v9, s0
	global_store_short v[24:25], v0, off offset:64
	v_cvt_pk_bf16_f32 v0, v10, s0
	global_store_short v[44:45], v0, off offset:64
	v_cvt_pk_bf16_f32 v0, v11, s0
	global_store_short v[26:27], v0, off offset:64
	v_cvt_pk_bf16_f32 v0, v12, s0
	global_store_short v[46:47], v0, off offset:64
	v_cvt_pk_bf16_f32 v0, v13, s0
	global_store_short v[28:29], v0, off offset:64
	v_cvt_pk_bf16_f32 v0, v14, s0
	global_store_short v[48:49], v0, off offset:64
	v_cvt_pk_bf16_f32 v0, v15, s0
	global_store_short v[30:31], v0, off offset:64
	s_waitcnt vmcnt(0)
	s_cbranch_scc0 .LBB0_95

; DEV int stage_next(int s) { return (s == 2 * GS_STAGE) ? 0 : s + GS_STAGE; }
; template <int WAIT0>
; DEV void gk_main(f32x16 (&acc)[2][2], const GTile& t, int s0) {
;     ...
;   vm_wait_bar<WAIT0>();
;   int stc = s0, std_ = stage_next(stage_next(s0));
; #pragma nounroll
;   for (int kt = 0; kt < nk - 2; ++kt) {
;     GK_DMA(std_, kt + 2);
;     GK_COMPUTE(stc);
;     vm_wait_bar<6>();
;     stc = stage_next(stc); std_ = stage_next(std_);
;   }
.LBB0_276:
	s_add_i32 s12, s10, s11
	s_mov_b32 s98, s12
	s_mov_b64 s[100:101], s[6:7]
	s_add_i32 s12, s3, 0
	v_add_u32_e32 v252, s12, v82
	v_add_u32_e32 v253, s12, v83
	ds_read_b128 v[84:87], v252
	ds_read_b128 v[88:91], v252 offset:4096
	ds_read_b128 v[92:95], v253 offset:16384
	ds_read_b128 v[96:99], v253 offset:20480
	s_waitcnt lgkmcnt(0)
	v_add_u32_e32 v252, s12, v80
	v_add_u32_e32 v253, s12, v81
	ds_read_b128 v[236:239], v252
	ds_read_b128 v[240:243], v252 offset:4096
	ds_read_b128 v[244:247], v253 offset:16384
	ds_read_b128 v[248:251], v253 offset:20480
	v_mfma_f32_32x32x16_bf16 v[48:63], v[92:95], v[84:87], v[48:63]
	v_mfma_f32_32x32x16_bf16 v[16:31], v[92:95], v[88:91], v[16:31]
	s_mov_b32 m0, s98
	v_lshl_add_u64 v[254:255], v[74:75], 0, s[100:101]
	global_load_lds_dwordx4 v[254:255], off
	v_mfma_f32_32x32x16_bf16 v[32:47], v[96:99], v[84:87], v[32:47]
	v_mfma_f32_32x32x16_bf16 v[0:15], v[96:99], v[88:91], v[0:15]
	s_add_i32 m0, s98, 0x2000
	v_lshl_add_u64 v[254:255], v[72:73], 0, s[100:101]
	global_load_lds_dwordx4 v[254:255], off
	s_waitcnt lgkmcnt(0)
	v_add_u32_e32 v252, s12, v78
	v_add_u32_e32 v253, s12, v79
	ds_read_b128 v[84:87], v252
	ds_read_b128 v[88:91], v252 offset:4096
	ds_read_b128 v[92:95], v253 offset:16384
	ds_read_b128 v[96:99], v253 offset:20480
	v_mfma_f32_32x32x16_bf16 v[48:63], v[244:247], v[236:239], v[48:63]
	v_mfma_f32_32x32x16_bf16 v[16:31], v[244:247], v[240:243], v[16:31]
	s_add_i32 m0, s98, 0x4000
	v_lshl_add_u64 v[254:255], v[70:71], 0, s[100:101]
	global_load_lds_dwordx4 v[254:255], off
	v_mfma_f32_32x32x16_bf16 v[32:47], v[248:251], v[236:239], v[32:47]
	v_mfma_f32_32x32x16_bf16 v[0:15], v[248:251], v[240:243], v[0:15]
	s_add_i32 m0, s98, 0x6000
	v_lshl_add_u64 v[254:255], v[68:69], 0, s[100:101]
	global_load_lds_dwordx4 v[254:255], off
	s_waitcnt lgkmcnt(0)
	v_add_u32_e32 v252, s12, v76
	v_add_u32_e32 v253, s12, v77
	ds_read_b128 v[236:239], v252
	ds_read_b128 v[240:243], v252 offset:4096
	ds_read_b128 v[244:247], v253 offset:16384
	ds_read_b128 v[248:251], v253 offset:20480
	v_mfma_f32_32x32x16_bf16 v[48:63], v[92:95], v[84:87], v[48:63]
	v_mfma_f32_32x32x16_bf16 v[16:31], v[92:95], v[88:91], v[16:31]
	s_add_i32 m0, s98, 0x8000
	v_lshl_add_u64 v[254:255], v[66:67], 0, s[100:101]
	global_load_lds_dwordx4 v[254:255], off
	v_mfma_f32_32x32x16_bf16 v[32:47], v[96:99], v[84:87], v[32:47]
	v_mfma_f32_32x32x16_bf16 v[0:15], v[96:99], v[88:91], v[0:15]
	s_add_i32 m0, s98, 0xa000
	v_lshl_add_u64 v[254:255], v[64:65], 0, s[100:101]
	global_load_lds_dwordx4 v[254:255], off
	s_add_i32 s12, s3, 0xc000
	s_cmp_lg_u32 s3, 0x18000
	s_cselect_b32 s3, s12, 0
	s_waitcnt lgkmcnt(0)
	v_mfma_f32_32x32x16_bf16 v[48:63], v[244:247], v[236:239], v[48:63]
	s_add_i32 s12, s11, 0xc000
	s_cmp_lg_u32 s11, 0x18000
	s_waitcnt vmcnt(6) lgkmcnt(0)
	s_barrier
	s_cselect_b32 s11, s12, 0
	s_add_u32 s6, s6, 0x80
	v_mfma_f32_32x32x16_bf16 v[16:31], v[244:247], v[240:243], v[16:31]
	s_addc_u32 s7, s7, 0
	v_mfma_f32_32x32x16_bf16 v[32:47], v[248:251], v[236:239], v[32:47]
	v_mfma_f32_32x32x16_bf16 v[0:15], v[248:251], v[240:243], v[0:15]
	s_cmpk_lg_i32 s6, 0x700
	s_cbranch_scc1 .LBB0_276
; DEV int stage_next(int s) { return (s == 2 * GS_STAGE) ? 0 : s + GS_STAGE; }
; template <int WAIT0>
; DEV void gk_main(f32x16 (&acc)[2][2], const GTile& t, int s0) {
;     ...
;   GK_COMPUTE(stc);
;   vm_wait_bar<0>();
;   stc = stage_next(stc);
;   GK_COMPUTE(stc);
;   vm_wait_bar<0>();
	s_add_i32 s6, s3, 0
	v_add_u32_e32 v84, s6, v83
	ds_read_b128 v[64:67], v84 offset:16384
	v_add_u32_e32 v72, s6, v82
	ds_read_b128 v[68:71], v72
	ds_read_b128 v[72:75], v72 offset:4096
	s_waitcnt lgkmcnt(0)
	v_mfma_f32_32x32x16_bf16 v[48:63], v[64:67], v[68:71], v[48:63]
	v_mfma_f32_32x32x16_bf16 v[16:31], v[64:67], v[72:75], v[16:31]
	ds_read_b128 v[64:67], v84 offset:20480
	v_add_u32_e32 v84, s6, v81
	s_waitcnt lgkmcnt(0)
	v_mfma_f32_32x32x16_bf16 v[32:47], v[64:67], v[68:71], v[32:47]
	v_mfma_f32_32x32x16_bf16 v[0:15], v[64:67], v[72:75], v[0:15]
	ds_read_b128 v[64:67], v84 offset:16384
	v_add_u32_e32 v72, s6, v80
	ds_read_b128 v[68:71], v72
	ds_read_b128 v[72:75], v72 offset:4096
	s_waitcnt lgkmcnt(0)
	v_mfma_f32_32x32x16_bf16 v[48:63], v[64:67], v[68:71], v[48:63]
	v_mfma_f32_32x32x16_bf16 v[16:31], v[64:67], v[72:75], v[16:31]
	ds_read_b128 v[64:67], v84 offset:20480
	v_add_u32_e32 v84, s6, v79
	s_waitcnt lgkmcnt(0)
	v_mfma_f32_32x32x16_bf16 v[32:47], v[64:67], v[68:71], v[32:47]
	v_mfma_f32_32x32x16_bf16 v[0:15], v[64:67], v[72:75], v[0:15]
	ds_read_b128 v[64:67], v84 offset:16384
	v_add_u32_e32 v72, s6, v78
	ds_read_b128 v[68:71], v72
	ds_read_b128 v[72:75], v72 offset:4096
	s_waitcnt lgkmcnt(0)
	v_mfma_f32_32x32x16_bf16 v[48:63], v[64:67], v[68:71], v[48:63]
	v_mfma_f32_32x32x16_bf16 v[16:31], v[64:67], v[72:75], v[16:31]
	ds_read_b128 v[64:67], v84 offset:20480
	v_add_u32_e32 v84, s6, v77
	s_waitcnt lgkmcnt(0)
	v_mfma_f32_32x32x16_bf16 v[32:47], v[64:67], v[68:71], v[32:47]
	v_mfma_f32_32x32x16_bf16 v[0:15], v[64:67], v[72:75], v[0:15]
	ds_read_b128 v[64:67], v84 offset:16384
	v_add_u32_e32 v72, s6, v76
	ds_read_b128 v[68:71], v72
	ds_read_b128 v[72:75], v72 offset:4096
	s_add_i32 s6, s3, 0xc000
	s_cmp_lg_u32 s3, 0x18000
	s_cselect_b32 s3, s6, 0
	s_waitcnt lgkmcnt(0)
	v_mfma_f32_32x32x16_bf16 v[48:63], v[64:67], v[68:71], v[48:63]
	s_add_i32 s3, s3, 0
	v_add_u32_e32 v83, s3, v83
	v_add_u32_e32 v81, s3, v81
	v_add_u32_e32 v79, s3, v79
	v_add_u32_e32 v77, s3, v77
	s_mov_b64 s[6:7], 0
	v_mfma_f32_32x32x16_bf16 v[16:31], v[64:67], v[72:75], v[16:31]
	ds_read_b128 v[64:67], v84 offset:20480
	s_waitcnt vmcnt(0) lgkmcnt(0)
	s_barrier
	s_waitcnt lgkmcnt(0)
	v_mfma_f32_32x32x16_bf16 v[32:47], v[64:67], v[68:71], v[32:47]
	v_mfma_f32_32x32x16_bf16 v[0:15], v[64:67], v[72:75], v[0:15]
	ds_read_b128 v[64:67], v83 offset:16384
	v_add_u32_e32 v72, s3, v82
	ds_read_b128 v[68:71], v72
	ds_read_b128 v[72:75], v72 offset:4096
	s_waitcnt lgkmcnt(0)
	v_mfma_f32_32x32x16_bf16 v[48:63], v[64:67], v[68:71], v[48:63]
	v_mfma_f32_32x32x16_bf16 v[16:31], v[64:67], v[72:75], v[16:31]
	ds_read_b128 v[64:67], v83 offset:20480
	s_waitcnt lgkmcnt(0)
	v_mfma_f32_32x32x16_bf16 v[32:47], v[64:67], v[68:71], v[32:47]
	v_mfma_f32_32x32x16_bf16 v[0:15], v[64:67], v[72:75], v[0:15]
	ds_read_b128 v[64:67], v81 offset:16384
	v_add_u32_e32 v72, s3, v80
	ds_read_b128 v[68:71], v72
	ds_read_b128 v[72:75], v72 offset:4096
	s_waitcnt lgkmcnt(0)
	v_mfma_f32_32x32x16_bf16 v[48:63], v[64:67], v[68:71], v[48:63]
	v_mfma_f32_32x32x16_bf16 v[16:31], v[64:67], v[72:75], v[16:31]
	ds_read_b128 v[64:67], v81 offset:20480
	s_waitcnt lgkmcnt(0)
	v_mfma_f32_32x32x16_bf16 v[32:47], v[64:67], v[68:71], v[32:47]
	v_mfma_f32_32x32x16_bf16 v[0:15], v[64:67], v[72:75], v[0:15]
	ds_read_b128 v[64:67], v79 offset:16384
	v_add_u32_e32 v72, s3, v78
	ds_read_b128 v[68:71], v72
	ds_read_b128 v[72:75], v72 offset:4096
	s_waitcnt lgkmcnt(0)
	v_mfma_f32_32x32x16_bf16 v[48:63], v[64:67], v[68:71], v[48:63]
	v_mfma_f32_32x32x16_bf16 v[16:31], v[64:67], v[72:75], v[16:31]
	ds_read_b128 v[64:67], v79 offset:20480
	s_waitcnt lgkmcnt(0)
	v_mfma_f32_32x32x16_bf16 v[32:47], v[64:67], v[68:71], v[32:47]
	v_mfma_f32_32x32x16_bf16 v[0:15], v[64:67], v[72:75], v[0:15]
	ds_read_b128 v[64:67], v77 offset:16384
	v_add_u32_e32 v72, s3, v76
	ds_read_b128 v[68:71], v72
	ds_read_b128 v[72:75], v72 offset:4096
	s_waitcnt lgkmcnt(0)
	v_mfma_f32_32x32x16_bf16 v[48:63], v[64:67], v[68:71], v[48:63]
	v_mfma_f32_32x32x16_bf16 v[16:31], v[64:67], v[72:75], v[16:31]
	ds_read_b128 v[64:67], v77 offset:20480
	s_waitcnt vmcnt(0) lgkmcnt(0)
	s_barrier
	s_waitcnt lgkmcnt(0)
	v_mfma_f32_32x32x16_bf16 v[32:47], v[64:67], v[68:71], v[32:47]
	v_mfma_f32_32x32x16_bf16 v[0:15], v[64:67], v[72:75], v[0:15]

; DEV int stage_next(int s) { return (s == 2 * GS_STAGE) ? 0 : s + GS_STAGE; }
; template <int WAIT0>
; DEV void gk_main(f32x16 (&acc)[2][2], const GTile& t, int s0) {
;     ...
;   vm_wait_bar<WAIT0>();
;   int stc = s0, std_ = stage_next(stage_next(s0));
; #pragma nounroll
;   for (int kt = 0; kt < nk - 2; ++kt) {
;     GK_DMA(std_, kt + 2);
;     GK_COMPUTE(stc);
;     vm_wait_bar<6>();
;     stc = stage_next(stc); std_ = stage_next(std_);
;   }
.LBB0_280:
	s_add_i32 s12, s10, s11
	s_mov_b32 s98, s12
	s_mov_b64 s[100:101], s[6:7]
	s_add_i32 s12, s3, 0
	v_add_u32_e32 v252, s12, v82
	v_add_u32_e32 v253, s12, v83
	ds_read_b128 v[84:87], v252
	ds_read_b128 v[88:91], v252 offset:4096
	ds_read_b128 v[92:95], v253 offset:16384
	ds_read_b128 v[96:99], v253 offset:20480
	s_waitcnt lgkmcnt(0)
	v_add_u32_e32 v252, s12, v80
	v_add_u32_e32 v253, s12, v81
	ds_read_b128 v[236:239], v252
	ds_read_b128 v[240:243], v252 offset:4096
	ds_read_b128 v[244:247], v253 offset:16384
	ds_read_b128 v[248:251], v253 offset:20480
	v_mfma_f32_32x32x16_bf16 v[48:63], v[92:95], v[84:87], v[48:63]
	v_mfma_f32_32x32x16_bf16 v[16:31], v[92:95], v[88:91], v[16:31]
	s_mov_b32 m0, s98
	v_lshl_add_u64 v[254:255], v[74:75], 0, s[100:101]
	global_load_lds_dwordx4 v[254:255], off
	v_mfma_f32_32x32x16_bf16 v[32:47], v[96:99], v[84:87], v[32:47]
	v_mfma_f32_32x32x16_bf16 v[0:15], v[96:99], v[88:91], v[0:15]
	s_add_i32 m0, s98, 0x2000
	v_lshl_add_u64 v[254:255], v[72:73], 0, s[100:101]
	global_load_lds_dwordx4 v[254:255], off
	s_waitcnt lgkmcnt(0)
	v_add_u32_e32 v252, s12, v78
	v_add_u32_e32 v253, s12, v79
	ds_read_b128 v[84:87], v252
	ds_read_b128 v[88:91], v252 offset:4096
	ds_read_b128 v[92:95], v253 offset:16384
	ds_read_b128 v[96:99], v253 offset:20480
	v_mfma_f32_32x32x16_bf16 v[48:63], v[244:247], v[236:239], v[48:63]
	v_mfma_f32_32x32x16_bf16 v[16:31], v[244:247], v[240:243], v[16:31]
	s_add_i32 m0, s98, 0x4000
	v_lshl_add_u64 v[254:255], v[70:71], 0, s[100:101]
	global_load_lds_dwordx4 v[254:255], off
	v_mfma_f32_32x32x16_bf16 v[32:47], v[248:251], v[236:239], v[32:47]
	v_mfma_f32_32x32x16_bf16 v[0:15], v[248:251], v[240:243], v[0:15]
	s_add_i32 m0, s98, 0x6000
	v_lshl_add_u64 v[254:255], v[68:69], 0, s[100:101]
	global_load_lds_dwordx4 v[254:255], off
	s_waitcnt lgkmcnt(0)
	v_add_u32_e32 v252, s12, v76
	v_add_u32_e32 v253, s12, v77
	ds_read_b128 v[236:239], v252
	ds_read_b128 v[240:243], v252 offset:4096
	ds_read_b128 v[244:247], v253 offset:16384
	ds_read_b128 v[248:251], v253 offset:20480
	v_mfma_f32_32x32x16_bf16 v[48:63], v[92:95], v[84:87], v[48:63]
	v_mfma_f32_32x32x16_bf16 v[16:31], v[92:95], v[88:91], v[16:31]
	s_add_i32 m0, s98, 0x8000
	v_lshl_add_u64 v[254:255], v[66:67], 0, s[100:101]
	global_load_lds_dwordx4 v[254:255], off
	v_mfma_f32_32x32x16_bf16 v[32:47], v[96:99], v[84:87], v[32:47]
	v_mfma_f32_32x32x16_bf16 v[0:15], v[96:99], v[88:91], v[0:15]
	s_add_i32 m0, s98, 0xa000
	v_lshl_add_u64 v[254:255], v[64:65], 0, s[100:101]
	global_load_lds_dwordx4 v[254:255], off
	s_add_i32 s12, s3, 0xc000
	s_cmp_lg_u32 s3, 0x18000
	s_cselect_b32 s3, s12, 0
	s_waitcnt lgkmcnt(0)
	v_mfma_f32_32x32x16_bf16 v[48:63], v[244:247], v[236:239], v[48:63]
	s_add_i32 s12, s11, 0xc000
	s_cmp_lg_u32 s11, 0x18000
	s_waitcnt vmcnt(6) lgkmcnt(0)
	s_barrier
	s_cselect_b32 s11, s12, 0
	s_add_u32 s6, s6, 0x80
	v_mfma_f32_32x32x16_bf16 v[16:31], v[244:247], v[240:243], v[16:31]
	s_addc_u32 s7, s7, 0
	v_mfma_f32_32x32x16_bf16 v[32:47], v[248:251], v[236:239], v[32:47]
	v_mfma_f32_32x32x16_bf16 v[0:15], v[248:251], v[240:243], v[0:15]
	s_cmpk_lg_i32 s6, 0x700
	s_cbranch_scc1 .LBB0_280
; DEV int stage_next(int s) { return (s == 2 * GS_STAGE) ? 0 : s + GS_STAGE; }
; template <int WAIT0>
; DEV void gk_main(f32x16 (&acc)[2][2], const GTile& t, int s0) {
;     ...
;   GK_COMPUTE(stc);
;   vm_wait_bar<0>();
;   stc = stage_next(stc);
;   GK_COMPUTE(stc);
;   vm_wait_bar<0>();
	s_add_i32 s6, s3, 0
	v_add_u32_e32 v84, s6, v83
	ds_read_b128 v[64:67], v84 offset:16384
	v_add_u32_e32 v72, s6, v82
	ds_read_b128 v[68:71], v72
	ds_read_b128 v[72:75], v72 offset:4096
	s_waitcnt lgkmcnt(0)
	v_mfma_f32_32x32x16_bf16 v[48:63], v[64:67], v[68:71], v[48:63]
	v_mfma_f32_32x32x16_bf16 v[16:31], v[64:67], v[72:75], v[16:31]
	ds_read_b128 v[64:67], v84 offset:20480
	v_add_u32_e32 v84, s6, v81
	s_waitcnt lgkmcnt(0)
	v_mfma_f32_32x32x16_bf16 v[32:47], v[64:67], v[68:71], v[32:47]
	v_mfma_f32_32x32x16_bf16 v[0:15], v[64:67], v[72:75], v[0:15]
	ds_read_b128 v[64:67], v84 offset:16384
	v_add_u32_e32 v72, s6, v80
	ds_read_b128 v[68:71], v72
	ds_read_b128 v[72:75], v72 offset:4096
	s_waitcnt lgkmcnt(0)
	v_mfma_f32_32x32x16_bf16 v[48:63], v[64:67], v[68:71], v[48:63]
	v_mfma_f32_32x32x16_bf16 v[16:31], v[64:67], v[72:75], v[16:31]
	ds_read_b128 v[64:67], v84 offset:20480
	v_add_u32_e32 v84, s6, v79
	s_waitcnt lgkmcnt(0)
	v_mfma_f32_32x32x16_bf16 v[32:47], v[64:67], v[68:71], v[32:47]
	v_mfma_f32_32x32x16_bf16 v[0:15], v[64:67], v[72:75], v[0:15]
	ds_read_b128 v[64:67], v84 offset:16384
	v_add_u32_e32 v72, s6, v78
	ds_read_b128 v[68:71], v72
	ds_read_b128 v[72:75], v72 offset:4096
	s_waitcnt lgkmcnt(0)
	v_mfma_f32_32x32x16_bf16 v[48:63], v[64:67], v[68:71], v[48:63]
	v_mfma_f32_32x32x16_bf16 v[16:31], v[64:67], v[72:75], v[16:31]
	ds_read_b128 v[64:67], v84 offset:20480
	v_add_u32_e32 v84, s6, v77
	s_waitcnt lgkmcnt(0)
	v_mfma_f32_32x32x16_bf16 v[32:47], v[64:67], v[68:71], v[32:47]
	v_mfma_f32_32x32x16_bf16 v[0:15], v[64:67], v[72:75], v[0:15]
	ds_read_b128 v[64:67], v84 offset:16384
	v_add_u32_e32 v72, s6, v76
	ds_read_b128 v[68:71], v72
	ds_read_b128 v[72:75], v72 offset:4096
	s_add_i32 s6, s3, 0xc000
	s_cmp_lg_u32 s3, 0x18000
	s_cselect_b32 s3, s6, 0
	s_waitcnt lgkmcnt(0)
	v_mfma_f32_32x32x16_bf16 v[48:63], v[64:67], v[68:71], v[48:63]
	s_add_i32 s3, s3, 0
	v_add_u32_e32 v83, s3, v83
	v_add_u32_e32 v81, s3, v81
	v_add_u32_e32 v79, s3, v79
	v_add_u32_e32 v77, s3, v77
	v_mfma_f32_32x32x16_bf16 v[16:31], v[64:67], v[72:75], v[16:31]
	ds_read_b128 v[64:67], v84 offset:20480
	s_waitcnt vmcnt(0) lgkmcnt(0)
	s_barrier
	s_waitcnt lgkmcnt(0)
	v_mfma_f32_32x32x16_bf16 v[32:47], v[64:67], v[68:71], v[32:47]
	v_mfma_f32_32x32x16_bf16 v[0:15], v[64:67], v[72:75], v[0:15]
	ds_read_b128 v[64:67], v83 offset:16384
	v_add_u32_e32 v72, s3, v82
	ds_read_b128 v[68:71], v72
	ds_read_b128 v[72:75], v72 offset:4096
	s_waitcnt lgkmcnt(0)
	v_mfma_f32_32x32x16_bf16 v[48:63], v[64:67], v[68:71], v[48:63]
	v_mfma_f32_32x32x16_bf16 v[16:31], v[64:67], v[72:75], v[16:31]
	ds_read_b128 v[64:67], v83 offset:20480
	s_waitcnt lgkmcnt(0)
	v_mfma_f32_32x32x16_bf16 v[32:47], v[64:67], v[68:71], v[32:47]
	v_mfma_f32_32x32x16_bf16 v[0:15], v[64:67], v[72:75], v[0:15]
	ds_read_b128 v[64:67], v81 offset:16384
	v_add_u32_e32 v72, s3, v80
	ds_read_b128 v[68:71], v72
	ds_read_b128 v[72:75], v72 offset:4096
	s_waitcnt lgkmcnt(0)
	v_mfma_f32_32x32x16_bf16 v[48:63], v[64:67], v[68:71], v[48:63]
	v_mfma_f32_32x32x16_bf16 v[16:31], v[64:67], v[72:75], v[16:31]
	ds_read_b128 v[64:67], v81 offset:20480
	s_waitcnt lgkmcnt(0)
	v_mfma_f32_32x32x16_bf16 v[32:47], v[64:67], v[68:71], v[32:47]
	v_mfma_f32_32x32x16_bf16 v[0:15], v[64:67], v[72:75], v[0:15]
	ds_read_b128 v[64:67], v79 offset:16384
	v_add_u32_e32 v72, s3, v78
	ds_read_b128 v[68:71], v72
	ds_read_b128 v[72:75], v72 offset:4096
	s_waitcnt lgkmcnt(0)
	v_mfma_f32_32x32x16_bf16 v[48:63], v[64:67], v[68:71], v[48:63]
	v_mfma_f32_32x32x16_bf16 v[16:31], v[64:67], v[72:75], v[16:31]
	ds_read_b128 v[64:67], v79 offset:20480
	s_waitcnt lgkmcnt(0)
	v_mfma_f32_32x32x16_bf16 v[32:47], v[64:67], v[68:71], v[32:47]
	v_mfma_f32_32x32x16_bf16 v[0:15], v[64:67], v[72:75], v[0:15]
	ds_read_b128 v[64:67], v77 offset:16384
	v_add_u32_e32 v72, s3, v76
	ds_read_b128 v[68:71], v72
	ds_read_b128 v[72:75], v72 offset:4096
	s_waitcnt lgkmcnt(0)
	v_mfma_f32_32x32x16_bf16 v[48:63], v[64:67], v[68:71], v[48:63]
	v_mfma_f32_32x32x16_bf16 v[16:31], v[64:67], v[72:75], v[16:31]
	ds_read_b128 v[64:67], v77 offset:20480
	s_waitcnt vmcnt(0) lgkmcnt(0)
	s_barrier
	s_waitcnt lgkmcnt(0)
	v_mfma_f32_32x32x16_bf16 v[32:47], v[64:67], v[68:71], v[32:47]
	v_mfma_f32_32x32x16_bf16 v[0:15], v[64:67], v[72:75], v[0:15]

; DEV int stage_next(int s) { return (s == 2 * GS_STAGE) ? 0 : s + GS_STAGE; }
; template <int WAIT0>
; DEV void gk_main(f32x16 (&acc)[2][2], const GTile& t, int s0) {
;     ...
;   vm_wait_bar<WAIT0>();
;   int stc = s0, std_ = stage_next(stage_next(s0));
; #pragma nounroll
;   for (int kt = 0; kt < nk - 2; ++kt) {
;     GK_DMA(std_, kt + 2);
;     GK_COMPUTE(stc);
;     vm_wait_bar<6>();
;     stc = stage_next(stc); std_ = stage_next(std_);
;   }
.LBB0_286:
	s_add_i32 s12, s10, s11
	s_mov_b32 s98, s12
	s_mov_b64 s[100:101], s[6:7]
	s_add_i32 s12, s3, 0
	v_add_u32_e32 v252, s12, v82
	v_add_u32_e32 v253, s12, v83
	ds_read_b128 v[84:87], v252
	ds_read_b128 v[88:91], v252 offset:4096
	ds_read_b128 v[92:95], v253 offset:16384
	ds_read_b128 v[96:99], v253 offset:20480
	s_waitcnt lgkmcnt(0)
	v_add_u32_e32 v252, s12, v80
	v_add_u32_e32 v253, s12, v81
	ds_read_b128 v[236:239], v252
	ds_read_b128 v[240:243], v252 offset:4096
	ds_read_b128 v[244:247], v253 offset:16384
	ds_read_b128 v[248:251], v253 offset:20480
	v_mfma_f32_32x32x16_bf16 v[48:63], v[92:95], v[84:87], v[48:63]
	v_mfma_f32_32x32x16_bf16 v[16:31], v[92:95], v[88:91], v[16:31]
	s_mov_b32 m0, s98
	v_lshl_add_u64 v[254:255], v[74:75], 0, s[100:101]
	global_load_lds_dwordx4 v[254:255], off
	v_mfma_f32_32x32x16_bf16 v[32:47], v[96:99], v[84:87], v[32:47]
	v_mfma_f32_32x32x16_bf16 v[0:15], v[96:99], v[88:91], v[0:15]
	s_add_i32 m0, s98, 0x2000
	v_lshl_add_u64 v[254:255], v[72:73], 0, s[100:101]
	global_load_lds_dwordx4 v[254:255], off
	s_waitcnt lgkmcnt(0)
	v_add_u32_e32 v252, s12, v78
	v_add_u32_e32 v253, s12, v79
	ds_read_b128 v[84:87], v252
	ds_read_b128 v[88:91], v252 offset:4096
	ds_read_b128 v[92:95], v253 offset:16384
	ds_read_b128 v[96:99], v253 offset:20480
	v_mfma_f32_32x32x16_bf16 v[48:63], v[244:247], v[236:239], v[48:63]
	v_mfma_f32_32x32x16_bf16 v[16:31], v[244:247], v[240:243], v[16:31]
	s_add_i32 m0, s98, 0x4000
	v_lshl_add_u64 v[254:255], v[70:71], 0, s[100:101]
	global_load_lds_dwordx4 v[254:255], off
	v_mfma_f32_32x32x16_bf16 v[32:47], v[248:251], v[236:239], v[32:47]
	v_mfma_f32_32x32x16_bf16 v[0:15], v[248:251], v[240:243], v[0:15]
	s_add_i32 m0, s98, 0x6000
	v_lshl_add_u64 v[254:255], v[68:69], 0, s[100:101]
	global_load_lds_dwordx4 v[254:255], off
	s_waitcnt lgkmcnt(0)
	v_add_u32_e32 v252, s12, v76
	v_add_u32_e32 v253, s12, v77
	ds_read_b128 v[236:239], v252
	ds_read_b128 v[240:243], v252 offset:4096
	ds_read_b128 v[244:247], v253 offset:16384
	ds_read_b128 v[248:251], v253 offset:20480
	v_mfma_f32_32x32x16_bf16 v[48:63], v[92:95], v[84:87], v[48:63]
	v_mfma_f32_32x32x16_bf16 v[16:31], v[92:95], v[88:91], v[16:31]
	s_add_i32 m0, s98, 0x8000
	v_lshl_add_u64 v[254:255], v[66:67], 0, s[100:101]
	global_load_lds_dwordx4 v[254:255], off
	v_mfma_f32_32x32x16_bf16 v[32:47], v[96:99], v[84:87], v[32:47]
	v_mfma_f32_32x32x16_bf16 v[0:15], v[96:99], v[88:91], v[0:15]
	s_add_i32 m0, s98, 0xa000
	v_lshl_add_u64 v[254:255], v[64:65], 0, s[100:101]
	global_load_lds_dwordx4 v[254:255], off
	s_add_i32 s12, s3, 0xc000
	s_cmp_lg_u32 s3, 0x18000
	s_cselect_b32 s3, s12, 0
	s_waitcnt lgkmcnt(0)
	v_mfma_f32_32x32x16_bf16 v[48:63], v[244:247], v[236:239], v[48:63]
	s_add_i32 s12, s11, 0xc000
	s_cmp_lg_u32 s11, 0x18000
	s_waitcnt vmcnt(6) lgkmcnt(0)
	s_barrier
	s_cselect_b32 s11, s12, 0
	s_add_u32 s6, s6, 0x80
	v_mfma_f32_32x32x16_bf16 v[16:31], v[244:247], v[240:243], v[16:31]
	s_addc_u32 s7, s7, 0
	v_mfma_f32_32x32x16_bf16 v[32:47], v[248:251], v[236:239], v[32:47]
	v_mfma_f32_32x32x16_bf16 v[0:15], v[248:251], v[240:243], v[0:15]
	s_cmpk_lg_i32 s6, 0x700
	s_cbranch_scc1 .LBB0_286
; DEV int stage_next(int s) { return (s == 2 * GS_STAGE) ? 0 : s + GS_STAGE; }
; template <int WAIT0>
; DEV void gk_main(f32x16 (&acc)[2][2], const GTile& t, int s0) {
;     ...
;   GK_COMPUTE(stc);
;   vm_wait_bar<0>();
;   stc = stage_next(stc);
;   GK_COMPUTE(stc);
;   vm_wait_bar<0>();
; template <int WAIT_E, int WAIT_O, class TileFn, class EpiFn>
; DEV void gemm_seq(int ntiles, TileFn tf, EpiFn epi) {
;     ...
;   for (int i = 0; i < ntiles; ++i) {
;     f32x16 acc[2][2]; acc_zero(acc);
;     if (i == 0) gk_main<6>(acc, cur, s0);
;     else if (i & 1) gk_main<WAIT_O>(acc, cur, s0);
;     else gk_main<WAIT_E>(acc, cur, s0);
;     const int sn = stage_next(s0);
;     if (i + 1 < ntiles) { cur = tf(i + 1); gk_issue2(cur, sn); }
;     epi(i, acc, s0);
;     s0 = sn;
;   }
	s_add_i32 s6, s3, 0
	v_add_u32_e32 v84, s6, v83
	ds_read_b128 v[64:67], v84 offset:16384
	v_add_u32_e32 v72, s6, v82
	ds_read_b128 v[68:71], v72
	ds_read_b128 v[72:75], v72 offset:4096
	s_waitcnt lgkmcnt(0)
	v_mfma_f32_32x32x16_bf16 v[48:63], v[64:67], v[68:71], v[48:63]
	v_mfma_f32_32x32x16_bf16 v[16:31], v[64:67], v[72:75], v[16:31]
	ds_read_b128 v[64:67], v84 offset:20480
	v_add_u32_e32 v84, s6, v81
	s_waitcnt lgkmcnt(0)
	v_mfma_f32_32x32x16_bf16 v[32:47], v[64:67], v[68:71], v[32:47]
	v_mfma_f32_32x32x16_bf16 v[0:15], v[64:67], v[72:75], v[0:15]
	ds_read_b128 v[64:67], v84 offset:16384
	v_add_u32_e32 v72, s6, v80
	ds_read_b128 v[68:71], v72
	ds_read_b128 v[72:75], v72 offset:4096
	s_waitcnt lgkmcnt(0)
	v_mfma_f32_32x32x16_bf16 v[48:63], v[64:67], v[68:71], v[48:63]
	v_mfma_f32_32x32x16_bf16 v[16:31], v[64:67], v[72:75], v[16:31]
	ds_read_b128 v[64:67], v84 offset:20480
	v_add_u32_e32 v84, s6, v79
	s_waitcnt lgkmcnt(0)
	v_mfma_f32_32x32x16_bf16 v[32:47], v[64:67], v[68:71], v[32:47]
	v_mfma_f32_32x32x16_bf16 v[0:15], v[64:67], v[72:75], v[0:15]
	ds_read_b128 v[64:67], v84 offset:16384
	v_add_u32_e32 v72, s6, v78
	ds_read_b128 v[68:71], v72
	ds_read_b128 v[72:75], v72 offset:4096
	s_waitcnt lgkmcnt(0)
	v_mfma_f32_32x32x16_bf16 v[48:63], v[64:67], v[68:71], v[48:63]
	v_mfma_f32_32x32x16_bf16 v[16:31], v[64:67], v[72:75], v[16:31]
	ds_read_b128 v[64:67], v84 offset:20480
	v_add_u32_e32 v84, s6, v77
	s_waitcnt lgkmcnt(0)
	v_mfma_f32_32x32x16_bf16 v[32:47], v[64:67], v[68:71], v[32:47]
	v_mfma_f32_32x32x16_bf16 v[0:15], v[64:67], v[72:75], v[0:15]
	ds_read_b128 v[64:67], v84 offset:16384
	v_add_u32_e32 v72, s6, v76
	ds_read_b128 v[68:71], v72
	ds_read_b128 v[72:75], v72 offset:4096
	s_add_i32 s6, s3, 0xc000
	s_cmp_lg_u32 s3, 0x18000
	s_cselect_b32 s3, s6, 0
	s_waitcnt lgkmcnt(0)
	v_mfma_f32_32x32x16_bf16 v[48:63], v[64:67], v[68:71], v[48:63]
	s_add_i32 s3, s3, 0
	v_add_u32_e32 v83, s3, v83
	v_add_u32_e32 v81, s3, v81
	v_add_u32_e32 v79, s3, v79
	v_add_u32_e32 v77, s3, v77
	v_mfma_f32_32x32x16_bf16 v[16:31], v[64:67], v[72:75], v[16:31]
	ds_read_b128 v[64:67], v84 offset:20480
	s_waitcnt vmcnt(0) lgkmcnt(0)
	s_barrier
	s_waitcnt lgkmcnt(0)
	v_mfma_f32_32x32x16_bf16 v[32:47], v[64:67], v[68:71], v[32:47]
	v_mfma_f32_32x32x16_bf16 v[0:15], v[64:67], v[72:75], v[0:15]
	ds_read_b128 v[64:67], v83 offset:16384
	v_add_u32_e32 v72, s3, v82
	ds_read_b128 v[68:71], v72
	ds_read_b128 v[72:75], v72 offset:4096
	s_waitcnt lgkmcnt(0)
	v_mfma_f32_32x32x16_bf16 v[48:63], v[64:67], v[68:71], v[48:63]
	v_mfma_f32_32x32x16_bf16 v[16:31], v[64:67], v[72:75], v[16:31]
	ds_read_b128 v[64:67], v83 offset:20480
	s_waitcnt lgkmcnt(0)
	v_mfma_f32_32x32x16_bf16 v[32:47], v[64:67], v[68:71], v[32:47]
	v_mfma_f32_32x32x16_bf16 v[0:15], v[64:67], v[72:75], v[0:15]
	ds_read_b128 v[64:67], v81 offset:16384
	v_add_u32_e32 v72, s3, v80
	ds_read_b128 v[68:71], v72
	ds_read_b128 v[72:75], v72 offset:4096
	s_waitcnt lgkmcnt(0)
	v_mfma_f32_32x32x16_bf16 v[48:63], v[64:67], v[68:71], v[48:63]
	v_mfma_f32_32x32x16_bf16 v[16:31], v[64:67], v[72:75], v[16:31]
	ds_read_b128 v[64:67], v81 offset:20480
	s_waitcnt lgkmcnt(0)
	v_mfma_f32_32x32x16_bf16 v[32:47], v[64:67], v[68:71], v[32:47]
	v_mfma_f32_32x32x16_bf16 v[0:15], v[64:67], v[72:75], v[0:15]
	ds_read_b128 v[64:67], v79 offset:16384
	v_add_u32_e32 v72, s3, v78
	ds_read_b128 v[68:71], v72
	ds_read_b128 v[72:75], v72 offset:4096
	s_waitcnt lgkmcnt(0)
	v_mfma_f32_32x32x16_bf16 v[48:63], v[64:67], v[68:71], v[48:63]
	v_mfma_f32_32x32x16_bf16 v[16:31], v[64:67], v[72:75], v[16:31]
	ds_read_b128 v[64:67], v79 offset:20480
	s_waitcnt lgkmcnt(0)
	v_mfma_f32_32x32x16_bf16 v[32:47], v[64:67], v[68:71], v[32:47]
	v_mfma_f32_32x32x16_bf16 v[0:15], v[64:67], v[72:75], v[0:15]
	ds_read_b128 v[64:67], v77 offset:16384
	v_add_u32_e32 v72, s3, v76
	ds_read_b128 v[68:71], v72
	ds_read_b128 v[72:75], v72 offset:4096
	s_waitcnt lgkmcnt(0)
	v_mfma_f32_32x32x16_bf16 v[48:63], v[64:67], v[68:71], v[48:63]
	v_mfma_f32_32x32x16_bf16 v[16:31], v[64:67], v[72:75], v[16:31]
	ds_read_b128 v[64:67], v77 offset:20480
	s_waitcnt vmcnt(0) lgkmcnt(0)
	s_barrier
	s_waitcnt lgkmcnt(0)
	v_mfma_f32_32x32x16_bf16 v[32:47], v[64:67], v[68:71], v[32:47]
	v_mfma_f32_32x32x16_bf16 v[0:15], v[64:67], v[72:75], v[0:15]
	s_add_i32 s3, s2, 1
	s_cmp_eq_u32 s2, 3
	s_cbranch_scc1 .LBB0_272

; DEV int stage_next(int s) { return (s == 2 * GS_STAGE) ? 0 : s + GS_STAGE; }
; template <int WAIT0>
; DEV void gk_main(f32x16 (&acc)[2][2], const GTile& t, int s0) {
;     ...
;   vm_wait_bar<WAIT0>();
;   int stc = s0, std_ = stage_next(stage_next(s0));
; #pragma nounroll
;   for (int kt = 0; kt < nk - 2; ++kt) {
;     GK_DMA(std_, kt + 2);
;     GK_COMPUTE(stc);
;     vm_wait_bar<6>();
;     stc = stage_next(stc); std_ = stage_next(std_);
;   }
.LBB0_298:
	s_add_i32 s16, s1, s3
	s_mov_b32 s98, s16
	s_mov_b64 s[100:101], s[10:11]
	s_add_i32 s16, s0, 0
	v_add_u32_e32 v87, s16, v85
	ds_read_b128 v[88:91], v87
	ds_read_b128 v[92:95], v87 offset:4096
	v_add_u32_e32 v87, s16, v86
	ds_read_b128 v[96:99], v87 offset:16384
	ds_read_b128 v[100:103], v87 offset:20480
	s_waitcnt lgkmcnt(0)
	v_add_u32_e32 v87, s16, v83
	ds_read_b128 v[236:239], v87
	ds_read_b128 v[240:243], v87 offset:4096
	v_add_u32_e32 v87, s16, v84
	ds_read_b128 v[244:247], v87 offset:16384
	ds_read_b128 v[248:251], v87 offset:20480
	v_mfma_f32_32x32x16_bf16 v[48:63], v[96:99], v[88:91], v[48:63]
	v_mfma_f32_32x32x16_bf16 v[32:47], v[96:99], v[92:95], v[32:47]
	s_mov_b32 m0, s98
	v_lshl_add_u64 v[254:255], v[76:77], 0, s[100:101]
	global_load_lds_dwordx4 v[254:255], off
	v_mfma_f32_32x32x16_bf16 v[16:31], v[100:103], v[88:91], v[16:31]
	v_mfma_f32_32x32x16_bf16 v[0:15], v[100:103], v[92:95], v[0:15]
	s_add_i32 m0, s98, 0x2000
	v_lshl_add_u64 v[254:255], v[74:75], 0, s[100:101]
	global_load_lds_dwordx4 v[254:255], off
	v_add_u32_e32 v87, s16, v81
	s_waitcnt lgkmcnt(0)
	ds_read_b128 v[88:91], v87
	ds_read_b128 v[92:95], v87 offset:4096
	v_add_u32_e32 v87, s16, v82
	ds_read_b128 v[96:99], v87 offset:16384
	ds_read_b128 v[100:103], v87 offset:20480
	v_mfma_f32_32x32x16_bf16 v[48:63], v[244:247], v[236:239], v[48:63]
	v_mfma_f32_32x32x16_bf16 v[32:47], v[244:247], v[240:243], v[32:47]
	s_add_i32 m0, s98, 0x4000
	v_lshl_add_u64 v[254:255], v[72:73], 0, s[100:101]
	global_load_lds_dwordx4 v[254:255], off
	v_mfma_f32_32x32x16_bf16 v[16:31], v[248:251], v[236:239], v[16:31]
	v_mfma_f32_32x32x16_bf16 v[0:15], v[248:251], v[240:243], v[0:15]
	s_add_i32 m0, s98, 0x6000
	v_lshl_add_u64 v[254:255], v[70:71], 0, s[100:101]
	global_load_lds_dwordx4 v[254:255], off
	v_add_u32_e32 v87, s16, v79
	s_waitcnt lgkmcnt(0)
	ds_read_b128 v[236:239], v87
	ds_read_b128 v[240:243], v87 offset:4096
	v_add_u32_e32 v87, s16, v80
	ds_read_b128 v[244:247], v87 offset:16384
	ds_read_b128 v[248:251], v87 offset:20480
	v_mfma_f32_32x32x16_bf16 v[48:63], v[96:99], v[88:91], v[48:63]
	v_mfma_f32_32x32x16_bf16 v[32:47], v[96:99], v[92:95], v[32:47]
	s_add_i32 m0, s98, 0x8000
	v_lshl_add_u64 v[254:255], v[68:69], 0, s[100:101]
	global_load_lds_dwordx4 v[254:255], off
	v_mfma_f32_32x32x16_bf16 v[16:31], v[100:103], v[88:91], v[16:31]
	v_mfma_f32_32x32x16_bf16 v[0:15], v[100:103], v[92:95], v[0:15]
	s_add_i32 m0, s98, 0xa000
	v_lshl_add_u64 v[254:255], v[66:67], 0, s[100:101]
	global_load_lds_dwordx4 v[254:255], off
	s_add_i32 s16, s0, 0xc000
	s_cmp_lg_u32 s0, 0x18000
	s_cselect_b32 s0, s16, 0
	s_add_i32 s16, s3, 0xc000
	s_waitcnt lgkmcnt(0)
	v_mfma_f32_32x32x16_bf16 v[48:63], v[244:247], v[236:239], v[48:63]
	s_cmp_lg_u32 s3, 0x18000
	s_waitcnt vmcnt(6) lgkmcnt(0)
	s_barrier
	s_cselect_b32 s3, s16, 0
	s_add_u32 s10, s10, 0x80
	s_addc_u32 s11, s11, 0
	v_mfma_f32_32x32x16_bf16 v[32:47], v[244:247], v[240:243], v[32:47]
	v_mfma_f32_32x32x16_bf16 v[16:31], v[248:251], v[236:239], v[16:31]
	v_mfma_f32_32x32x16_bf16 v[0:15], v[248:251], v[240:243], v[0:15]
	s_cmpk_lg_i32 s10, 0x700
	s_cbranch_scc1 .LBB0_298
; DEV int stage_next(int s) { return (s == 2 * GS_STAGE) ? 0 : s + GS_STAGE; }
; template <int WAIT0>
; DEV void gk_main(f32x16 (&acc)[2][2], const GTile& t, int s0) {
;     ...
;   GK_COMPUTE(stc);
;   vm_wait_bar<0>();
;   stc = stage_next(stc);
;   GK_COMPUTE(stc);
;   vm_wait_bar<0>();
	s_add_i32 s1, s0, 0
	v_add_u32_e32 v87, s1, v86
	ds_read_b128 v[66:69], v87 offset:16384
	v_add_u32_e32 v74, s1, v85
	ds_read_b128 v[70:73], v74
	ds_read_b128 v[74:77], v74 offset:4096
	s_waitcnt lgkmcnt(0)
	v_mfma_f32_32x32x16_bf16 v[48:63], v[66:69], v[70:73], v[48:63]
	v_mfma_f32_32x32x16_bf16 v[32:47], v[66:69], v[74:77], v[32:47]
	ds_read_b128 v[66:69], v87 offset:20480
	v_add_u32_e32 v87, s1, v84
	s_waitcnt lgkmcnt(0)
	v_mfma_f32_32x32x16_bf16 v[16:31], v[66:69], v[70:73], v[16:31]
	v_mfma_f32_32x32x16_bf16 v[0:15], v[66:69], v[74:77], v[0:15]
	ds_read_b128 v[66:69], v87 offset:16384
	v_add_u32_e32 v74, s1, v83
	ds_read_b128 v[70:73], v74
	ds_read_b128 v[74:77], v74 offset:4096
	s_waitcnt lgkmcnt(0)
	v_mfma_f32_32x32x16_bf16 v[48:63], v[66:69], v[70:73], v[48:63]
	v_mfma_f32_32x32x16_bf16 v[32:47], v[66:69], v[74:77], v[32:47]
	ds_read_b128 v[66:69], v87 offset:20480
	v_add_u32_e32 v87, s1, v82
	s_waitcnt lgkmcnt(0)
	v_mfma_f32_32x32x16_bf16 v[16:31], v[66:69], v[70:73], v[16:31]
	v_mfma_f32_32x32x16_bf16 v[0:15], v[66:69], v[74:77], v[0:15]
	ds_read_b128 v[66:69], v87 offset:16384
	v_add_u32_e32 v74, s1, v81
	ds_read_b128 v[70:73], v74
	ds_read_b128 v[74:77], v74 offset:4096
	s_waitcnt lgkmcnt(0)
	v_mfma_f32_32x32x16_bf16 v[48:63], v[66:69], v[70:73], v[48:63]
	v_mfma_f32_32x32x16_bf16 v[32:47], v[66:69], v[74:77], v[32:47]
	ds_read_b128 v[66:69], v87 offset:20480
	v_add_u32_e32 v87, s1, v80
	s_waitcnt lgkmcnt(0)
	v_mfma_f32_32x32x16_bf16 v[16:31], v[66:69], v[70:73], v[16:31]
	v_mfma_f32_32x32x16_bf16 v[0:15], v[66:69], v[74:77], v[0:15]
	ds_read_b128 v[66:69], v87 offset:16384
	v_add_u32_e32 v74, s1, v79
	ds_read_b128 v[70:73], v74
	ds_read_b128 v[74:77], v74 offset:4096
	s_add_i32 s1, s0, 0xc000
	s_cmp_lg_u32 s0, 0x18000
	s_cselect_b32 s0, s1, 0
	s_waitcnt lgkmcnt(0)
	v_mfma_f32_32x32x16_bf16 v[48:63], v[66:69], v[70:73], v[48:63]
	s_add_i32 s0, s0, 0
	v_add_u32_e32 v86, s0, v86
	v_add_u32_e32 v84, s0, v84
	v_add_u32_e32 v82, s0, v82
	v_add_u32_e32 v80, s0, v80
	v_mfma_f32_32x32x16_bf16 v[32:47], v[66:69], v[74:77], v[32:47]
	ds_read_b128 v[66:69], v87 offset:20480
	s_waitcnt vmcnt(0) lgkmcnt(0)
	s_barrier
	s_waitcnt lgkmcnt(0)
	v_mfma_f32_32x32x16_bf16 v[16:31], v[66:69], v[70:73], v[16:31]
	v_mfma_f32_32x32x16_bf16 v[0:15], v[66:69], v[74:77], v[0:15]
	ds_read_b128 v[66:69], v86 offset:16384
	v_add_u32_e32 v74, s0, v85
	ds_read_b128 v[70:73], v74
	ds_read_b128 v[74:77], v74 offset:4096
	s_waitcnt lgkmcnt(0)
	v_mfma_f32_32x32x16_bf16 v[48:63], v[66:69], v[70:73], v[48:63]
	v_mfma_f32_32x32x16_bf16 v[32:47], v[66:69], v[74:77], v[32:47]
	ds_read_b128 v[66:69], v86 offset:20480
	s_waitcnt lgkmcnt(0)
	v_mfma_f32_32x32x16_bf16 v[16:31], v[66:69], v[70:73], v[16:31]
	v_mfma_f32_32x32x16_bf16 v[0:15], v[66:69], v[74:77], v[0:15]
	ds_read_b128 v[66:69], v84 offset:16384
	v_add_u32_e32 v74, s0, v83
	ds_read_b128 v[70:73], v74
	ds_read_b128 v[74:77], v74 offset:4096
	s_waitcnt lgkmcnt(0)
	v_mfma_f32_32x32x16_bf16 v[48:63], v[66:69], v[70:73], v[48:63]
	v_mfma_f32_32x32x16_bf16 v[32:47], v[66:69], v[74:77], v[32:47]
	ds_read_b128 v[66:69], v84 offset:20480
	s_waitcnt lgkmcnt(0)
	v_mfma_f32_32x32x16_bf16 v[16:31], v[66:69], v[70:73], v[16:31]
	v_mfma_f32_32x32x16_bf16 v[0:15], v[66:69], v[74:77], v[0:15]
	ds_read_b128 v[66:69], v82 offset:16384
	v_add_u32_e32 v74, s0, v81
	ds_read_b128 v[70:73], v74
	ds_read_b128 v[74:77], v74 offset:4096
	s_waitcnt lgkmcnt(0)
	v_mfma_f32_32x32x16_bf16 v[48:63], v[66:69], v[70:73], v[48:63]
	v_mfma_f32_32x32x16_bf16 v[32:47], v[66:69], v[74:77], v[32:47]
	ds_read_b128 v[66:69], v82 offset:20480
	s_waitcnt lgkmcnt(0)
	v_mfma_f32_32x32x16_bf16 v[16:31], v[66:69], v[70:73], v[16:31]
	v_mfma_f32_32x32x16_bf16 v[0:15], v[66:69], v[74:77], v[0:15]
	ds_read_b128 v[66:69], v80 offset:16384
	v_add_u32_e32 v74, s0, v79
	ds_read_b128 v[70:73], v74
	ds_read_b128 v[74:77], v74 offset:4096
	s_mov_b64 s[0:1], 0
	s_waitcnt lgkmcnt(0)
	v_mfma_f32_32x32x16_bf16 v[48:63], v[66:69], v[70:73], v[48:63]
	v_mfma_f32_32x32x16_bf16 v[32:47], v[66:69], v[74:77], v[32:47]
	ds_read_b128 v[66:69], v80 offset:20480
	s_waitcnt vmcnt(0) lgkmcnt(0)
	s_barrier
	s_waitcnt lgkmcnt(0)
	v_mfma_f32_32x32x16_bf16 v[16:31], v[66:69], v[70:73], v[16:31]
	v_mfma_f32_32x32x16_bf16 v[0:15], v[66:69], v[74:77], v[0:15]

; DEV int stage_next(int s) { return (s == 2 * GS_STAGE) ? 0 : s + GS_STAGE; }
; template <int WAIT0>
; DEV void gk_main(f32x16 (&acc)[2][2], const GTile& t, int s0) {
;     ...
;   vm_wait_bar<WAIT0>();
;   int stc = s0, std_ = stage_next(stage_next(s0));
; #pragma nounroll
;   for (int kt = 0; kt < nk - 2; ++kt) {
;     GK_DMA(std_, kt + 2);
;     GK_COMPUTE(stc);
;     vm_wait_bar<6>();
;     stc = stage_next(stc); std_ = stage_next(std_);
;   }
.LBB0_302:
	s_add_i32 s16, s1, s3
	s_mov_b32 s98, s16
	s_mov_b64 s[100:101], s[10:11]
	s_add_i32 s16, s0, 0
	v_add_u32_e32 v87, s16, v85
	ds_read_b128 v[88:91], v87
	ds_read_b128 v[92:95], v87 offset:4096
	v_add_u32_e32 v87, s16, v86
	ds_read_b128 v[96:99], v87 offset:16384
	ds_read_b128 v[100:103], v87 offset:20480
	s_waitcnt lgkmcnt(0)
	v_add_u32_e32 v87, s16, v83
	ds_read_b128 v[236:239], v87
	ds_read_b128 v[240:243], v87 offset:4096
	v_add_u32_e32 v87, s16, v84
	ds_read_b128 v[244:247], v87 offset:16384
	ds_read_b128 v[248:251], v87 offset:20480
	v_mfma_f32_32x32x16_bf16 v[48:63], v[96:99], v[88:91], v[48:63]
	v_mfma_f32_32x32x16_bf16 v[32:47], v[96:99], v[92:95], v[32:47]
	s_mov_b32 m0, s98
	v_lshl_add_u64 v[254:255], v[76:77], 0, s[100:101]
	global_load_lds_dwordx4 v[254:255], off
	v_mfma_f32_32x32x16_bf16 v[16:31], v[100:103], v[88:91], v[16:31]
	v_mfma_f32_32x32x16_bf16 v[0:15], v[100:103], v[92:95], v[0:15]
	s_add_i32 m0, s98, 0x2000
	v_lshl_add_u64 v[254:255], v[74:75], 0, s[100:101]
	global_load_lds_dwordx4 v[254:255], off
	v_add_u32_e32 v87, s16, v81
	s_waitcnt lgkmcnt(0)
	ds_read_b128 v[88:91], v87
	ds_read_b128 v[92:95], v87 offset:4096
	v_add_u32_e32 v87, s16, v82
	ds_read_b128 v[96:99], v87 offset:16384
	ds_read_b128 v[100:103], v87 offset:20480
	v_mfma_f32_32x32x16_bf16 v[48:63], v[244:247], v[236:239], v[48:63]
	v_mfma_f32_32x32x16_bf16 v[32:47], v[244:247], v[240:243], v[32:47]
	s_add_i32 m0, s98, 0x4000
	v_lshl_add_u64 v[254:255], v[72:73], 0, s[100:101]
	global_load_lds_dwordx4 v[254:255], off
	v_mfma_f32_32x32x16_bf16 v[16:31], v[248:251], v[236:239], v[16:31]
	v_mfma_f32_32x32x16_bf16 v[0:15], v[248:251], v[240:243], v[0:15]
	s_add_i32 m0, s98, 0x6000
	v_lshl_add_u64 v[254:255], v[70:71], 0, s[100:101]
	global_load_lds_dwordx4 v[254:255], off
	v_add_u32_e32 v87, s16, v79
	s_waitcnt lgkmcnt(0)
	ds_read_b128 v[236:239], v87
	ds_read_b128 v[240:243], v87 offset:4096
	v_add_u32_e32 v87, s16, v80
	ds_read_b128 v[244:247], v87 offset:16384
	ds_read_b128 v[248:251], v87 offset:20480
	v_mfma_f32_32x32x16_bf16 v[48:63], v[96:99], v[88:91], v[48:63]
	v_mfma_f32_32x32x16_bf16 v[32:47], v[96:99], v[92:95], v[32:47]
	s_add_i32 m0, s98, 0x8000
	v_lshl_add_u64 v[254:255], v[68:69], 0, s[100:101]
	global_load_lds_dwordx4 v[254:255], off
	v_mfma_f32_32x32x16_bf16 v[16:31], v[100:103], v[88:91], v[16:31]
	v_mfma_f32_32x32x16_bf16 v[0:15], v[100:103], v[92:95], v[0:15]
	s_add_i32 m0, s98, 0xa000
	v_lshl_add_u64 v[254:255], v[66:67], 0, s[100:101]
	global_load_lds_dwordx4 v[254:255], off
	s_add_i32 s16, s0, 0xc000
	s_cmp_lg_u32 s0, 0x18000
	s_cselect_b32 s0, s16, 0
	s_add_i32 s16, s3, 0xc000
	s_waitcnt lgkmcnt(0)
	v_mfma_f32_32x32x16_bf16 v[48:63], v[244:247], v[236:239], v[48:63]
	s_cmp_lg_u32 s3, 0x18000
	s_waitcnt vmcnt(6) lgkmcnt(0)
	s_barrier
	s_cselect_b32 s3, s16, 0
	s_add_u32 s10, s10, 0x80
	s_addc_u32 s11, s11, 0
	v_mfma_f32_32x32x16_bf16 v[32:47], v[244:247], v[240:243], v[32:47]
	v_mfma_f32_32x32x16_bf16 v[16:31], v[248:251], v[236:239], v[16:31]
	v_mfma_f32_32x32x16_bf16 v[0:15], v[248:251], v[240:243], v[0:15]
	s_cmpk_lg_i32 s10, 0x700
	s_cbranch_scc1 .LBB0_302
; DEV int stage_next(int s) { return (s == 2 * GS_STAGE) ? 0 : s + GS_STAGE; }
; template <int WAIT0>
; DEV void gk_main(f32x16 (&acc)[2][2], const GTile& t, int s0) {
;     ...
;   GK_COMPUTE(stc);
;   vm_wait_bar<0>();
;   stc = stage_next(stc);
;   GK_COMPUTE(stc);
;   vm_wait_bar<0>();
	s_add_i32 s1, s0, 0
	v_add_u32_e32 v87, s1, v86
	ds_read_b128 v[66:69], v87 offset:16384
	v_add_u32_e32 v74, s1, v85
	ds_read_b128 v[70:73], v74
	ds_read_b128 v[74:77], v74 offset:4096
	s_waitcnt lgkmcnt(0)
	v_mfma_f32_32x32x16_bf16 v[48:63], v[66:69], v[70:73], v[48:63]
	v_mfma_f32_32x32x16_bf16 v[32:47], v[66:69], v[74:77], v[32:47]
	ds_read_b128 v[66:69], v87 offset:20480
	v_add_u32_e32 v87, s1, v84
	s_waitcnt lgkmcnt(0)
	v_mfma_f32_32x32x16_bf16 v[16:31], v[66:69], v[70:73], v[16:31]
	v_mfma_f32_32x32x16_bf16 v[0:15], v[66:69], v[74:77], v[0:15]
	ds_read_b128 v[66:69], v87 offset:16384
	v_add_u32_e32 v74, s1, v83
	ds_read_b128 v[70:73], v74
	ds_read_b128 v[74:77], v74 offset:4096
	s_waitcnt lgkmcnt(0)
	v_mfma_f32_32x32x16_bf16 v[48:63], v[66:69], v[70:73], v[48:63]
	v_mfma_f32_32x32x16_bf16 v[32:47], v[66:69], v[74:77], v[32:47]
	ds_read_b128 v[66:69], v87 offset:20480
	v_add_u32_e32 v87, s1, v82
	s_waitcnt lgkmcnt(0)
	v_mfma_f32_32x32x16_bf16 v[16:31], v[66:69], v[70:73], v[16:31]
	v_mfma_f32_32x32x16_bf16 v[0:15], v[66:69], v[74:77], v[0:15]
	ds_read_b128 v[66:69], v87 offset:16384
	v_add_u32_e32 v74, s1, v81
	ds_read_b128 v[70:73], v74
	ds_read_b128 v[74:77], v74 offset:4096
	s_waitcnt lgkmcnt(0)
	v_mfma_f32_32x32x16_bf16 v[48:63], v[66:69], v[70:73], v[48:63]
	v_mfma_f32_32x32x16_bf16 v[32:47], v[66:69], v[74:77], v[32:47]
	ds_read_b128 v[66:69], v87 offset:20480
	v_add_u32_e32 v87, s1, v80
	s_waitcnt lgkmcnt(0)
	v_mfma_f32_32x32x16_bf16 v[16:31], v[66:69], v[70:73], v[16:31]
	v_mfma_f32_32x32x16_bf16 v[0:15], v[66:69], v[74:77], v[0:15]
	ds_read_b128 v[66:69], v87 offset:16384
	v_add_u32_e32 v74, s1, v79
	ds_read_b128 v[70:73], v74
	ds_read_b128 v[74:77], v74 offset:4096
	s_add_i32 s1, s0, 0xc000
	s_cmp_lg_u32 s0, 0x18000
	s_cselect_b32 s0, s1, 0
	s_waitcnt lgkmcnt(0)
	v_mfma_f32_32x32x16_bf16 v[48:63], v[66:69], v[70:73], v[48:63]
	s_add_i32 s0, s0, 0
	v_add_u32_e32 v86, s0, v86
	v_add_u32_e32 v84, s0, v84
	v_add_u32_e32 v82, s0, v82
	v_add_u32_e32 v80, s0, v80
	v_mfma_f32_32x32x16_bf16 v[32:47], v[66:69], v[74:77], v[32:47]
	ds_read_b128 v[66:69], v87 offset:20480
	s_waitcnt vmcnt(0) lgkmcnt(0)
	s_barrier
	s_waitcnt lgkmcnt(0)
	v_mfma_f32_32x32x16_bf16 v[16:31], v[66:69], v[70:73], v[16:31]
	v_mfma_f32_32x32x16_bf16 v[0:15], v[66:69], v[74:77], v[0:15]
	ds_read_b128 v[66:69], v86 offset:16384
	v_add_u32_e32 v74, s0, v85
	ds_read_b128 v[70:73], v74
	ds_read_b128 v[74:77], v74 offset:4096
	s_waitcnt lgkmcnt(0)
	v_mfma_f32_32x32x16_bf16 v[48:63], v[66:69], v[70:73], v[48:63]
	v_mfma_f32_32x32x16_bf16 v[32:47], v[66:69], v[74:77], v[32:47]
	ds_read_b128 v[66:69], v86 offset:20480
	s_waitcnt lgkmcnt(0)
	v_mfma_f32_32x32x16_bf16 v[16:31], v[66:69], v[70:73], v[16:31]
	v_mfma_f32_32x32x16_bf16 v[0:15], v[66:69], v[74:77], v[0:15]
	ds_read_b128 v[66:69], v84 offset:16384
	v_add_u32_e32 v74, s0, v83
	ds_read_b128 v[70:73], v74
	ds_read_b128 v[74:77], v74 offset:4096
	s_waitcnt lgkmcnt(0)
	v_mfma_f32_32x32x16_bf16 v[48:63], v[66:69], v[70:73], v[48:63]
	v_mfma_f32_32x32x16_bf16 v[32:47], v[66:69], v[74:77], v[32:47]
	ds_read_b128 v[66:69], v84 offset:20480
	s_waitcnt lgkmcnt(0)
	v_mfma_f32_32x32x16_bf16 v[16:31], v[66:69], v[70:73], v[16:31]
	v_mfma_f32_32x32x16_bf16 v[0:15], v[66:69], v[74:77], v[0:15]
	ds_read_b128 v[66:69], v82 offset:16384
	v_add_u32_e32 v74, s0, v81
	ds_read_b128 v[70:73], v74
	ds_read_b128 v[74:77], v74 offset:4096
	s_waitcnt lgkmcnt(0)
	v_mfma_f32_32x32x16_bf16 v[48:63], v[66:69], v[70:73], v[48:63]
	v_mfma_f32_32x32x16_bf16 v[32:47], v[66:69], v[74:77], v[32:47]
	ds_read_b128 v[66:69], v82 offset:20480
	s_waitcnt lgkmcnt(0)
	v_mfma_f32_32x32x16_bf16 v[16:31], v[66:69], v[70:73], v[16:31]
	v_mfma_f32_32x32x16_bf16 v[0:15], v[66:69], v[74:77], v[0:15]
	ds_read_b128 v[66:69], v80 offset:16384
	v_add_u32_e32 v74, s0, v79
	ds_read_b128 v[70:73], v74
	ds_read_b128 v[74:77], v74 offset:4096
	s_waitcnt lgkmcnt(0)
	v_mfma_f32_32x32x16_bf16 v[48:63], v[66:69], v[70:73], v[48:63]
	v_mfma_f32_32x32x16_bf16 v[32:47], v[66:69], v[74:77], v[32:47]
	ds_read_b128 v[66:69], v80 offset:20480
	s_waitcnt vmcnt(0) lgkmcnt(0)
	s_barrier
	s_waitcnt lgkmcnt(0)
	v_mfma_f32_32x32x16_bf16 v[16:31], v[66:69], v[70:73], v[16:31]
	v_mfma_f32_32x32x16_bf16 v[0:15], v[66:69], v[74:77], v[0:15]

; DEV int stage_next(int s) { return (s == 2 * GS_STAGE) ? 0 : s + GS_STAGE; }
; template <int WAIT0>
; DEV void gk_main(f32x16 (&acc)[2][2], const GTile& t, int s0) {
;     ...
;   vm_wait_bar<WAIT0>();
;   int stc = s0, std_ = stage_next(stage_next(s0));
; #pragma nounroll
;   for (int kt = 0; kt < nk - 2; ++kt) {
;     GK_DMA(std_, kt + 2);
;     GK_COMPUTE(stc);
;     vm_wait_bar<6>();
;     stc = stage_next(stc); std_ = stage_next(std_);
;   }
.LBB0_308:
	s_add_i32 s3, s0, s1
	s_mov_b32 s98, s3
	s_mov_b64 s[100:101], s[10:11]
	s_add_i32 s3, s14, 0
	v_add_u32_e32 v87, s3, v85
	ds_read_b128 v[88:91], v87
	ds_read_b128 v[92:95], v87 offset:4096
	v_add_u32_e32 v87, s3, v86
	ds_read_b128 v[96:99], v87 offset:16384
	ds_read_b128 v[100:103], v87 offset:20480
	s_waitcnt lgkmcnt(0)
	v_add_u32_e32 v87, s3, v83
	ds_read_b128 v[236:239], v87
	ds_read_b128 v[240:243], v87 offset:4096
	v_add_u32_e32 v87, s3, v84
	ds_read_b128 v[244:247], v87 offset:16384
	ds_read_b128 v[248:251], v87 offset:20480
	v_mfma_f32_32x32x16_bf16 v[48:63], v[96:99], v[88:91], v[48:63]
	v_mfma_f32_32x32x16_bf16 v[32:47], v[96:99], v[92:95], v[32:47]
	s_mov_b32 m0, s98
	v_lshl_add_u64 v[254:255], v[76:77], 0, s[100:101]
	global_load_lds_dwordx4 v[254:255], off
	v_mfma_f32_32x32x16_bf16 v[16:31], v[100:103], v[88:91], v[16:31]
	v_mfma_f32_32x32x16_bf16 v[0:15], v[100:103], v[92:95], v[0:15]
	s_add_i32 m0, s98, 0x2000
	v_lshl_add_u64 v[254:255], v[74:75], 0, s[100:101]
	global_load_lds_dwordx4 v[254:255], off
	v_add_u32_e32 v87, s3, v81
	s_waitcnt lgkmcnt(0)
	ds_read_b128 v[88:91], v87
	ds_read_b128 v[92:95], v87 offset:4096
	v_add_u32_e32 v87, s3, v82
	ds_read_b128 v[96:99], v87 offset:16384
	ds_read_b128 v[100:103], v87 offset:20480
	v_mfma_f32_32x32x16_bf16 v[48:63], v[244:247], v[236:239], v[48:63]
	v_mfma_f32_32x32x16_bf16 v[32:47], v[244:247], v[240:243], v[32:47]
	s_add_i32 m0, s98, 0x4000
	v_lshl_add_u64 v[254:255], v[72:73], 0, s[100:101]
	global_load_lds_dwordx4 v[254:255], off
	v_mfma_f32_32x32x16_bf16 v[16:31], v[248:251], v[236:239], v[16:31]
	v_mfma_f32_32x32x16_bf16 v[0:15], v[248:251], v[240:243], v[0:15]
	s_add_i32 m0, s98, 0x6000
	v_lshl_add_u64 v[254:255], v[70:71], 0, s[100:101]
	global_load_lds_dwordx4 v[254:255], off
	v_add_u32_e32 v87, s3, v79
	s_waitcnt lgkmcnt(0)
	ds_read_b128 v[236:239], v87
	ds_read_b128 v[240:243], v87 offset:4096
	v_add_u32_e32 v87, s3, v80
	ds_read_b128 v[244:247], v87 offset:16384
	ds_read_b128 v[248:251], v87 offset:20480
	v_mfma_f32_32x32x16_bf16 v[48:63], v[96:99], v[88:91], v[48:63]
	v_mfma_f32_32x32x16_bf16 v[32:47], v[96:99], v[92:95], v[32:47]
	s_add_i32 m0, s98, 0x8000
	v_lshl_add_u64 v[254:255], v[68:69], 0, s[100:101]
	global_load_lds_dwordx4 v[254:255], off
	v_mfma_f32_32x32x16_bf16 v[16:31], v[100:103], v[88:91], v[16:31]
	v_mfma_f32_32x32x16_bf16 v[0:15], v[100:103], v[92:95], v[0:15]
	s_add_i32 m0, s98, 0xa000
	v_lshl_add_u64 v[254:255], v[66:67], 0, s[100:101]
	global_load_lds_dwordx4 v[254:255], off
	s_add_i32 s3, s14, 0xc000
	s_cmp_lg_u32 s14, 0x18000
	s_cselect_b32 s14, s3, 0
	s_add_i32 s3, s1, 0xc000
	s_waitcnt lgkmcnt(0)
	v_mfma_f32_32x32x16_bf16 v[48:63], v[244:247], v[236:239], v[48:63]
	s_cmp_lg_u32 s1, 0x18000
	s_waitcnt vmcnt(6) lgkmcnt(0)
	s_barrier
	s_cselect_b32 s1, s3, 0
	s_add_u32 s10, s10, 0x80
	s_addc_u32 s11, s11, 0
	v_mfma_f32_32x32x16_bf16 v[32:47], v[244:247], v[240:243], v[32:47]
	v_mfma_f32_32x32x16_bf16 v[16:31], v[248:251], v[236:239], v[16:31]
	v_mfma_f32_32x32x16_bf16 v[0:15], v[248:251], v[240:243], v[0:15]
	s_cmpk_lg_i32 s10, 0x700
	s_cbranch_scc1 .LBB0_308
; DEV int stage_next(int s) { return (s == 2 * GS_STAGE) ? 0 : s + GS_STAGE; }
; template <int WAIT0>
; DEV void gk_main(f32x16 (&acc)[2][2], const GTile& t, int s0) {
;     ...
;   GK_COMPUTE(stc);
;   vm_wait_bar<0>();
;   stc = stage_next(stc);
;   GK_COMPUTE(stc);
;   vm_wait_bar<0>();
; template <int WAIT_E, int WAIT_O, class TileFn, class EpiFn>
; DEV void gemm_seq(int ntiles, TileFn tf, EpiFn epi) {
;     ...
;   for (int i = 0; i < ntiles; ++i) {
;     f32x16 acc[2][2]; acc_zero(acc);
;     if (i == 0) gk_main<6>(acc, cur, s0);
;     else if (i & 1) gk_main<WAIT_O>(acc, cur, s0);
;     else gk_main<WAIT_E>(acc, cur, s0);
;     const int sn = stage_next(s0);
;     if (i + 1 < ntiles) { cur = tf(i + 1); gk_issue2(cur, sn); }
;     epi(i, acc, s0);
;     s0 = sn;
;   }
	s_add_i32 s0, s14, 0
	v_add_u32_e32 v87, s0, v86
	ds_read_b128 v[66:69], v87 offset:16384
	v_add_u32_e32 v74, s0, v85
	ds_read_b128 v[70:73], v74
	ds_read_b128 v[74:77], v74 offset:4096
	s_waitcnt lgkmcnt(0)
	v_mfma_f32_32x32x16_bf16 v[48:63], v[66:69], v[70:73], v[48:63]
	v_mfma_f32_32x32x16_bf16 v[32:47], v[66:69], v[74:77], v[32:47]
	ds_read_b128 v[66:69], v87 offset:20480
	v_add_u32_e32 v87, s0, v84
	s_waitcnt lgkmcnt(0)
	v_mfma_f32_32x32x16_bf16 v[16:31], v[66:69], v[70:73], v[16:31]
	v_mfma_f32_32x32x16_bf16 v[0:15], v[66:69], v[74:77], v[0:15]
	ds_read_b128 v[66:69], v87 offset:16384
	v_add_u32_e32 v74, s0, v83
	ds_read_b128 v[70:73], v74
	ds_read_b128 v[74:77], v74 offset:4096
	s_waitcnt lgkmcnt(0)
	v_mfma_f32_32x32x16_bf16 v[48:63], v[66:69], v[70:73], v[48:63]
	v_mfma_f32_32x32x16_bf16 v[32:47], v[66:69], v[74:77], v[32:47]
	ds_read_b128 v[66:69], v87 offset:20480
	v_add_u32_e32 v87, s0, v82
	s_waitcnt lgkmcnt(0)
	v_mfma_f32_32x32x16_bf16 v[16:31], v[66:69], v[70:73], v[16:31]
	v_mfma_f32_32x32x16_bf16 v[0:15], v[66:69], v[74:77], v[0:15]
	ds_read_b128 v[66:69], v87 offset:16384
	v_add_u32_e32 v74, s0, v81
	ds_read_b128 v[70:73], v74
	ds_read_b128 v[74:77], v74 offset:4096
	s_waitcnt lgkmcnt(0)
	v_mfma_f32_32x32x16_bf16 v[48:63], v[66:69], v[70:73], v[48:63]
	v_mfma_f32_32x32x16_bf16 v[32:47], v[66:69], v[74:77], v[32:47]
	ds_read_b128 v[66:69], v87 offset:20480
	v_add_u32_e32 v87, s0, v80
	s_waitcnt lgkmcnt(0)
	v_mfma_f32_32x32x16_bf16 v[16:31], v[66:69], v[70:73], v[16:31]
	v_mfma_f32_32x32x16_bf16 v[0:15], v[66:69], v[74:77], v[0:15]
	ds_read_b128 v[66:69], v87 offset:16384
	v_add_u32_e32 v74, s0, v79
	ds_read_b128 v[70:73], v74
	ds_read_b128 v[74:77], v74 offset:4096
	s_add_i32 s0, s14, 0xc000
	s_cmp_lg_u32 s14, 0x18000
	s_cselect_b32 s0, s0, 0
	s_waitcnt lgkmcnt(0)
	v_mfma_f32_32x32x16_bf16 v[48:63], v[66:69], v[70:73], v[48:63]
	s_add_i32 s0, s0, 0
	v_add_u32_e32 v86, s0, v86
	v_add_u32_e32 v84, s0, v84
	v_add_u32_e32 v82, s0, v82
	v_add_u32_e32 v80, s0, v80
	v_mfma_f32_32x32x16_bf16 v[32:47], v[66:69], v[74:77], v[32:47]
	ds_read_b128 v[66:69], v87 offset:20480
	s_waitcnt vmcnt(0) lgkmcnt(0)
	s_barrier
	s_waitcnt lgkmcnt(0)
	v_mfma_f32_32x32x16_bf16 v[16:31], v[66:69], v[70:73], v[16:31]
	v_mfma_f32_32x32x16_bf16 v[0:15], v[66:69], v[74:77], v[0:15]
	ds_read_b128 v[66:69], v86 offset:16384
	v_add_u32_e32 v74, s0, v85
	ds_read_b128 v[70:73], v74
	ds_read_b128 v[74:77], v74 offset:4096
	s_waitcnt lgkmcnt(0)
	v_mfma_f32_32x32x16_bf16 v[48:63], v[66:69], v[70:73], v[48:63]
	v_mfma_f32_32x32x16_bf16 v[32:47], v[66:69], v[74:77], v[32:47]
	ds_read_b128 v[66:69], v86 offset:20480
	s_waitcnt lgkmcnt(0)
	v_mfma_f32_32x32x16_bf16 v[16:31], v[66:69], v[70:73], v[16:31]
	v_mfma_f32_32x32x16_bf16 v[0:15], v[66:69], v[74:77], v[0:15]
	ds_read_b128 v[66:69], v84 offset:16384
	v_add_u32_e32 v74, s0, v83
	ds_read_b128 v[70:73], v74
	ds_read_b128 v[74:77], v74 offset:4096
	s_waitcnt lgkmcnt(0)
	v_mfma_f32_32x32x16_bf16 v[48:63], v[66:69], v[70:73], v[48:63]
	v_mfma_f32_32x32x16_bf16 v[32:47], v[66:69], v[74:77], v[32:47]
	ds_read_b128 v[66:69], v84 offset:20480
	s_waitcnt lgkmcnt(0)
	v_mfma_f32_32x32x16_bf16 v[16:31], v[66:69], v[70:73], v[16:31]
	v_mfma_f32_32x32x16_bf16 v[0:15], v[66:69], v[74:77], v[0:15]
	ds_read_b128 v[66:69], v82 offset:16384
	v_add_u32_e32 v74, s0, v81
	ds_read_b128 v[70:73], v74
	ds_read_b128 v[74:77], v74 offset:4096
	s_waitcnt lgkmcnt(0)
	v_mfma_f32_32x32x16_bf16 v[48:63], v[66:69], v[70:73], v[48:63]
	v_mfma_f32_32x32x16_bf16 v[32:47], v[66:69], v[74:77], v[32:47]
	ds_read_b128 v[66:69], v82 offset:20480
	s_waitcnt lgkmcnt(0)
	v_mfma_f32_32x32x16_bf16 v[16:31], v[66:69], v[70:73], v[16:31]
	v_mfma_f32_32x32x16_bf16 v[0:15], v[66:69], v[74:77], v[0:15]
	ds_read_b128 v[66:69], v80 offset:16384
	v_add_u32_e32 v74, s0, v79
	ds_read_b128 v[70:73], v74
	ds_read_b128 v[74:77], v74 offset:4096
	s_waitcnt lgkmcnt(0)
	v_mfma_f32_32x32x16_bf16 v[48:63], v[66:69], v[70:73], v[48:63]
	v_mfma_f32_32x32x16_bf16 v[32:47], v[66:69], v[74:77], v[32:47]
	ds_read_b128 v[66:69], v80 offset:20480
	s_waitcnt vmcnt(0) lgkmcnt(0)
	s_barrier
	s_waitcnt lgkmcnt(0)
	v_mfma_f32_32x32x16_bf16 v[16:31], v[66:69], v[70:73], v[16:31]
	v_mfma_f32_32x32x16_bf16 v[0:15], v[66:69], v[74:77], v[0:15]
	s_add_i32 s0, s15, 1
	s_mov_b32 s14, s2
	s_cmp_eq_u32 s15, 3
	s_cbranch_scc1 .LBB0_294

; DEV int stage_next(int s) { return (s == 2 * GS_STAGE) ? 0 : s + GS_STAGE; }
; template <int WAIT0>
; DEV void gk_main(f32x16 (&acc)[2][2], const GTile& t, int s0) {
;     ...
;   vm_wait_bar<WAIT0>();
;   int stc = s0, std_ = stage_next(stage_next(s0));
; #pragma nounroll
;   for (int kt = 0; kt < nk - 2; ++kt) {
;     GK_DMA(std_, kt + 2);
;     GK_COMPUTE(stc);
;     vm_wait_bar<6>();
;     stc = stage_next(stc); std_ = stage_next(std_);
;   }
.LBB0_437:
	s_add_i32 s12, s10, s11
	s_mov_b32 s98, s12
	s_mov_b64 s[100:101], s[6:7]
	s_add_i32 s12, s3, 0
	v_add_u32_e32 v252, s12, v82
	v_add_u32_e32 v253, s12, v83
	ds_read_b128 v[84:87], v252
	ds_read_b128 v[88:91], v252 offset:4096
	ds_read_b128 v[92:95], v253 offset:16384
	ds_read_b128 v[96:99], v253 offset:20480
	s_waitcnt lgkmcnt(0)
	v_add_u32_e32 v252, s12, v80
	v_add_u32_e32 v253, s12, v81
	ds_read_b128 v[236:239], v252
	ds_read_b128 v[240:243], v252 offset:4096
	ds_read_b128 v[244:247], v253 offset:16384
	ds_read_b128 v[248:251], v253 offset:20480
	v_mfma_f32_32x32x16_bf16 v[48:63], v[92:95], v[84:87], v[48:63]
	v_mfma_f32_32x32x16_bf16 v[16:31], v[92:95], v[88:91], v[16:31]
	s_mov_b32 m0, s98
	v_lshl_add_u64 v[254:255], v[74:75], 0, s[100:101]
	global_load_lds_dwordx4 v[254:255], off
	v_mfma_f32_32x32x16_bf16 v[32:47], v[96:99], v[84:87], v[32:47]
	v_mfma_f32_32x32x16_bf16 v[0:15], v[96:99], v[88:91], v[0:15]
	s_add_i32 m0, s98, 0x2000
	v_lshl_add_u64 v[254:255], v[72:73], 0, s[100:101]
	global_load_lds_dwordx4 v[254:255], off
	s_waitcnt lgkmcnt(0)
	v_add_u32_e32 v252, s12, v78
	v_add_u32_e32 v253, s12, v79
	ds_read_b128 v[84:87], v252
	ds_read_b128 v[88:91], v252 offset:4096
	ds_read_b128 v[92:95], v253 offset:16384
	ds_read_b128 v[96:99], v253 offset:20480
	v_mfma_f32_32x32x16_bf16 v[48:63], v[244:247], v[236:239], v[48:63]
	v_mfma_f32_32x32x16_bf16 v[16:31], v[244:247], v[240:243], v[16:31]
	s_add_i32 m0, s98, 0x4000
	v_lshl_add_u64 v[254:255], v[70:71], 0, s[100:101]
	global_load_lds_dwordx4 v[254:255], off
	v_mfma_f32_32x32x16_bf16 v[32:47], v[248:251], v[236:239], v[32:47]
	v_mfma_f32_32x32x16_bf16 v[0:15], v[248:251], v[240:243], v[0:15]
	s_add_i32 m0, s98, 0x6000
	v_lshl_add_u64 v[254:255], v[68:69], 0, s[100:101]
	global_load_lds_dwordx4 v[254:255], off
	s_waitcnt lgkmcnt(0)
	v_add_u32_e32 v252, s12, v76
	v_add_u32_e32 v253, s12, v77
	ds_read_b128 v[236:239], v252
	ds_read_b128 v[240:243], v252 offset:4096
	ds_read_b128 v[244:247], v253 offset:16384
	ds_read_b128 v[248:251], v253 offset:20480
	v_mfma_f32_32x32x16_bf16 v[48:63], v[92:95], v[84:87], v[48:63]
	v_mfma_f32_32x32x16_bf16 v[16:31], v[92:95], v[88:91], v[16:31]
	s_add_i32 m0, s98, 0x8000
	v_lshl_add_u64 v[254:255], v[66:67], 0, s[100:101]
	global_load_lds_dwordx4 v[254:255], off
	v_mfma_f32_32x32x16_bf16 v[32:47], v[96:99], v[84:87], v[32:47]
	v_mfma_f32_32x32x16_bf16 v[0:15], v[96:99], v[88:91], v[0:15]
	s_add_i32 m0, s98, 0xa000
	v_lshl_add_u64 v[254:255], v[64:65], 0, s[100:101]
	global_load_lds_dwordx4 v[254:255], off
	s_add_i32 s12, s3, 0xc000
	s_cmp_lg_u32 s3, 0x18000
	s_cselect_b32 s3, s12, 0
	s_waitcnt lgkmcnt(0)
	v_mfma_f32_32x32x16_bf16 v[48:63], v[244:247], v[236:239], v[48:63]
	s_add_i32 s12, s11, 0xc000
	s_cmp_lg_u32 s11, 0x18000
	s_waitcnt vmcnt(6) lgkmcnt(0)
	s_barrier
	s_cselect_b32 s11, s12, 0
	s_add_u32 s6, s6, 0x80
	v_mfma_f32_32x32x16_bf16 v[16:31], v[244:247], v[240:243], v[16:31]
	s_addc_u32 s7, s7, 0
	v_mfma_f32_32x32x16_bf16 v[32:47], v[248:251], v[236:239], v[32:47]
	v_mfma_f32_32x32x16_bf16 v[0:15], v[248:251], v[240:243], v[0:15]
	s_cmpk_lg_i32 s6, 0x700
	s_cbranch_scc1 .LBB0_437
; DEV int stage_next(int s) { return (s == 2 * GS_STAGE) ? 0 : s + GS_STAGE; }
; template <int WAIT0>
; DEV void gk_main(f32x16 (&acc)[2][2], const GTile& t, int s0) {
;     ...
;   GK_COMPUTE(stc);
;   vm_wait_bar<0>();
;   stc = stage_next(stc);
;   GK_COMPUTE(stc);
;   vm_wait_bar<0>();
; template <int WAIT_E, int WAIT_O, class TileFn, class EpiFn>
; DEV void gemm_seq(int ntiles, TileFn tf, EpiFn epi) {
;     ...
;   for (int i = 0; i < ntiles; ++i) {
;     f32x16 acc[2][2]; acc_zero(acc);
;     if (i == 0) gk_main<6>(acc, cur, s0);
;     else if (i & 1) gk_main<WAIT_O>(acc, cur, s0);
;     else gk_main<WAIT_E>(acc, cur, s0);
;     const int sn = stage_next(s0);
;     if (i + 1 < ntiles) { cur = tf(i + 1); gk_issue2(cur, sn); }
;     epi(i, acc, s0);
;     s0 = sn;
;   }
	s_add_i32 s6, s3, 0
	v_add_u32_e32 v84, s6, v83
	ds_read_b128 v[64:67], v84 offset:16384
	v_add_u32_e32 v72, s6, v82
	ds_read_b128 v[68:71], v72
	ds_read_b128 v[72:75], v72 offset:4096
	s_waitcnt lgkmcnt(0)
	v_mfma_f32_32x32x16_bf16 v[48:63], v[64:67], v[68:71], v[48:63]
	v_mfma_f32_32x32x16_bf16 v[16:31], v[64:67], v[72:75], v[16:31]
	ds_read_b128 v[64:67], v84 offset:20480
	v_add_u32_e32 v84, s6, v81
	s_waitcnt lgkmcnt(0)
	v_mfma_f32_32x32x16_bf16 v[32:47], v[64:67], v[68:71], v[32:47]
	v_mfma_f32_32x32x16_bf16 v[0:15], v[64:67], v[72:75], v[0:15]
	ds_read_b128 v[64:67], v84 offset:16384
	v_add_u32_e32 v72, s6, v80
	ds_read_b128 v[68:71], v72
	ds_read_b128 v[72:75], v72 offset:4096
	s_waitcnt lgkmcnt(0)
	v_mfma_f32_32x32x16_bf16 v[48:63], v[64:67], v[68:71], v[48:63]
	v_mfma_f32_32x32x16_bf16 v[16:31], v[64:67], v[72:75], v[16:31]
	ds_read_b128 v[64:67], v84 offset:20480
	v_add_u32_e32 v84, s6, v79
	s_waitcnt lgkmcnt(0)
	v_mfma_f32_32x32x16_bf16 v[32:47], v[64:67], v[68:71], v[32:47]
	v_mfma_f32_32x32x16_bf16 v[0:15], v[64:67], v[72:75], v[0:15]
	ds_read_b128 v[64:67], v84 offset:16384
	v_add_u32_e32 v72, s6, v78
	ds_read_b128 v[68:71], v72
	ds_read_b128 v[72:75], v72 offset:4096
	s_waitcnt lgkmcnt(0)
	v_mfma_f32_32x32x16_bf16 v[48:63], v[64:67], v[68:71], v[48:63]
	v_mfma_f32_32x32x16_bf16 v[16:31], v[64:67], v[72:75], v[16:31]
	ds_read_b128 v[64:67], v84 offset:20480
	v_add_u32_e32 v84, s6, v77
	s_waitcnt lgkmcnt(0)
	v_mfma_f32_32x32x16_bf16 v[32:47], v[64:67], v[68:71], v[32:47]
	v_mfma_f32_32x32x16_bf16 v[0:15], v[64:67], v[72:75], v[0:15]
	ds_read_b128 v[64:67], v84 offset:16384
	v_add_u32_e32 v72, s6, v76
	ds_read_b128 v[68:71], v72
	ds_read_b128 v[72:75], v72 offset:4096
	s_add_i32 s6, s3, 0xc000
	s_cmp_lg_u32 s3, 0x18000
	s_cselect_b32 s3, s6, 0
	s_waitcnt lgkmcnt(0)
	v_mfma_f32_32x32x16_bf16 v[48:63], v[64:67], v[68:71], v[48:63]
	s_add_i32 s3, s3, 0
	v_add_u32_e32 v83, s3, v83
	v_add_u32_e32 v81, s3, v81
	v_add_u32_e32 v79, s3, v79
	v_add_u32_e32 v77, s3, v77
	v_mfma_f32_32x32x16_bf16 v[16:31], v[64:67], v[72:75], v[16:31]
	ds_read_b128 v[64:67], v84 offset:20480
	s_waitcnt vmcnt(0) lgkmcnt(0)
	s_barrier
	s_waitcnt lgkmcnt(0)
	v_mfma_f32_32x32x16_bf16 v[32:47], v[64:67], v[68:71], v[32:47]
	v_mfma_f32_32x32x16_bf16 v[0:15], v[64:67], v[72:75], v[0:15]
	ds_read_b128 v[64:67], v83 offset:16384
	v_add_u32_e32 v72, s3, v82
	ds_read_b128 v[68:71], v72
	ds_read_b128 v[72:75], v72 offset:4096
	s_waitcnt lgkmcnt(0)
	v_mfma_f32_32x32x16_bf16 v[48:63], v[64:67], v[68:71], v[48:63]
	v_mfma_f32_32x32x16_bf16 v[16:31], v[64:67], v[72:75], v[16:31]
	ds_read_b128 v[64:67], v83 offset:20480
	s_waitcnt lgkmcnt(0)
	v_mfma_f32_32x32x16_bf16 v[32:47], v[64:67], v[68:71], v[32:47]
	v_mfma_f32_32x32x16_bf16 v[0:15], v[64:67], v[72:75], v[0:15]
	ds_read_b128 v[64:67], v81 offset:16384
	v_add_u32_e32 v72, s3, v80
	ds_read_b128 v[68:71], v72
	ds_read_b128 v[72:75], v72 offset:4096
	s_waitcnt lgkmcnt(0)
	v_mfma_f32_32x32x16_bf16 v[48:63], v[64:67], v[68:71], v[48:63]
	v_mfma_f32_32x32x16_bf16 v[16:31], v[64:67], v[72:75], v[16:31]
	ds_read_b128 v[64:67], v81 offset:20480
	s_waitcnt lgkmcnt(0)
	v_mfma_f32_32x32x16_bf16 v[32:47], v[64:67], v[68:71], v[32:47]
	v_mfma_f32_32x32x16_bf16 v[0:15], v[64:67], v[72:75], v[0:15]
	ds_read_b128 v[64:67], v79 offset:16384
	v_add_u32_e32 v72, s3, v78
	ds_read_b128 v[68:71], v72
	ds_read_b128 v[72:75], v72 offset:4096
	s_waitcnt lgkmcnt(0)
	v_mfma_f32_32x32x16_bf16 v[48:63], v[64:67], v[68:71], v[48:63]
	v_mfma_f32_32x32x16_bf16 v[16:31], v[64:67], v[72:75], v[16:31]
	ds_read_b128 v[64:67], v79 offset:20480
	s_waitcnt lgkmcnt(0)
	v_mfma_f32_32x32x16_bf16 v[32:47], v[64:67], v[68:71], v[32:47]
	v_mfma_f32_32x32x16_bf16 v[0:15], v[64:67], v[72:75], v[0:15]
	ds_read_b128 v[64:67], v77 offset:16384
	v_add_u32_e32 v72, s3, v76
	ds_read_b128 v[68:71], v72
	ds_read_b128 v[72:75], v72 offset:4096
	s_waitcnt lgkmcnt(0)
	v_mfma_f32_32x32x16_bf16 v[48:63], v[64:67], v[68:71], v[48:63]
	v_mfma_f32_32x32x16_bf16 v[16:31], v[64:67], v[72:75], v[16:31]
	ds_read_b128 v[64:67], v77 offset:20480
	s_waitcnt vmcnt(0) lgkmcnt(0)
	s_barrier
	s_waitcnt lgkmcnt(0)
	v_mfma_f32_32x32x16_bf16 v[32:47], v[64:67], v[68:71], v[32:47]
	v_mfma_f32_32x32x16_bf16 v[0:15], v[64:67], v[72:75], v[0:15]
	s_add_i32 s3, s2, 1
	s_cmp_eq_u32 s2, 7
	s_cbranch_scc1 .LBB0_423

; DEV int stage_next(int s) { return (s == 2 * GS_STAGE) ? 0 : s + GS_STAGE; }
; template <int WAIT0>
; DEV void gk_main(f32x16 (&acc)[2][2], const GTile& t, int s0) {
;     ...
;   vm_wait_bar<WAIT0>();
;   int stc = s0, std_ = stage_next(stage_next(s0));
; #pragma nounroll
;   for (int kt = 0; kt < nk - 2; ++kt) {
;     GK_DMA(std_, kt + 2);
;     GK_COMPUTE(stc);
;     vm_wait_bar<6>();
;     stc = stage_next(stc); std_ = stage_next(std_);
;   }
.LBB0_715:
	s_add_i32 s14, s3, s13
	s_mov_b32 s98, s14
	s_mov_b64 s[100:101], s[6:7]
	s_add_i32 s15, s2, 0
	v_add_u32_e32 v253, s15, v81
	v_add_u32_e32 v252, s15, v83
	ds_read_b128 v[84:87], v252 offset:16384
	ds_read_b128 v[88:91], v253
	ds_read_b128 v[92:95], v253 offset:4096
	ds_read_b128 v[96:99], v252 offset:20480
	s_waitcnt lgkmcnt(0)
	v_add_u32_e32 v101, s15, v82
	v_add_u32_e32 v100, s15, v79
	s_add_i32 s14, s2, 0xc000
	s_cmp_lg_u32 s2, 0x18000
	s_cselect_b32 s2, s14, 0
	s_add_i32 s14, s13, 0xc000
	s_cmp_lg_u32 s13, 0x18000
	s_cselect_b32 s13, s14, 0
	s_add_u32 s6, s6, 0x80
	s_addc_u32 s7, s7, 0
	ds_read_b128 v[236:239], v101 offset:16384
	ds_read_b128 v[240:243], v100
	ds_read_b128 v[244:247], v100 offset:4096
	ds_read_b128 v[248:251], v101 offset:20480
	v_mfma_f32_32x32x16_bf16 v[48:63], v[84:87], v[88:91], v[48:63]
	v_mfma_f32_32x32x16_bf16 v[16:31], v[84:87], v[92:95], v[16:31]
	s_mov_b32 m0, s98
	v_lshl_add_u64 v[254:255], v[74:75], 0, s[100:101]
	global_load_lds_dwordx4 v[254:255], off
	v_mfma_f32_32x32x16_bf16 v[32:47], v[96:99], v[88:91], v[32:47]
	v_mfma_f32_32x32x16_bf16 v[0:15], v[96:99], v[92:95], v[0:15]
	s_add_i32 m0, s98, 0x2000
	v_lshl_add_u64 v[254:255], v[72:73], 0, s[100:101]
	global_load_lds_dwordx4 v[254:255], off
	v_add_u32_e32 v101, s15, v80
	v_add_u32_e32 v100, s15, v77
	s_waitcnt lgkmcnt(0)
	ds_read_b128 v[84:87], v101 offset:16384
	ds_read_b128 v[88:91], v100
	ds_read_b128 v[92:95], v100 offset:4096
	ds_read_b128 v[96:99], v101 offset:20480
	v_mfma_f32_32x32x16_bf16 v[48:63], v[236:239], v[240:243], v[48:63]
	v_mfma_f32_32x32x16_bf16 v[16:31], v[236:239], v[244:247], v[16:31]
	s_add_i32 m0, s98, 0x4000
	v_lshl_add_u64 v[254:255], v[70:71], 0, s[100:101]
	global_load_lds_dwordx4 v[254:255], off
	v_mfma_f32_32x32x16_bf16 v[32:47], v[248:251], v[240:243], v[32:47]
	v_mfma_f32_32x32x16_bf16 v[0:15], v[248:251], v[244:247], v[0:15]
	s_add_i32 m0, s98, 0x6000
	v_lshl_add_u64 v[254:255], v[68:69], 0, s[100:101]
	global_load_lds_dwordx4 v[254:255], off
	v_add_u32_e32 v101, s15, v78
	v_add_u32_e32 v100, s15, v76
	s_waitcnt lgkmcnt(0)
	ds_read_b128 v[236:239], v101 offset:16384
	ds_read_b128 v[240:243], v100
	ds_read_b128 v[244:247], v100 offset:4096
	ds_read_b128 v[248:251], v101 offset:20480
	v_mfma_f32_32x32x16_bf16 v[48:63], v[84:87], v[88:91], v[48:63]
	v_mfma_f32_32x32x16_bf16 v[16:31], v[84:87], v[92:95], v[16:31]
	s_add_i32 m0, s98, 0x8000
	v_lshl_add_u64 v[254:255], v[66:67], 0, s[100:101]
	global_load_lds_dwordx4 v[254:255], off
	v_mfma_f32_32x32x16_bf16 v[32:47], v[96:99], v[88:91], v[32:47]
	v_mfma_f32_32x32x16_bf16 v[0:15], v[96:99], v[92:95], v[0:15]
	s_add_i32 m0, s98, 0xa000
	v_lshl_add_u64 v[254:255], v[64:65], 0, s[100:101]
	global_load_lds_dwordx4 v[254:255], off
	s_waitcnt vmcnt(6) lgkmcnt(0)
	s_barrier
	s_waitcnt lgkmcnt(0)
	v_mfma_f32_32x32x16_bf16 v[48:63], v[236:239], v[240:243], v[48:63]
	v_mfma_f32_32x32x16_bf16 v[16:31], v[236:239], v[244:247], v[16:31]
	v_mfma_f32_32x32x16_bf16 v[32:47], v[248:251], v[240:243], v[32:47]
	v_mfma_f32_32x32x16_bf16 v[0:15], v[248:251], v[244:247], v[0:15]
	s_cmpk_lg_i32 s6, 0x700
	s_cbranch_scc1 .LBB0_715
; DEV int stage_next(int s) { return (s == 2 * GS_STAGE) ? 0 : s + GS_STAGE; }
; template <int WAIT0>
; DEV void gk_main(f32x16 (&acc)[2][2], const GTile& t, int s0) {
;     ...
;   GK_COMPUTE(stc);
;   vm_wait_bar<0>();
;   stc = stage_next(stc);
;   GK_COMPUTE(stc);
;   vm_wait_bar<0>();
	s_add_i32 s3, s2, 0
	v_add_u32_e32 v84, s3, v83
	ds_read_b128 v[64:67], v84 offset:16384
	v_add_u32_e32 v72, s3, v81
	ds_read_b128 v[68:71], v72
	ds_read_b128 v[72:75], v72 offset:4096
	ds_read_b128 v[84:87], v84 offset:20480
	s_mov_b64 s[6:7], 0
	s_waitcnt lgkmcnt(0)
	v_mfma_f32_32x32x16_bf16 v[32:47], v[84:87], v[68:71], v[32:47]
	v_mfma_f32_32x32x16_bf16 v[0:15], v[84:87], v[72:75], v[0:15]
	v_add_u32_e32 v84, s3, v82
	v_mfma_f32_32x32x16_bf16 v[48:63], v[64:67], v[68:71], v[48:63]
	v_mfma_f32_32x32x16_bf16 v[16:31], v[64:67], v[72:75], v[16:31]
	ds_read_b128 v[64:67], v84 offset:16384
	v_add_u32_e32 v72, s3, v79
	ds_read_b128 v[68:71], v72
	ds_read_b128 v[72:75], v72 offset:4096
	ds_read_b128 v[84:87], v84 offset:20480
	s_waitcnt lgkmcnt(0)
	v_mfma_f32_32x32x16_bf16 v[32:47], v[84:87], v[68:71], v[32:47]
	v_mfma_f32_32x32x16_bf16 v[0:15], v[84:87], v[72:75], v[0:15]
	v_add_u32_e32 v84, s3, v80
	v_mfma_f32_32x32x16_bf16 v[48:63], v[64:67], v[68:71], v[48:63]
	v_mfma_f32_32x32x16_bf16 v[16:31], v[64:67], v[72:75], v[16:31]
	ds_read_b128 v[64:67], v84 offset:16384
	v_add_u32_e32 v72, s3, v77
	ds_read_b128 v[68:71], v72
	ds_read_b128 v[72:75], v72 offset:4096
	ds_read_b128 v[84:87], v84 offset:20480
	s_waitcnt lgkmcnt(0)
	v_mfma_f32_32x32x16_bf16 v[32:47], v[84:87], v[68:71], v[32:47]
	v_mfma_f32_32x32x16_bf16 v[0:15], v[84:87], v[72:75], v[0:15]
	v_add_u32_e32 v84, s3, v78
	v_mfma_f32_32x32x16_bf16 v[48:63], v[64:67], v[68:71], v[48:63]
	v_mfma_f32_32x32x16_bf16 v[16:31], v[64:67], v[72:75], v[16:31]
	ds_read_b128 v[64:67], v84 offset:16384
	v_add_u32_e32 v72, s3, v76
	s_add_i32 s3, s2, 0xc000
	ds_read_b128 v[68:71], v72
	ds_read_b128 v[72:75], v72 offset:4096
	ds_read_b128 v[84:87], v84 offset:20480
	s_cmp_lg_u32 s2, 0x18000
	s_cselect_b32 s2, s3, 0
	s_add_i32 s2, s2, 0
	s_waitcnt vmcnt(0) lgkmcnt(0)
	s_barrier
	v_add_u32_e32 v83, s2, v83
	s_waitcnt lgkmcnt(0)
	v_mfma_f32_32x32x16_bf16 v[48:63], v[64:67], v[68:71], v[48:63]
	v_mfma_f32_32x32x16_bf16 v[16:31], v[64:67], v[72:75], v[16:31]
	ds_read_b128 v[64:67], v83 offset:16384
	v_mfma_f32_32x32x16_bf16 v[32:47], v[84:87], v[68:71], v[32:47]
	v_mfma_f32_32x32x16_bf16 v[0:15], v[84:87], v[72:75], v[0:15]
	v_add_u32_e32 v72, s2, v81
	ds_read_b128 v[68:71], v72
	ds_read_b128 v[72:75], v72 offset:4096
	ds_read_b128 v[84:87], v83 offset:20480
	v_add_u32_e32 v81, s2, v82
	s_waitcnt lgkmcnt(0)
	v_mfma_f32_32x32x16_bf16 v[48:63], v[64:67], v[68:71], v[48:63]
	v_mfma_f32_32x32x16_bf16 v[16:31], v[64:67], v[72:75], v[16:31]
	ds_read_b128 v[64:67], v81 offset:16384
	v_mfma_f32_32x32x16_bf16 v[32:47], v[84:87], v[68:71], v[32:47]
	v_mfma_f32_32x32x16_bf16 v[0:15], v[84:87], v[72:75], v[0:15]
	v_add_u32_e32 v72, s2, v79
	ds_read_b128 v[68:71], v72
	ds_read_b128 v[72:75], v72 offset:4096
	ds_read_b128 v[82:85], v81 offset:20480
	v_add_u32_e32 v79, s2, v80
	s_waitcnt lgkmcnt(0)
	v_mfma_f32_32x32x16_bf16 v[48:63], v[64:67], v[68:71], v[48:63]
	v_mfma_f32_32x32x16_bf16 v[16:31], v[64:67], v[72:75], v[16:31]
	ds_read_b128 v[64:67], v79 offset:16384
	v_mfma_f32_32x32x16_bf16 v[32:47], v[82:85], v[68:71], v[32:47]
	v_mfma_f32_32x32x16_bf16 v[0:15], v[82:85], v[72:75], v[0:15]
	v_add_u32_e32 v72, s2, v77
	ds_read_b128 v[68:71], v72
	ds_read_b128 v[72:75], v72 offset:4096
	ds_read_b128 v[80:83], v79 offset:20480
	v_add_u32_e32 v77, s2, v78
	s_waitcnt lgkmcnt(0)
	v_mfma_f32_32x32x16_bf16 v[48:63], v[64:67], v[68:71], v[48:63]
	v_mfma_f32_32x32x16_bf16 v[16:31], v[64:67], v[72:75], v[16:31]
	ds_read_b128 v[64:67], v77 offset:16384
	v_mfma_f32_32x32x16_bf16 v[32:47], v[80:83], v[68:71], v[32:47]
	v_mfma_f32_32x32x16_bf16 v[0:15], v[80:83], v[72:75], v[0:15]
	v_add_u32_e32 v72, s2, v76
	ds_read_b128 v[68:71], v72
	ds_read_b128 v[72:75], v72 offset:4096
	ds_read_b128 v[76:79], v77 offset:20480
	s_waitcnt vmcnt(0) lgkmcnt(0)
	s_barrier
	s_waitcnt lgkmcnt(0)
	v_mfma_f32_32x32x16_bf16 v[48:63], v[64:67], v[68:71], v[48:63]
	v_mfma_f32_32x32x16_bf16 v[16:31], v[64:67], v[72:75], v[16:31]
	v_mfma_f32_32x32x16_bf16 v[32:47], v[76:79], v[68:71], v[32:47]
	v_mfma_f32_32x32x16_bf16 v[0:15], v[76:79], v[72:75], v[0:15]

; DEV int stage_next(int s) { return (s == 2 * GS_STAGE) ? 0 : s + GS_STAGE; }
; template <int WAIT0>
; DEV void gk_main(f32x16 (&acc)[2][2], const GTile& t, int s0) {
;     ...
;   vm_wait_bar<WAIT0>();
;   int stc = s0, std_ = stage_next(stage_next(s0));
; #pragma nounroll
;   for (int kt = 0; kt < nk - 2; ++kt) {
;     GK_DMA(std_, kt + 2);
;     GK_COMPUTE(stc);
;     vm_wait_bar<6>();
;     stc = stage_next(stc); std_ = stage_next(std_);
;   }
.LBB0_719:
	s_add_i32 s14, s3, s13
	s_mov_b32 s98, s14
	s_mov_b64 s[100:101], s[6:7]
	s_add_i32 s15, s2, 0
	v_add_u32_e32 v253, s15, v81
	v_add_u32_e32 v252, s15, v83
	ds_read_b128 v[84:87], v252 offset:16384
	ds_read_b128 v[88:91], v253
	ds_read_b128 v[92:95], v253 offset:4096
	ds_read_b128 v[96:99], v252 offset:20480
	s_waitcnt lgkmcnt(0)
	v_add_u32_e32 v101, s15, v82
	v_add_u32_e32 v100, s15, v79
	s_add_i32 s14, s2, 0xc000
	s_cmp_lg_u32 s2, 0x18000
	s_cselect_b32 s2, s14, 0
	s_add_i32 s14, s13, 0xc000
	s_cmp_lg_u32 s13, 0x18000
	s_cselect_b32 s13, s14, 0
	s_add_u32 s6, s6, 0x80
	s_addc_u32 s7, s7, 0
	ds_read_b128 v[236:239], v101 offset:16384
	ds_read_b128 v[240:243], v100
	ds_read_b128 v[244:247], v100 offset:4096
	ds_read_b128 v[248:251], v101 offset:20480
	v_mfma_f32_32x32x16_bf16 v[48:63], v[84:87], v[88:91], v[48:63]
	v_mfma_f32_32x32x16_bf16 v[16:31], v[84:87], v[92:95], v[16:31]
	s_mov_b32 m0, s98
	v_lshl_add_u64 v[254:255], v[74:75], 0, s[100:101]
	global_load_lds_dwordx4 v[254:255], off
	v_mfma_f32_32x32x16_bf16 v[32:47], v[96:99], v[88:91], v[32:47]
	v_mfma_f32_32x32x16_bf16 v[0:15], v[96:99], v[92:95], v[0:15]
	s_add_i32 m0, s98, 0x2000
	v_lshl_add_u64 v[254:255], v[72:73], 0, s[100:101]
	global_load_lds_dwordx4 v[254:255], off
	v_add_u32_e32 v101, s15, v80
	v_add_u32_e32 v100, s15, v77
	s_waitcnt lgkmcnt(0)
	ds_read_b128 v[84:87], v101 offset:16384
	ds_read_b128 v[88:91], v100
	ds_read_b128 v[92:95], v100 offset:4096
	ds_read_b128 v[96:99], v101 offset:20480
	v_mfma_f32_32x32x16_bf16 v[48:63], v[236:239], v[240:243], v[48:63]
	v_mfma_f32_32x32x16_bf16 v[16:31], v[236:239], v[244:247], v[16:31]
	s_add_i32 m0, s98, 0x4000
	v_lshl_add_u64 v[254:255], v[70:71], 0, s[100:101]
	global_load_lds_dwordx4 v[254:255], off
	v_mfma_f32_32x32x16_bf16 v[32:47], v[248:251], v[240:243], v[32:47]
	v_mfma_f32_32x32x16_bf16 v[0:15], v[248:251], v[244:247], v[0:15]
	s_add_i32 m0, s98, 0x6000
	v_lshl_add_u64 v[254:255], v[68:69], 0, s[100:101]
	global_load_lds_dwordx4 v[254:255], off
	v_add_u32_e32 v101, s15, v78
	v_add_u32_e32 v100, s15, v76
	s_waitcnt lgkmcnt(0)
	ds_read_b128 v[236:239], v101 offset:16384
	ds_read_b128 v[240:243], v100
	ds_read_b128 v[244:247], v100 offset:4096
	ds_read_b128 v[248:251], v101 offset:20480
	v_mfma_f32_32x32x16_bf16 v[48:63], v[84:87], v[88:91], v[48:63]
	v_mfma_f32_32x32x16_bf16 v[16:31], v[84:87], v[92:95], v[16:31]
	s_add_i32 m0, s98, 0x8000
	v_lshl_add_u64 v[254:255], v[66:67], 0, s[100:101]
	global_load_lds_dwordx4 v[254:255], off
	v_mfma_f32_32x32x16_bf16 v[32:47], v[96:99], v[88:91], v[32:47]
	v_mfma_f32_32x32x16_bf16 v[0:15], v[96:99], v[92:95], v[0:15]
	s_add_i32 m0, s98, 0xa000
	v_lshl_add_u64 v[254:255], v[64:65], 0, s[100:101]
	global_load_lds_dwordx4 v[254:255], off
	s_waitcnt vmcnt(6) lgkmcnt(0)
	s_barrier
	s_waitcnt lgkmcnt(0)
	v_mfma_f32_32x32x16_bf16 v[48:63], v[236:239], v[240:243], v[48:63]
	v_mfma_f32_32x32x16_bf16 v[16:31], v[236:239], v[244:247], v[16:31]
	v_mfma_f32_32x32x16_bf16 v[32:47], v[248:251], v[240:243], v[32:47]
	v_mfma_f32_32x32x16_bf16 v[0:15], v[248:251], v[244:247], v[0:15]
	s_cmpk_lg_i32 s6, 0x700
	s_cbranch_scc1 .LBB0_719
; DEV int stage_next(int s) { return (s == 2 * GS_STAGE) ? 0 : s + GS_STAGE; }
; template <int WAIT0>
; DEV void gk_main(f32x16 (&acc)[2][2], const GTile& t, int s0) {
;     ...
;   GK_COMPUTE(stc);
;   vm_wait_bar<0>();
;   stc = stage_next(stc);
;   GK_COMPUTE(stc);
;   vm_wait_bar<0>();
	s_add_i32 s3, s2, 0
	v_add_u32_e32 v84, s3, v83
	ds_read_b128 v[64:67], v84 offset:16384
	v_add_u32_e32 v72, s3, v81
	ds_read_b128 v[68:71], v72
	ds_read_b128 v[72:75], v72 offset:4096
	ds_read_b128 v[84:87], v84 offset:20480
	s_waitcnt lgkmcnt(0)
	v_mfma_f32_32x32x16_bf16 v[32:47], v[84:87], v[68:71], v[32:47]
	v_mfma_f32_32x32x16_bf16 v[0:15], v[84:87], v[72:75], v[0:15]
	v_add_u32_e32 v84, s3, v82
	v_mfma_f32_32x32x16_bf16 v[48:63], v[64:67], v[68:71], v[48:63]
	v_mfma_f32_32x32x16_bf16 v[16:31], v[64:67], v[72:75], v[16:31]
	ds_read_b128 v[64:67], v84 offset:16384
	v_add_u32_e32 v72, s3, v79
	ds_read_b128 v[68:71], v72
	ds_read_b128 v[72:75], v72 offset:4096
	ds_read_b128 v[84:87], v84 offset:20480
	s_waitcnt lgkmcnt(0)
	v_mfma_f32_32x32x16_bf16 v[32:47], v[84:87], v[68:71], v[32:47]
	v_mfma_f32_32x32x16_bf16 v[0:15], v[84:87], v[72:75], v[0:15]
	v_add_u32_e32 v84, s3, v80
	v_mfma_f32_32x32x16_bf16 v[48:63], v[64:67], v[68:71], v[48:63]
	v_mfma_f32_32x32x16_bf16 v[16:31], v[64:67], v[72:75], v[16:31]
	ds_read_b128 v[64:67], v84 offset:16384
	v_add_u32_e32 v72, s3, v77
	ds_read_b128 v[68:71], v72
	ds_read_b128 v[72:75], v72 offset:4096
	ds_read_b128 v[84:87], v84 offset:20480
	s_waitcnt lgkmcnt(0)
	v_mfma_f32_32x32x16_bf16 v[32:47], v[84:87], v[68:71], v[32:47]
	v_mfma_f32_32x32x16_bf16 v[0:15], v[84:87], v[72:75], v[0:15]
	v_add_u32_e32 v84, s3, v78
	v_mfma_f32_32x32x16_bf16 v[48:63], v[64:67], v[68:71], v[48:63]
	v_mfma_f32_32x32x16_bf16 v[16:31], v[64:67], v[72:75], v[16:31]
	ds_read_b128 v[64:67], v84 offset:16384
	v_add_u32_e32 v72, s3, v76
	s_add_i32 s3, s2, 0xc000
	ds_read_b128 v[68:71], v72
	ds_read_b128 v[72:75], v72 offset:4096
	ds_read_b128 v[84:87], v84 offset:20480
	s_cmp_lg_u32 s2, 0x18000
	s_cselect_b32 s2, s3, 0
	s_add_i32 s2, s2, 0
	s_waitcnt vmcnt(0) lgkmcnt(0)
	s_barrier
	v_add_u32_e32 v83, s2, v83
	s_waitcnt lgkmcnt(0)
	v_mfma_f32_32x32x16_bf16 v[48:63], v[64:67], v[68:71], v[48:63]
	v_mfma_f32_32x32x16_bf16 v[16:31], v[64:67], v[72:75], v[16:31]
	ds_read_b128 v[64:67], v83 offset:16384
	v_mfma_f32_32x32x16_bf16 v[32:47], v[84:87], v[68:71], v[32:47]
	v_mfma_f32_32x32x16_bf16 v[0:15], v[84:87], v[72:75], v[0:15]
	v_add_u32_e32 v72, s2, v81
	ds_read_b128 v[68:71], v72
	ds_read_b128 v[72:75], v72 offset:4096
	ds_read_b128 v[84:87], v83 offset:20480
	v_add_u32_e32 v81, s2, v82
	s_waitcnt lgkmcnt(0)
	v_mfma_f32_32x32x16_bf16 v[48:63], v[64:67], v[68:71], v[48:63]
	v_mfma_f32_32x32x16_bf16 v[16:31], v[64:67], v[72:75], v[16:31]
	ds_read_b128 v[64:67], v81 offset:16384
	v_mfma_f32_32x32x16_bf16 v[32:47], v[84:87], v[68:71], v[32:47]
	v_mfma_f32_32x32x16_bf16 v[0:15], v[84:87], v[72:75], v[0:15]
	v_add_u32_e32 v72, s2, v79
	ds_read_b128 v[68:71], v72
	ds_read_b128 v[72:75], v72 offset:4096
	ds_read_b128 v[82:85], v81 offset:20480
	v_add_u32_e32 v79, s2, v80
	s_waitcnt lgkmcnt(0)
	v_mfma_f32_32x32x16_bf16 v[48:63], v[64:67], v[68:71], v[48:63]
	v_mfma_f32_32x32x16_bf16 v[16:31], v[64:67], v[72:75], v[16:31]
	ds_read_b128 v[64:67], v79 offset:16384
	v_mfma_f32_32x32x16_bf16 v[32:47], v[82:85], v[68:71], v[32:47]
	v_mfma_f32_32x32x16_bf16 v[0:15], v[82:85], v[72:75], v[0:15]
	v_add_u32_e32 v72, s2, v77
	ds_read_b128 v[68:71], v72
	ds_read_b128 v[72:75], v72 offset:4096
	ds_read_b128 v[80:83], v79 offset:20480
	v_add_u32_e32 v77, s2, v78
	s_waitcnt lgkmcnt(0)
	v_mfma_f32_32x32x16_bf16 v[48:63], v[64:67], v[68:71], v[48:63]
	v_mfma_f32_32x32x16_bf16 v[16:31], v[64:67], v[72:75], v[16:31]
	ds_read_b128 v[64:67], v77 offset:16384
	v_mfma_f32_32x32x16_bf16 v[32:47], v[80:83], v[68:71], v[32:47]
	v_mfma_f32_32x32x16_bf16 v[0:15], v[80:83], v[72:75], v[0:15]
	v_add_u32_e32 v72, s2, v76
	ds_read_b128 v[68:71], v72
	ds_read_b128 v[72:75], v72 offset:4096
	ds_read_b128 v[76:79], v77 offset:20480
	s_waitcnt vmcnt(0) lgkmcnt(0)
	s_barrier
	s_waitcnt lgkmcnt(0)
	v_mfma_f32_32x32x16_bf16 v[48:63], v[64:67], v[68:71], v[48:63]
	v_mfma_f32_32x32x16_bf16 v[16:31], v[64:67], v[72:75], v[16:31]
	v_mfma_f32_32x32x16_bf16 v[32:47], v[76:79], v[68:71], v[32:47]
	v_mfma_f32_32x32x16_bf16 v[0:15], v[76:79], v[72:75], v[0:15]

; DEV int stage_next(int s) { return (s == 2 * GS_STAGE) ? 0 : s + GS_STAGE; }
; template <int WAIT0>
; DEV void gk_main(f32x16 (&acc)[2][2], const GTile& t, int s0) {
;     ...
;   vm_wait_bar<WAIT0>();
;   int stc = s0, std_ = stage_next(stage_next(s0));
; #pragma nounroll
;   for (int kt = 0; kt < nk - 2; ++kt) {
;     GK_DMA(std_, kt + 2);
;     GK_COMPUTE(stc);
;     vm_wait_bar<6>();
;     stc = stage_next(stc); std_ = stage_next(std_);
;   }
.LBB0_725:
	s_add_i32 s14, s3, s13
	s_mov_b32 s98, s14
	s_mov_b64 s[100:101], s[6:7]
	s_add_i32 s15, s2, 0
	v_add_u32_e32 v253, s15, v81
	v_add_u32_e32 v252, s15, v83
	ds_read_b128 v[84:87], v252 offset:16384
	ds_read_b128 v[88:91], v253
	ds_read_b128 v[92:95], v253 offset:4096
	ds_read_b128 v[96:99], v252 offset:20480
	s_waitcnt lgkmcnt(0)
	v_add_u32_e32 v101, s15, v82
	v_add_u32_e32 v100, s15, v79
	s_add_i32 s14, s2, 0xc000
	s_cmp_lg_u32 s2, 0x18000
	s_cselect_b32 s2, s14, 0
	s_add_i32 s14, s13, 0xc000
	s_cmp_lg_u32 s13, 0x18000
	s_cselect_b32 s13, s14, 0
	s_add_u32 s6, s6, 0x80
	s_addc_u32 s7, s7, 0
	ds_read_b128 v[236:239], v101 offset:16384
	ds_read_b128 v[240:243], v100
	ds_read_b128 v[244:247], v100 offset:4096
	ds_read_b128 v[248:251], v101 offset:20480
	v_mfma_f32_32x32x16_bf16 v[48:63], v[84:87], v[88:91], v[48:63]
	v_mfma_f32_32x32x16_bf16 v[16:31], v[84:87], v[92:95], v[16:31]
	s_mov_b32 m0, s98
	v_lshl_add_u64 v[254:255], v[74:75], 0, s[100:101]
	global_load_lds_dwordx4 v[254:255], off
	v_mfma_f32_32x32x16_bf16 v[32:47], v[96:99], v[88:91], v[32:47]
	v_mfma_f32_32x32x16_bf16 v[0:15], v[96:99], v[92:95], v[0:15]
	s_add_i32 m0, s98, 0x2000
	v_lshl_add_u64 v[254:255], v[72:73], 0, s[100:101]
	global_load_lds_dwordx4 v[254:255], off
	v_add_u32_e32 v101, s15, v80
	v_add_u32_e32 v100, s15, v77
	s_waitcnt lgkmcnt(0)
	ds_read_b128 v[84:87], v101 offset:16384
	ds_read_b128 v[88:91], v100
	ds_read_b128 v[92:95], v100 offset:4096
	ds_read_b128 v[96:99], v101 offset:20480
	v_mfma_f32_32x32x16_bf16 v[48:63], v[236:239], v[240:243], v[48:63]
	v_mfma_f32_32x32x16_bf16 v[16:31], v[236:239], v[244:247], v[16:31]
	s_add_i32 m0, s98, 0x4000
	v_lshl_add_u64 v[254:255], v[70:71], 0, s[100:101]
	global_load_lds_dwordx4 v[254:255], off
	v_mfma_f32_32x32x16_bf16 v[32:47], v[248:251], v[240:243], v[32:47]
	v_mfma_f32_32x32x16_bf16 v[0:15], v[248:251], v[244:247], v[0:15]
	s_add_i32 m0, s98, 0x6000
	v_lshl_add_u64 v[254:255], v[68:69], 0, s[100:101]
	global_load_lds_dwordx4 v[254:255], off
	v_add_u32_e32 v101, s15, v78
	v_add_u32_e32 v100, s15, v76
	s_waitcnt lgkmcnt(0)
	ds_read_b128 v[236:239], v101 offset:16384
	ds_read_b128 v[240:243], v100
	ds_read_b128 v[244:247], v100 offset:4096
	ds_read_b128 v[248:251], v101 offset:20480
	v_mfma_f32_32x32x16_bf16 v[48:63], v[84:87], v[88:91], v[48:63]
	v_mfma_f32_32x32x16_bf16 v[16:31], v[84:87], v[92:95], v[16:31]
	s_add_i32 m0, s98, 0x8000
	v_lshl_add_u64 v[254:255], v[66:67], 0, s[100:101]
	global_load_lds_dwordx4 v[254:255], off
	v_mfma_f32_32x32x16_bf16 v[32:47], v[96:99], v[88:91], v[32:47]
	v_mfma_f32_32x32x16_bf16 v[0:15], v[96:99], v[92:95], v[0:15]
	s_add_i32 m0, s98, 0xa000
	v_lshl_add_u64 v[254:255], v[64:65], 0, s[100:101]
	global_load_lds_dwordx4 v[254:255], off
	s_waitcnt vmcnt(6) lgkmcnt(0)
	s_barrier
	s_waitcnt lgkmcnt(0)
	v_mfma_f32_32x32x16_bf16 v[48:63], v[236:239], v[240:243], v[48:63]
	v_mfma_f32_32x32x16_bf16 v[16:31], v[236:239], v[244:247], v[16:31]
	v_mfma_f32_32x32x16_bf16 v[32:47], v[248:251], v[240:243], v[32:47]
	v_mfma_f32_32x32x16_bf16 v[0:15], v[248:251], v[244:247], v[0:15]
	s_cmpk_lg_i32 s6, 0x700
	s_cbranch_scc1 .LBB0_725
; DEV int stage_next(int s) { return (s == 2 * GS_STAGE) ? 0 : s + GS_STAGE; }
; template <int WAIT0>
; DEV void gk_main(f32x16 (&acc)[2][2], const GTile& t, int s0) {
;     ...
;   GK_COMPUTE(stc);
;   vm_wait_bar<0>();
;   stc = stage_next(stc);
;   GK_COMPUTE(stc);
;   vm_wait_bar<0>();
	s_add_i32 s3, s2, 0
	v_add_u32_e32 v84, s3, v83
	ds_read_b128 v[64:67], v84 offset:16384
	v_add_u32_e32 v72, s3, v81
	ds_read_b128 v[68:71], v72
	ds_read_b128 v[72:75], v72 offset:4096
	ds_read_b128 v[84:87], v84 offset:20480
	s_waitcnt lgkmcnt(0)
	v_mfma_f32_32x32x16_bf16 v[32:47], v[84:87], v[68:71], v[32:47]
	v_mfma_f32_32x32x16_bf16 v[0:15], v[84:87], v[72:75], v[0:15]
	v_add_u32_e32 v84, s3, v82
	v_mfma_f32_32x32x16_bf16 v[48:63], v[64:67], v[68:71], v[48:63]
	v_mfma_f32_32x32x16_bf16 v[16:31], v[64:67], v[72:75], v[16:31]
	ds_read_b128 v[64:67], v84 offset:16384
	v_add_u32_e32 v72, s3, v79
	ds_read_b128 v[68:71], v72
	ds_read_b128 v[72:75], v72 offset:4096
	ds_read_b128 v[84:87], v84 offset:20480
	s_waitcnt lgkmcnt(0)
	v_mfma_f32_32x32x16_bf16 v[32:47], v[84:87], v[68:71], v[32:47]
	v_mfma_f32_32x32x16_bf16 v[0:15], v[84:87], v[72:75], v[0:15]
	v_add_u32_e32 v84, s3, v80
	v_mfma_f32_32x32x16_bf16 v[48:63], v[64:67], v[68:71], v[48:63]
	v_mfma_f32_32x32x16_bf16 v[16:31], v[64:67], v[72:75], v[16:31]
	ds_read_b128 v[64:67], v84 offset:16384
	v_add_u32_e32 v72, s3, v77
	ds_read_b128 v[68:71], v72
	ds_read_b128 v[72:75], v72 offset:4096
	ds_read_b128 v[84:87], v84 offset:20480
	s_waitcnt lgkmcnt(0)
	v_mfma_f32_32x32x16_bf16 v[32:47], v[84:87], v[68:71], v[32:47]
	v_mfma_f32_32x32x16_bf16 v[0:15], v[84:87], v[72:75], v[0:15]
	v_add_u32_e32 v84, s3, v78
	v_mfma_f32_32x32x16_bf16 v[48:63], v[64:67], v[68:71], v[48:63]
	v_mfma_f32_32x32x16_bf16 v[16:31], v[64:67], v[72:75], v[16:31]
	ds_read_b128 v[64:67], v84 offset:16384
	v_add_u32_e32 v72, s3, v76
	s_add_i32 s3, s2, 0xc000
	ds_read_b128 v[68:71], v72
	ds_read_b128 v[72:75], v72 offset:4096
	ds_read_b128 v[84:87], v84 offset:20480
	s_cmp_lg_u32 s2, 0x18000
	s_cselect_b32 s2, s3, 0
	s_add_i32 s2, s2, 0
	s_waitcnt vmcnt(0) lgkmcnt(0)
	s_barrier
	v_add_u32_e32 v83, s2, v83
	s_waitcnt lgkmcnt(0)
	v_mfma_f32_32x32x16_bf16 v[48:63], v[64:67], v[68:71], v[48:63]
	v_mfma_f32_32x32x16_bf16 v[16:31], v[64:67], v[72:75], v[16:31]
	ds_read_b128 v[64:67], v83 offset:16384
	v_mfma_f32_32x32x16_bf16 v[32:47], v[84:87], v[68:71], v[32:47]
	v_mfma_f32_32x32x16_bf16 v[0:15], v[84:87], v[72:75], v[0:15]
	v_add_u32_e32 v72, s2, v81
	ds_read_b128 v[68:71], v72
	ds_read_b128 v[72:75], v72 offset:4096
	ds_read_b128 v[84:87], v83 offset:20480
	v_add_u32_e32 v81, s2, v82
	s_waitcnt lgkmcnt(0)
	v_mfma_f32_32x32x16_bf16 v[48:63], v[64:67], v[68:71], v[48:63]
	v_mfma_f32_32x32x16_bf16 v[16:31], v[64:67], v[72:75], v[16:31]
	ds_read_b128 v[64:67], v81 offset:16384
	v_mfma_f32_32x32x16_bf16 v[32:47], v[84:87], v[68:71], v[32:47]
	v_mfma_f32_32x32x16_bf16 v[0:15], v[84:87], v[72:75], v[0:15]
	v_add_u32_e32 v72, s2, v79
	ds_read_b128 v[68:71], v72
	ds_read_b128 v[72:75], v72 offset:4096
	ds_read_b128 v[82:85], v81 offset:20480
	v_add_u32_e32 v79, s2, v80
	s_waitcnt lgkmcnt(0)
	v_mfma_f32_32x32x16_bf16 v[48:63], v[64:67], v[68:71], v[48:63]
	v_mfma_f32_32x32x16_bf16 v[16:31], v[64:67], v[72:75], v[16:31]
	ds_read_b128 v[64:67], v79 offset:16384
	v_mfma_f32_32x32x16_bf16 v[32:47], v[82:85], v[68:71], v[32:47]
	v_mfma_f32_32x32x16_bf16 v[0:15], v[82:85], v[72:75], v[0:15]
	v_add_u32_e32 v72, s2, v77
	ds_read_b128 v[68:71], v72
	ds_read_b128 v[72:75], v72 offset:4096
	ds_read_b128 v[80:83], v79 offset:20480
	v_add_u32_e32 v77, s2, v78
	s_waitcnt lgkmcnt(0)
	v_mfma_f32_32x32x16_bf16 v[48:63], v[64:67], v[68:71], v[48:63]
	v_mfma_f32_32x32x16_bf16 v[16:31], v[64:67], v[72:75], v[16:31]
	ds_read_b128 v[64:67], v77 offset:16384
	v_mfma_f32_32x32x16_bf16 v[32:47], v[80:83], v[68:71], v[32:47]
	v_mfma_f32_32x32x16_bf16 v[0:15], v[80:83], v[72:75], v[0:15]
	v_add_u32_e32 v72, s2, v76
	ds_read_b128 v[68:71], v72
	ds_read_b128 v[72:75], v72 offset:4096
	ds_read_b128 v[76:79], v77 offset:20480
	s_waitcnt vmcnt(0) lgkmcnt(0)
	s_barrier
	s_waitcnt lgkmcnt(0)
	v_mfma_f32_32x32x16_bf16 v[48:63], v[64:67], v[68:71], v[48:63]
	v_mfma_f32_32x32x16_bf16 v[16:31], v[64:67], v[72:75], v[16:31]
	v_mfma_f32_32x32x16_bf16 v[32:47], v[76:79], v[68:71], v[32:47]
	v_mfma_f32_32x32x16_bf16 v[0:15], v[76:79], v[72:75], v[0:15]
	s_add_i32 s2, s12, 1
	s_cmp_eq_u32 s12, 3
	s_cbranch_scc1 .LBB0_711

; DEV int stage_next(int s) { return (s == 2 * GS_STAGE) ? 0 : s + GS_STAGE; }
; template <int WAIT0>
; DEV void gk_main(f32x16 (&acc)[2][2], const GTile& t, int s0) {
;     ...
;   vm_wait_bar<WAIT0>();
;   int stc = s0, std_ = stage_next(stage_next(s0));
; #pragma nounroll
;   for (int kt = 0; kt < nk - 2; ++kt) {
;     GK_DMA(std_, kt + 2);
;     GK_COMPUTE(stc);
;     vm_wait_bar<6>();
;     stc = stage_next(stc); std_ = stage_next(std_);
;   }
.LBB0_737:
	s_add_i32 s20, s3, s19
	s_mov_b32 s98, s20
	s_mov_b64 s[100:101], s[10:11]
	s_add_i32 s21, s2, 0
	v_add_u32_e32 v252, s21, v86
	v_add_u32_e32 v87, s21, v84
	ds_read_b128 v[88:91], v252 offset:16384
	ds_read_b128 v[92:95], v87
	ds_read_b128 v[96:99], v87 offset:4096
	ds_read_b128 v[100:103], v252 offset:20480
	s_waitcnt lgkmcnt(0)
	v_add_u32_e32 v104, s21, v85
	v_add_u32_e32 v87, s21, v82
	s_add_i32 s20, s2, 0xc000
	s_cmp_lg_u32 s2, 0x18000
	s_cselect_b32 s2, s20, 0
	s_add_i32 s20, s19, 0xc000
	s_cmp_lg_u32 s19, 0x18000
	s_cselect_b32 s19, s20, 0
	s_add_u32 s10, s10, 0x80
	s_addc_u32 s11, s11, 0
	ds_read_b128 v[236:239], v104 offset:16384
	ds_read_b128 v[240:243], v87
	ds_read_b128 v[244:247], v87 offset:4096
	ds_read_b128 v[248:251], v104 offset:20480
	v_mfma_f32_32x32x16_bf16 v[48:63], v[88:91], v[92:95], v[48:63]
	v_mfma_f32_32x32x16_bf16 v[32:47], v[88:91], v[96:99], v[32:47]
	s_mov_b32 m0, s98
	v_lshl_add_u64 v[254:255], v[76:77], 0, s[100:101]
	global_load_lds_dwordx4 v[254:255], off
	v_mfma_f32_32x32x16_bf16 v[16:31], v[100:103], v[92:95], v[16:31]
	v_mfma_f32_32x32x16_bf16 v[0:15], v[100:103], v[96:99], v[0:15]
	s_add_i32 m0, s98, 0x2000
	v_lshl_add_u64 v[254:255], v[74:75], 0, s[100:101]
	global_load_lds_dwordx4 v[254:255], off
	v_add_u32_e32 v104, s21, v83
	v_add_u32_e32 v87, s21, v80
	s_waitcnt lgkmcnt(0)
	ds_read_b128 v[88:91], v104 offset:16384
	ds_read_b128 v[92:95], v87
	ds_read_b128 v[96:99], v87 offset:4096
	ds_read_b128 v[100:103], v104 offset:20480
	v_mfma_f32_32x32x16_bf16 v[48:63], v[236:239], v[240:243], v[48:63]
	v_mfma_f32_32x32x16_bf16 v[32:47], v[236:239], v[244:247], v[32:47]
	s_add_i32 m0, s98, 0x4000
	v_lshl_add_u64 v[254:255], v[72:73], 0, s[100:101]
	global_load_lds_dwordx4 v[254:255], off
	v_mfma_f32_32x32x16_bf16 v[16:31], v[248:251], v[240:243], v[16:31]
	v_mfma_f32_32x32x16_bf16 v[0:15], v[248:251], v[244:247], v[0:15]
	s_add_i32 m0, s98, 0x6000
	v_lshl_add_u64 v[254:255], v[70:71], 0, s[100:101]
	global_load_lds_dwordx4 v[254:255], off
	v_add_u32_e32 v104, s21, v81
	v_add_u32_e32 v87, s21, v79
	s_waitcnt lgkmcnt(0)
	ds_read_b128 v[236:239], v104 offset:16384
	ds_read_b128 v[240:243], v87
	ds_read_b128 v[244:247], v87 offset:4096
	ds_read_b128 v[248:251], v104 offset:20480
	v_mfma_f32_32x32x16_bf16 v[48:63], v[88:91], v[92:95], v[48:63]
	v_mfma_f32_32x32x16_bf16 v[32:47], v[88:91], v[96:99], v[32:47]
	s_add_i32 m0, s98, 0x8000
	v_lshl_add_u64 v[254:255], v[68:69], 0, s[100:101]
	global_load_lds_dwordx4 v[254:255], off
	v_mfma_f32_32x32x16_bf16 v[16:31], v[100:103], v[92:95], v[16:31]
	v_mfma_f32_32x32x16_bf16 v[0:15], v[100:103], v[96:99], v[0:15]
	s_add_i32 m0, s98, 0xa000
	v_lshl_add_u64 v[254:255], v[66:67], 0, s[100:101]
	global_load_lds_dwordx4 v[254:255], off
	s_waitcnt vmcnt(6) lgkmcnt(0)
	s_barrier
	s_waitcnt lgkmcnt(0)
	v_mfma_f32_32x32x16_bf16 v[48:63], v[236:239], v[240:243], v[48:63]
	v_mfma_f32_32x32x16_bf16 v[32:47], v[236:239], v[244:247], v[32:47]
	v_mfma_f32_32x32x16_bf16 v[16:31], v[248:251], v[240:243], v[16:31]
	v_mfma_f32_32x32x16_bf16 v[0:15], v[248:251], v[244:247], v[0:15]
	s_cmpk_lg_i32 s10, 0x700
	s_cbranch_scc1 .LBB0_737
; DEV int stage_next(int s) { return (s == 2 * GS_STAGE) ? 0 : s + GS_STAGE; }
; template <int WAIT0>
; DEV void gk_main(f32x16 (&acc)[2][2], const GTile& t, int s0) {
;     ...
;   GK_COMPUTE(stc);
;   vm_wait_bar<0>();
;   stc = stage_next(stc);
;   GK_COMPUTE(stc);
;   vm_wait_bar<0>();
	s_add_i32 s3, s2, 0
	v_add_u32_e32 v87, s3, v86
	ds_read_b128 v[66:69], v87 offset:16384
	v_add_u32_e32 v74, s3, v84
	ds_read_b128 v[70:73], v74
	ds_read_b128 v[74:77], v74 offset:4096
	ds_read_b128 v[88:91], v87 offset:20480
	v_add_u32_e32 v87, s3, v85
	s_mov_b64 s[10:11], 0
	s_waitcnt lgkmcnt(0)
	v_mfma_f32_32x32x16_bf16 v[0:15], v[88:91], v[74:77], v[0:15]
	v_mfma_f32_32x32x16_bf16 v[48:63], v[66:69], v[70:73], v[48:63]
	v_mfma_f32_32x32x16_bf16 v[32:47], v[66:69], v[74:77], v[32:47]
	ds_read_b128 v[66:69], v87 offset:16384
	v_add_u32_e32 v74, s3, v82
	v_mfma_f32_32x32x16_bf16 v[16:31], v[88:91], v[70:73], v[16:31]
	ds_read_b128 v[70:73], v74
	ds_read_b128 v[74:77], v74 offset:4096
	ds_read_b128 v[88:91], v87 offset:20480
	v_add_u32_e32 v87, s3, v83
	s_waitcnt lgkmcnt(0)
	v_mfma_f32_32x32x16_bf16 v[48:63], v[66:69], v[70:73], v[48:63]
	v_mfma_f32_32x32x16_bf16 v[32:47], v[66:69], v[74:77], v[32:47]
	ds_read_b128 v[66:69], v87 offset:16384
	v_mfma_f32_32x32x16_bf16 v[0:15], v[88:91], v[74:77], v[0:15]
	v_add_u32_e32 v74, s3, v80
	v_mfma_f32_32x32x16_bf16 v[16:31], v[88:91], v[70:73], v[16:31]
	ds_read_b128 v[70:73], v74
	ds_read_b128 v[74:77], v74 offset:4096
	ds_read_b128 v[88:91], v87 offset:20480
	v_add_u32_e32 v87, s3, v81
	s_waitcnt lgkmcnt(0)
	v_mfma_f32_32x32x16_bf16 v[48:63], v[66:69], v[70:73], v[48:63]
	v_mfma_f32_32x32x16_bf16 v[32:47], v[66:69], v[74:77], v[32:47]
	ds_read_b128 v[66:69], v87 offset:16384
	v_mfma_f32_32x32x16_bf16 v[0:15], v[88:91], v[74:77], v[0:15]
	v_add_u32_e32 v74, s3, v79
	s_add_i32 s3, s2, 0xc000
	s_cmp_lg_u32 s2, 0x18000
	s_cselect_b32 s2, s3, 0
	s_add_i32 s2, s2, 0
	v_add_u32_e32 v86, s2, v86
	v_mfma_f32_32x32x16_bf16 v[16:31], v[88:91], v[70:73], v[16:31]
	ds_read_b128 v[70:73], v74
	ds_read_b128 v[74:77], v74 offset:4096
	ds_read_b128 v[88:91], v87 offset:20480
	s_waitcnt vmcnt(0) lgkmcnt(0)
	s_barrier
	s_waitcnt lgkmcnt(0)
	v_mfma_f32_32x32x16_bf16 v[48:63], v[66:69], v[70:73], v[48:63]
	v_mfma_f32_32x32x16_bf16 v[32:47], v[66:69], v[74:77], v[32:47]
	ds_read_b128 v[66:69], v86 offset:16384
	v_mfma_f32_32x32x16_bf16 v[16:31], v[88:91], v[70:73], v[16:31]
	v_mfma_f32_32x32x16_bf16 v[0:15], v[88:91], v[74:77], v[0:15]
	v_add_u32_e32 v74, s2, v84
	ds_read_b128 v[70:73], v74
	ds_read_b128 v[74:77], v74 offset:4096
	ds_read_b128 v[86:89], v86 offset:20480
	v_add_u32_e32 v84, s2, v85
	s_waitcnt lgkmcnt(0)
	v_mfma_f32_32x32x16_bf16 v[48:63], v[66:69], v[70:73], v[48:63]
	v_mfma_f32_32x32x16_bf16 v[32:47], v[66:69], v[74:77], v[32:47]
	ds_read_b128 v[66:69], v84 offset:16384
	v_mfma_f32_32x32x16_bf16 v[16:31], v[86:89], v[70:73], v[16:31]
	v_mfma_f32_32x32x16_bf16 v[0:15], v[86:89], v[74:77], v[0:15]
	v_add_u32_e32 v74, s2, v82
	ds_read_b128 v[70:73], v74
	ds_read_b128 v[74:77], v74 offset:4096
	ds_read_b128 v[84:87], v84 offset:20480
	v_add_u32_e32 v82, s2, v83
	s_waitcnt lgkmcnt(0)
	v_mfma_f32_32x32x16_bf16 v[48:63], v[66:69], v[70:73], v[48:63]
	v_mfma_f32_32x32x16_bf16 v[32:47], v[66:69], v[74:77], v[32:47]
	ds_read_b128 v[66:69], v82 offset:16384
	v_mfma_f32_32x32x16_bf16 v[16:31], v[84:87], v[70:73], v[16:31]
	v_mfma_f32_32x32x16_bf16 v[0:15], v[84:87], v[74:77], v[0:15]
	v_add_u32_e32 v74, s2, v80
	ds_read_b128 v[70:73], v74
	ds_read_b128 v[74:77], v74 offset:4096
	ds_read_b128 v[82:85], v82 offset:20480
	v_add_u32_e32 v80, s2, v81
	s_waitcnt lgkmcnt(0)
	v_mfma_f32_32x32x16_bf16 v[48:63], v[66:69], v[70:73], v[48:63]
	v_mfma_f32_32x32x16_bf16 v[32:47], v[66:69], v[74:77], v[32:47]
	ds_read_b128 v[66:69], v80 offset:16384
	v_mfma_f32_32x32x16_bf16 v[16:31], v[82:85], v[70:73], v[16:31]
	v_mfma_f32_32x32x16_bf16 v[0:15], v[82:85], v[74:77], v[0:15]
	v_add_u32_e32 v74, s2, v79
	ds_read_b128 v[70:73], v74
	ds_read_b128 v[74:77], v74 offset:4096
	ds_read_b128 v[80:83], v80 offset:20480
	s_waitcnt vmcnt(0) lgkmcnt(0)
	s_barrier
	s_waitcnt lgkmcnt(0)
	v_mfma_f32_32x32x16_bf16 v[48:63], v[66:69], v[70:73], v[48:63]
	v_mfma_f32_32x32x16_bf16 v[32:47], v[66:69], v[74:77], v[32:47]
	v_mfma_f32_32x32x16_bf16 v[16:31], v[80:83], v[70:73], v[16:31]
	v_mfma_f32_32x32x16_bf16 v[0:15], v[80:83], v[74:77], v[0:15]

; DEV int stage_next(int s) { return (s == 2 * GS_STAGE) ? 0 : s + GS_STAGE; }
; template <int WAIT0>
; DEV void gk_main(f32x16 (&acc)[2][2], const GTile& t, int s0) {
;     ...
;   vm_wait_bar<WAIT0>();
;   int stc = s0, std_ = stage_next(stage_next(s0));
; #pragma nounroll
;   for (int kt = 0; kt < nk - 2; ++kt) {
;     GK_DMA(std_, kt + 2);
;     GK_COMPUTE(stc);
;     vm_wait_bar<6>();
;     stc = stage_next(stc); std_ = stage_next(std_);
;   }
.LBB0_741:
	s_add_i32 s20, s3, s19
	s_mov_b32 s98, s20
	s_mov_b64 s[100:101], s[10:11]
	s_add_i32 s21, s2, 0
	v_add_u32_e32 v252, s21, v86
	v_add_u32_e32 v87, s21, v84
	ds_read_b128 v[88:91], v252 offset:16384
	ds_read_b128 v[92:95], v87
	ds_read_b128 v[96:99], v87 offset:4096
	ds_read_b128 v[100:103], v252 offset:20480
	s_waitcnt lgkmcnt(0)
	v_add_u32_e32 v104, s21, v85
	v_add_u32_e32 v87, s21, v82
	s_add_i32 s20, s2, 0xc000
	s_cmp_lg_u32 s2, 0x18000
	s_cselect_b32 s2, s20, 0
	s_add_i32 s20, s19, 0xc000
	s_cmp_lg_u32 s19, 0x18000
	s_cselect_b32 s19, s20, 0
	s_add_u32 s10, s10, 0x80
	s_addc_u32 s11, s11, 0
	ds_read_b128 v[236:239], v104 offset:16384
	ds_read_b128 v[240:243], v87
	ds_read_b128 v[244:247], v87 offset:4096
	ds_read_b128 v[248:251], v104 offset:20480
	v_mfma_f32_32x32x16_bf16 v[48:63], v[88:91], v[92:95], v[48:63]
	v_mfma_f32_32x32x16_bf16 v[32:47], v[88:91], v[96:99], v[32:47]
	s_mov_b32 m0, s98
	v_lshl_add_u64 v[254:255], v[76:77], 0, s[100:101]
	global_load_lds_dwordx4 v[254:255], off
	v_mfma_f32_32x32x16_bf16 v[16:31], v[100:103], v[92:95], v[16:31]
	v_mfma_f32_32x32x16_bf16 v[0:15], v[100:103], v[96:99], v[0:15]
	s_add_i32 m0, s98, 0x2000
	v_lshl_add_u64 v[254:255], v[74:75], 0, s[100:101]
	global_load_lds_dwordx4 v[254:255], off
	v_add_u32_e32 v104, s21, v83
	v_add_u32_e32 v87, s21, v80
	s_waitcnt lgkmcnt(0)
	ds_read_b128 v[88:91], v104 offset:16384
	ds_read_b128 v[92:95], v87
	ds_read_b128 v[96:99], v87 offset:4096
	ds_read_b128 v[100:103], v104 offset:20480
	v_mfma_f32_32x32x16_bf16 v[48:63], v[236:239], v[240:243], v[48:63]
	v_mfma_f32_32x32x16_bf16 v[32:47], v[236:239], v[244:247], v[32:47]
	s_add_i32 m0, s98, 0x4000
	v_lshl_add_u64 v[254:255], v[72:73], 0, s[100:101]
	global_load_lds_dwordx4 v[254:255], off
	v_mfma_f32_32x32x16_bf16 v[16:31], v[248:251], v[240:243], v[16:31]
	v_mfma_f32_32x32x16_bf16 v[0:15], v[248:251], v[244:247], v[0:15]
	s_add_i32 m0, s98, 0x6000
	v_lshl_add_u64 v[254:255], v[70:71], 0, s[100:101]
	global_load_lds_dwordx4 v[254:255], off
	v_add_u32_e32 v104, s21, v81
	v_add_u32_e32 v87, s21, v79
	s_waitcnt lgkmcnt(0)
	ds_read_b128 v[236:239], v104 offset:16384
	ds_read_b128 v[240:243], v87
	ds_read_b128 v[244:247], v87 offset:4096
	ds_read_b128 v[248:251], v104 offset:20480
	v_mfma_f32_32x32x16_bf16 v[48:63], v[88:91], v[92:95], v[48:63]
	v_mfma_f32_32x32x16_bf16 v[32:47], v[88:91], v[96:99], v[32:47]
	s_add_i32 m0, s98, 0x8000
	v_lshl_add_u64 v[254:255], v[68:69], 0, s[100:101]
	global_load_lds_dwordx4 v[254:255], off
	v_mfma_f32_32x32x16_bf16 v[16:31], v[100:103], v[92:95], v[16:31]
	v_mfma_f32_32x32x16_bf16 v[0:15], v[100:103], v[96:99], v[0:15]
	s_add_i32 m0, s98, 0xa000
	v_lshl_add_u64 v[254:255], v[66:67], 0, s[100:101]
	global_load_lds_dwordx4 v[254:255], off
	s_waitcnt vmcnt(6) lgkmcnt(0)
	s_barrier
	s_waitcnt lgkmcnt(0)
	v_mfma_f32_32x32x16_bf16 v[48:63], v[236:239], v[240:243], v[48:63]
	v_mfma_f32_32x32x16_bf16 v[32:47], v[236:239], v[244:247], v[32:47]
	v_mfma_f32_32x32x16_bf16 v[16:31], v[248:251], v[240:243], v[16:31]
	v_mfma_f32_32x32x16_bf16 v[0:15], v[248:251], v[244:247], v[0:15]
	s_cmpk_lg_i32 s10, 0x700
	s_cbranch_scc1 .LBB0_741
; DEV int stage_next(int s) { return (s == 2 * GS_STAGE) ? 0 : s + GS_STAGE; }
; template <int WAIT0>
; DEV void gk_main(f32x16 (&acc)[2][2], const GTile& t, int s0) {
;     ...
;   GK_COMPUTE(stc);
;   vm_wait_bar<0>();
;   stc = stage_next(stc);
;   GK_COMPUTE(stc);
;   vm_wait_bar<0>();
	s_add_i32 s3, s2, 0
	v_add_u32_e32 v87, s3, v86
	ds_read_b128 v[66:69], v87 offset:16384
	v_add_u32_e32 v74, s3, v84
	ds_read_b128 v[70:73], v74
	ds_read_b128 v[74:77], v74 offset:4096
	ds_read_b128 v[88:91], v87 offset:20480
	v_add_u32_e32 v87, s3, v85
	s_waitcnt lgkmcnt(0)
	v_mfma_f32_32x32x16_bf16 v[0:15], v[88:91], v[74:77], v[0:15]
	v_mfma_f32_32x32x16_bf16 v[48:63], v[66:69], v[70:73], v[48:63]
	v_mfma_f32_32x32x16_bf16 v[32:47], v[66:69], v[74:77], v[32:47]
	ds_read_b128 v[66:69], v87 offset:16384
	v_add_u32_e32 v74, s3, v82
	v_mfma_f32_32x32x16_bf16 v[16:31], v[88:91], v[70:73], v[16:31]
	ds_read_b128 v[70:73], v74
	ds_read_b128 v[74:77], v74 offset:4096
	ds_read_b128 v[88:91], v87 offset:20480
	v_add_u32_e32 v87, s3, v83
	s_waitcnt lgkmcnt(0)
	v_mfma_f32_32x32x16_bf16 v[48:63], v[66:69], v[70:73], v[48:63]
	v_mfma_f32_32x32x16_bf16 v[32:47], v[66:69], v[74:77], v[32:47]
	ds_read_b128 v[66:69], v87 offset:16384
	v_mfma_f32_32x32x16_bf16 v[0:15], v[88:91], v[74:77], v[0:15]
	v_add_u32_e32 v74, s3, v80
	v_mfma_f32_32x32x16_bf16 v[16:31], v[88:91], v[70:73], v[16:31]
	ds_read_b128 v[70:73], v74
	ds_read_b128 v[74:77], v74 offset:4096
	ds_read_b128 v[88:91], v87 offset:20480
	v_add_u32_e32 v87, s3, v81
	s_waitcnt lgkmcnt(0)
	v_mfma_f32_32x32x16_bf16 v[48:63], v[66:69], v[70:73], v[48:63]
	v_mfma_f32_32x32x16_bf16 v[32:47], v[66:69], v[74:77], v[32:47]
	ds_read_b128 v[66:69], v87 offset:16384
	v_mfma_f32_32x32x16_bf16 v[0:15], v[88:91], v[74:77], v[0:15]
	v_add_u32_e32 v74, s3, v79
	s_add_i32 s3, s2, 0xc000
	s_cmp_lg_u32 s2, 0x18000
	s_cselect_b32 s2, s3, 0
	s_add_i32 s2, s2, 0
	v_add_u32_e32 v86, s2, v86
	v_mfma_f32_32x32x16_bf16 v[16:31], v[88:91], v[70:73], v[16:31]
	ds_read_b128 v[70:73], v74
	ds_read_b128 v[74:77], v74 offset:4096
	ds_read_b128 v[88:91], v87 offset:20480
	s_waitcnt vmcnt(0) lgkmcnt(0)
	s_barrier
	s_waitcnt lgkmcnt(0)
	v_mfma_f32_32x32x16_bf16 v[48:63], v[66:69], v[70:73], v[48:63]
	v_mfma_f32_32x32x16_bf16 v[32:47], v[66:69], v[74:77], v[32:47]
	ds_read_b128 v[66:69], v86 offset:16384
	v_mfma_f32_32x32x16_bf16 v[16:31], v[88:91], v[70:73], v[16:31]
	v_mfma_f32_32x32x16_bf16 v[0:15], v[88:91], v[74:77], v[0:15]
	v_add_u32_e32 v74, s2, v84
	ds_read_b128 v[70:73], v74
	ds_read_b128 v[74:77], v74 offset:4096
	ds_read_b128 v[86:89], v86 offset:20480
	v_add_u32_e32 v84, s2, v85
	s_waitcnt lgkmcnt(0)
	v_mfma_f32_32x32x16_bf16 v[48:63], v[66:69], v[70:73], v[48:63]
	v_mfma_f32_32x32x16_bf16 v[32:47], v[66:69], v[74:77], v[32:47]
	ds_read_b128 v[66:69], v84 offset:16384
	v_mfma_f32_32x32x16_bf16 v[16:31], v[86:89], v[70:73], v[16:31]
	v_mfma_f32_32x32x16_bf16 v[0:15], v[86:89], v[74:77], v[0:15]
	v_add_u32_e32 v74, s2, v82
	ds_read_b128 v[70:73], v74
	ds_read_b128 v[74:77], v74 offset:4096
	ds_read_b128 v[84:87], v84 offset:20480
	v_add_u32_e32 v82, s2, v83
	s_waitcnt lgkmcnt(0)
	v_mfma_f32_32x32x16_bf16 v[48:63], v[66:69], v[70:73], v[48:63]
	v_mfma_f32_32x32x16_bf16 v[32:47], v[66:69], v[74:77], v[32:47]
	ds_read_b128 v[66:69], v82 offset:16384
	v_mfma_f32_32x32x16_bf16 v[16:31], v[84:87], v[70:73], v[16:31]
	v_mfma_f32_32x32x16_bf16 v[0:15], v[84:87], v[74:77], v[0:15]
	v_add_u32_e32 v74, s2, v80
	ds_read_b128 v[70:73], v74
	ds_read_b128 v[74:77], v74 offset:4096
	ds_read_b128 v[82:85], v82 offset:20480
	v_add_u32_e32 v80, s2, v81
	s_waitcnt lgkmcnt(0)
	v_mfma_f32_32x32x16_bf16 v[48:63], v[66:69], v[70:73], v[48:63]
	v_mfma_f32_32x32x16_bf16 v[32:47], v[66:69], v[74:77], v[32:47]
	ds_read_b128 v[66:69], v80 offset:16384
	v_mfma_f32_32x32x16_bf16 v[16:31], v[82:85], v[70:73], v[16:31]
	v_mfma_f32_32x32x16_bf16 v[0:15], v[82:85], v[74:77], v[0:15]
	v_add_u32_e32 v74, s2, v79
	ds_read_b128 v[70:73], v74
	ds_read_b128 v[74:77], v74 offset:4096
	ds_read_b128 v[80:83], v80 offset:20480
	s_waitcnt vmcnt(0) lgkmcnt(0)
	s_barrier
	s_waitcnt lgkmcnt(0)
	v_mfma_f32_32x32x16_bf16 v[48:63], v[66:69], v[70:73], v[48:63]
	v_mfma_f32_32x32x16_bf16 v[32:47], v[66:69], v[74:77], v[32:47]
	v_mfma_f32_32x32x16_bf16 v[16:31], v[80:83], v[70:73], v[16:31]
	v_mfma_f32_32x32x16_bf16 v[0:15], v[80:83], v[74:77], v[0:15]

; DEV int stage_next(int s) { return (s == 2 * GS_STAGE) ? 0 : s + GS_STAGE; }
; template <int WAIT0>
; DEV void gk_main(f32x16 (&acc)[2][2], const GTile& t, int s0) {
;     ...
;   vm_wait_bar<WAIT0>();
;   int stc = s0, std_ = stage_next(stage_next(s0));
; #pragma nounroll
;   for (int kt = 0; kt < nk - 2; ++kt) {
;     GK_DMA(std_, kt + 2);
;     GK_COMPUTE(stc);
;     vm_wait_bar<6>();
;     stc = stage_next(stc); std_ = stage_next(std_);
;   }
.LBB0_747:
	s_add_i32 s19, s2, s3
	s_mov_b32 s98, s19
	s_mov_b64 s[100:101], s[10:11]
	s_add_i32 s20, s16, 0
	v_add_u32_e32 v252, s20, v86
	v_add_u32_e32 v87, s20, v84
	ds_read_b128 v[88:91], v252 offset:16384
	ds_read_b128 v[92:95], v87
	ds_read_b128 v[96:99], v87 offset:4096
	ds_read_b128 v[100:103], v252 offset:20480
	s_waitcnt lgkmcnt(0)
	v_add_u32_e32 v104, s20, v85
	v_add_u32_e32 v87, s20, v82
	s_add_i32 s19, s16, 0xc000
	s_cmp_lg_u32 s16, 0x18000
	s_cselect_b32 s16, s19, 0
	s_add_i32 s19, s3, 0xc000
	s_cmp_lg_u32 s3, 0x18000
	s_cselect_b32 s3, s19, 0
	s_add_u32 s10, s10, 0x80
	s_addc_u32 s11, s11, 0
	ds_read_b128 v[236:239], v104 offset:16384
	ds_read_b128 v[240:243], v87
	ds_read_b128 v[244:247], v87 offset:4096
	ds_read_b128 v[248:251], v104 offset:20480
	v_mfma_f32_32x32x16_bf16 v[48:63], v[88:91], v[92:95], v[48:63]
	v_mfma_f32_32x32x16_bf16 v[32:47], v[88:91], v[96:99], v[32:47]
	s_mov_b32 m0, s98
	v_lshl_add_u64 v[254:255], v[76:77], 0, s[100:101]
	global_load_lds_dwordx4 v[254:255], off
	v_mfma_f32_32x32x16_bf16 v[16:31], v[100:103], v[92:95], v[16:31]
	v_mfma_f32_32x32x16_bf16 v[0:15], v[100:103], v[96:99], v[0:15]
	s_add_i32 m0, s98, 0x2000
	v_lshl_add_u64 v[254:255], v[74:75], 0, s[100:101]
	global_load_lds_dwordx4 v[254:255], off
	v_add_u32_e32 v104, s20, v83
	v_add_u32_e32 v87, s20, v80
	s_waitcnt lgkmcnt(0)
	ds_read_b128 v[88:91], v104 offset:16384
	ds_read_b128 v[92:95], v87
	ds_read_b128 v[96:99], v87 offset:4096
	ds_read_b128 v[100:103], v104 offset:20480
	v_mfma_f32_32x32x16_bf16 v[48:63], v[236:239], v[240:243], v[48:63]
	v_mfma_f32_32x32x16_bf16 v[32:47], v[236:239], v[244:247], v[32:47]
	s_add_i32 m0, s98, 0x4000
	v_lshl_add_u64 v[254:255], v[72:73], 0, s[100:101]
	global_load_lds_dwordx4 v[254:255], off
	v_mfma_f32_32x32x16_bf16 v[16:31], v[248:251], v[240:243], v[16:31]
	v_mfma_f32_32x32x16_bf16 v[0:15], v[248:251], v[244:247], v[0:15]
	s_add_i32 m0, s98, 0x6000
	v_lshl_add_u64 v[254:255], v[70:71], 0, s[100:101]
	global_load_lds_dwordx4 v[254:255], off
	v_add_u32_e32 v104, s20, v81
	v_add_u32_e32 v87, s20, v79
	s_waitcnt lgkmcnt(0)
	ds_read_b128 v[236:239], v104 offset:16384
	ds_read_b128 v[240:243], v87
	ds_read_b128 v[244:247], v87 offset:4096
	ds_read_b128 v[248:251], v104 offset:20480
	v_mfma_f32_32x32x16_bf16 v[48:63], v[88:91], v[92:95], v[48:63]
	v_mfma_f32_32x32x16_bf16 v[32:47], v[88:91], v[96:99], v[32:47]
	s_add_i32 m0, s98, 0x8000
	v_lshl_add_u64 v[254:255], v[68:69], 0, s[100:101]
	global_load_lds_dwordx4 v[254:255], off
	v_mfma_f32_32x32x16_bf16 v[16:31], v[100:103], v[92:95], v[16:31]
	v_mfma_f32_32x32x16_bf16 v[0:15], v[100:103], v[96:99], v[0:15]
	s_add_i32 m0, s98, 0xa000
	v_lshl_add_u64 v[254:255], v[66:67], 0, s[100:101]
	global_load_lds_dwordx4 v[254:255], off
	s_waitcnt vmcnt(6) lgkmcnt(0)
	s_barrier
	s_waitcnt lgkmcnt(0)
	v_mfma_f32_32x32x16_bf16 v[48:63], v[236:239], v[240:243], v[48:63]
	v_mfma_f32_32x32x16_bf16 v[32:47], v[236:239], v[244:247], v[32:47]
	v_mfma_f32_32x32x16_bf16 v[16:31], v[248:251], v[240:243], v[16:31]
	v_mfma_f32_32x32x16_bf16 v[0:15], v[248:251], v[244:247], v[0:15]
	s_cmpk_lg_i32 s10, 0x700
	s_cbranch_scc1 .LBB0_747
; DEV int stage_next(int s) { return (s == 2 * GS_STAGE) ? 0 : s + GS_STAGE; }
; template <int WAIT0>
; DEV void gk_main(f32x16 (&acc)[2][2], const GTile& t, int s0) {
;     ...
;   GK_COMPUTE(stc);
;   vm_wait_bar<0>();
;   stc = stage_next(stc);
;   GK_COMPUTE(stc);
;   vm_wait_bar<0>();
	s_add_i32 s2, s16, 0
	v_add_u32_e32 v87, s2, v86
	ds_read_b128 v[66:69], v87 offset:16384
	v_add_u32_e32 v74, s2, v84
	ds_read_b128 v[70:73], v74
	ds_read_b128 v[74:77], v74 offset:4096
	ds_read_b128 v[88:91], v87 offset:20480
	v_add_u32_e32 v87, s2, v85
	s_waitcnt lgkmcnt(0)
	v_mfma_f32_32x32x16_bf16 v[0:15], v[88:91], v[74:77], v[0:15]
	v_mfma_f32_32x32x16_bf16 v[48:63], v[66:69], v[70:73], v[48:63]
	v_mfma_f32_32x32x16_bf16 v[32:47], v[66:69], v[74:77], v[32:47]
	ds_read_b128 v[66:69], v87 offset:16384
	v_add_u32_e32 v74, s2, v82
	v_mfma_f32_32x32x16_bf16 v[16:31], v[88:91], v[70:73], v[16:31]
	ds_read_b128 v[70:73], v74
	ds_read_b128 v[74:77], v74 offset:4096
	ds_read_b128 v[88:91], v87 offset:20480
	v_add_u32_e32 v87, s2, v83
	s_waitcnt lgkmcnt(0)
	v_mfma_f32_32x32x16_bf16 v[48:63], v[66:69], v[70:73], v[48:63]
	v_mfma_f32_32x32x16_bf16 v[32:47], v[66:69], v[74:77], v[32:47]
	ds_read_b128 v[66:69], v87 offset:16384
	v_mfma_f32_32x32x16_bf16 v[0:15], v[88:91], v[74:77], v[0:15]
	v_add_u32_e32 v74, s2, v80
	v_mfma_f32_32x32x16_bf16 v[16:31], v[88:91], v[70:73], v[16:31]
	ds_read_b128 v[70:73], v74
	ds_read_b128 v[74:77], v74 offset:4096
	ds_read_b128 v[88:91], v87 offset:20480
	v_add_u32_e32 v87, s2, v81
	s_waitcnt lgkmcnt(0)
	v_mfma_f32_32x32x16_bf16 v[48:63], v[66:69], v[70:73], v[48:63]
	v_mfma_f32_32x32x16_bf16 v[32:47], v[66:69], v[74:77], v[32:47]
	ds_read_b128 v[66:69], v87 offset:16384
	v_mfma_f32_32x32x16_bf16 v[0:15], v[88:91], v[74:77], v[0:15]
	v_add_u32_e32 v74, s2, v79
	s_add_i32 s2, s16, 0xc000
	s_cmp_lg_u32 s16, 0x18000
	s_cselect_b32 s2, s2, 0
	s_add_i32 s2, s2, 0
	v_add_u32_e32 v86, s2, v86
	v_mfma_f32_32x32x16_bf16 v[16:31], v[88:91], v[70:73], v[16:31]
	ds_read_b128 v[70:73], v74
	ds_read_b128 v[74:77], v74 offset:4096
	ds_read_b128 v[88:91], v87 offset:20480
	s_waitcnt vmcnt(0) lgkmcnt(0)
	s_barrier
	s_waitcnt lgkmcnt(0)
	v_mfma_f32_32x32x16_bf16 v[48:63], v[66:69], v[70:73], v[48:63]
	v_mfma_f32_32x32x16_bf16 v[32:47], v[66:69], v[74:77], v[32:47]
	ds_read_b128 v[66:69], v86 offset:16384
	v_mfma_f32_32x32x16_bf16 v[16:31], v[88:91], v[70:73], v[16:31]
	v_mfma_f32_32x32x16_bf16 v[0:15], v[88:91], v[74:77], v[0:15]
	v_add_u32_e32 v74, s2, v84
	ds_read_b128 v[70:73], v74
	ds_read_b128 v[74:77], v74 offset:4096
	ds_read_b128 v[86:89], v86 offset:20480
	v_add_u32_e32 v84, s2, v85
	s_waitcnt lgkmcnt(0)
	v_mfma_f32_32x32x16_bf16 v[48:63], v[66:69], v[70:73], v[48:63]
	v_mfma_f32_32x32x16_bf16 v[32:47], v[66:69], v[74:77], v[32:47]
	ds_read_b128 v[66:69], v84 offset:16384
	v_mfma_f32_32x32x16_bf16 v[16:31], v[86:89], v[70:73], v[16:31]
	v_mfma_f32_32x32x16_bf16 v[0:15], v[86:89], v[74:77], v[0:15]
	v_add_u32_e32 v74, s2, v82
	ds_read_b128 v[70:73], v74
	ds_read_b128 v[74:77], v74 offset:4096
	ds_read_b128 v[84:87], v84 offset:20480
	v_add_u32_e32 v82, s2, v83
	s_waitcnt lgkmcnt(0)
	v_mfma_f32_32x32x16_bf16 v[48:63], v[66:69], v[70:73], v[48:63]
	v_mfma_f32_32x32x16_bf16 v[32:47], v[66:69], v[74:77], v[32:47]
	ds_read_b128 v[66:69], v82 offset:16384
	v_mfma_f32_32x32x16_bf16 v[16:31], v[84:87], v[70:73], v[16:31]
	v_mfma_f32_32x32x16_bf16 v[0:15], v[84:87], v[74:77], v[0:15]
	v_add_u32_e32 v74, s2, v80
	ds_read_b128 v[70:73], v74
	ds_read_b128 v[74:77], v74 offset:4096
	ds_read_b128 v[82:85], v82 offset:20480
	v_add_u32_e32 v80, s2, v81
	s_waitcnt lgkmcnt(0)
	v_mfma_f32_32x32x16_bf16 v[48:63], v[66:69], v[70:73], v[48:63]
	v_mfma_f32_32x32x16_bf16 v[32:47], v[66:69], v[74:77], v[32:47]
	ds_read_b128 v[66:69], v80 offset:16384
	v_mfma_f32_32x32x16_bf16 v[16:31], v[82:85], v[70:73], v[16:31]
	v_mfma_f32_32x32x16_bf16 v[0:15], v[82:85], v[74:77], v[0:15]
	v_add_u32_e32 v74, s2, v79
	ds_read_b128 v[70:73], v74
	ds_read_b128 v[74:77], v74 offset:4096
	ds_read_b128 v[80:83], v80 offset:20480
	s_waitcnt vmcnt(0) lgkmcnt(0)
	s_barrier
	s_waitcnt lgkmcnt(0)
	v_mfma_f32_32x32x16_bf16 v[48:63], v[66:69], v[70:73], v[48:63]
	v_mfma_f32_32x32x16_bf16 v[32:47], v[66:69], v[74:77], v[32:47]
	v_mfma_f32_32x32x16_bf16 v[16:31], v[80:83], v[70:73], v[16:31]
	v_mfma_f32_32x32x16_bf16 v[0:15], v[80:83], v[74:77], v[0:15]
	s_add_i32 s2, s17, 1
	s_mov_b32 s16, s18
	s_cmp_eq_u32 s17, 3
	s_cbranch_scc1 .LBB0_733
